# norm passes: sample-row operand loads hoisted above the prompt-row loop (all workgroups issue them, the 32 sample workgroups consume them); plus sc1 stores, no final barrier
# baseline (speedup 1.0000x reference)
.LBB0_306:
	s_add_u32 s4, s94, 0x1b500000
	s_addc_u32 s5, s95, 0
	v_writelane_b32 v254, s4, 60
	s_cmp_lt_i32 s42, 4
	s_nop 0
	v_writelane_b32 v254, s5, 61
	s_cselect_b64 s[4:5], -1, 0
	s_cmp_gt_i32 s43, 3
	s_cselect_b64 s[6:7], -1, 0
	s_and_b64 s[4:5], s[4:5], s[6:7]
	s_andn2_b64 vcc, exec, s[4:5]
	s_cbranch_vccnz .LBB0_378
	s_load_dwordx16 s[4:19], s[0:1], 0x0
	s_waitcnt lgkmcnt(0)
	s_mov_b64 s[4:5], s[8:9]
	s_mov_b64 s[6:7], s[10:11]
	s_mov_b64 s[8:9], s[12:13]
	s_mov_b64 s[10:11], s[14:15]
	s_mov_b64 s[12:13], s[16:17]
	s_mov_b64 s[14:15], s[18:19]
	s_add_u32 s4, s14, 0x2000
	s_addc_u32 s5, s15, 0
	s_add_u32 s6, s14, 0x4000
	s_addc_u32 s7, s15, 0
	s_ashr_i32 s9, s90, 5
	s_abs_i32 s8, s9
	v_cvt_f32_u32_e32 v169, s8
	s_sub_i32 s12, 0, s8
	s_abs_i32 s10, s62
	s_xor_b32 s11, s62, s9
	v_rcp_iflag_f32_e32 v169, v169
	s_ashr_i32 s11, s11, 31
	v_mul_f32_e32 v169, 0x4f7ffffe, v169
	v_cvt_u32_f32_e32 v169, v169
	s_nop 0
	v_readfirstlane_b32 s13, v169
	s_mul_i32 s12, s12, s13
	s_mul_hi_u32 s12, s13, s12
	s_add_i32 s13, s13, s12
	s_mul_hi_u32 s12, s10, s13
	s_mul_i32 s13, s12, s8
	s_sub_i32 s10, s10, s13
	s_add_i32 s14, s12, 1
	s_sub_i32 s13, s10, s8
	s_cmp_ge_u32 s10, s8
	s_cselect_b32 s12, s14, s12
	s_cselect_b32 s10, s13, s10
	s_add_i32 s13, s12, 1
	s_cmp_ge_u32 s10, s8
	s_cselect_b32 s8, s13, s12
	s_xor_b32 s8, s8, s11
	s_sub_i32 s8, s8, s11
	s_mul_i32 s9, s8, s9
	s_sub_i32 s9, s62, s9
	s_cmp_lg_u32 s9, 0
	s_ashr_i32 s9, s8, 31
	s_lshl_b64 s[10:11], s[8:9], 13
	v_readlane_b32 s12, v254, 58
	v_readlane_b32 s13, v254, 59
	s_add_u32 s10, s12, s10
	s_addc_u32 s11, s13, s11
	v_mov_b32_e32 v181, 0
	v_lshlrev_b32_e32 v180, 4, v0
	v_lshl_add_u64 v[170:171], s[10:11], 0, v[180:181]
	v_add_co_u32_e32 v172, vcc, 0x40000, v170
	global_load_dwordx4 v[186:189], v180, s[10:11]
	s_nop 0
	v_addc_co_u32_e32 v173, vcc, 0, v171, vcc
	v_add_co_u32_e32 v174, vcc, 0x80000, v170
	s_addk_i32 s8, 0x2000
	s_nop 0
	v_addc_co_u32_e32 v175, vcc, 0, v171, vcc
	v_add_co_u32_e32 v170, vcc, 0xc0000, v170
	global_load_dwordx4 v[190:193], v[172:173], off
	global_load_dwordx4 v[194:197], v[174:175], off
	v_addc_co_u32_e32 v171, vcc, 0, v171, vcc
	global_load_dwordx4 v[198:201], v[170:171], off
	s_ashr_i32 s9, s8, 31
	s_lshl_b64 s[10:11], s[8:9], 12
	v_readlane_b32 s12, v254, 54
	v_readlane_b32 s13, v254, 55
	s_add_u32 s10, s12, s10
	s_addc_u32 s11, s13, s11
	v_lshlrev_b32_e32 v178, 3, v0
	global_load_dwordx4 v[174:177], v180, s[4:5]
	global_load_dwordx4 v[170:173], v180, s[6:7]
	global_load_dwordx2 v[182:183], v178, s[10:11]
	s_lshl_b32 s9, s62, 3
	s_add_i32 s8, s9, s96
	s_and_b32 s9, s9, 0xf8
	s_lshl_b32 s10, s62, 5
	s_add_i32 s9, s9, s96
	s_and_b32 s10, s10, 0xfffffc00
	s_add_i32 s9, s9, s10
	s_add_i32 s14, s9, 0x400
	s_cmpk_eq_i32 s90, 0x100
	s_cselect_b64 s[12:13], -1, 0
	s_and_b64 s[10:11], s[12:13], exec
	s_cselect_b32 s10, s9, s8
	s_cselect_b32 s9, s14, 0x2000
	s_cmp_ge_i32 s10, s9
	s_cbranch_scc1 .LBB0_312
	s_lshl_b32 s11, s90, 3
	v_lshlrev_b32_e32 v1, 5, v166
	s_and_b64 s[12:13], s[12:13], exec
	v_or_b32_e32 v46, 0x800, v1
	v_or_b32_e32 v54, 0x1000, v1
	v_or_b32_e32 v62, 0x1800, v1
	s_cselect_b32 s12, 0x100, s11
	s_ashr_i32 s11, s10, 31
	global_load_dwordx4 v[2:5], v1, s[4:5] offset:16
	global_load_dwordx4 v[6:9], v1, s[4:5]
	global_load_dwordx4 v[10:13], v46, s[4:5] offset:16
	global_load_dwordx4 v[14:17], v46, s[4:5]
	global_load_dwordx4 v[18:21], v54, s[4:5] offset:16
	global_load_dwordx4 v[22:25], v54, s[4:5]
	global_load_dwordx4 v[26:29], v62, s[4:5] offset:16
	global_load_dwordx4 v[30:33], v62, s[4:5]
	global_load_dwordx4 v[34:37], v1, s[6:7] offset:16
	global_load_dwordx4 v[38:41], v1, s[6:7]
	global_load_dwordx4 v[42:45], v46, s[6:7] offset:16
	s_nop 0
	global_load_dwordx4 v[46:49], v46, s[6:7]
	s_nop 0
	global_load_dwordx4 v[50:53], v54, s[6:7] offset:16
	s_nop 0
	global_load_dwordx4 v[54:57], v54, s[6:7]
	s_lshl_b64 s[14:15], s[10:11], 12
	v_readlane_b32 s16, v254, 54
	v_readlane_b32 s17, v254, 55
	s_add_u32 s16, s16, s14
	s_addc_u32 s17, s17, s15
	s_add_u32 s18, s80, s14
	v_lshlrev_b32_e32 v130, 4, v166
	s_addc_u32 s19, s81, s15
	global_load_dwordx4 v[110:113], v130, s[16:17]
	global_load_dwordx4 v[106:109], v130, s[16:17] offset:1024
	global_load_dwordx4 v[102:105], v130, s[16:17] offset:2048
	global_load_dwordx4 v[126:129], v130, s[18:19]
	global_load_dwordx4 v[122:125], v130, s[18:19] offset:1024
	global_load_dwordx4 v[98:101], v130, s[16:17] offset:3072
	global_load_dwordx4 v[118:121], v130, s[18:19] offset:2048
	global_load_dwordx4 v[114:117], v130, s[18:19] offset:3072
	global_load_dwordx4 v[58:61], v62, s[6:7] offset:16
	s_nop 0
	global_load_dwordx4 v[62:65], v62, s[6:7]
	s_add_u32 s14, s94, s14
	s_addc_u32 s15, s95, s15
	s_add_i32 s18, s10, s12
	s_ashr_i32 s13, s12, 31
	s_ashr_i32 s19, s18, 31
	s_lshl_b64 s[16:17], s[12:13], 12
	s_lshl_b64 s[18:19], s[18:19], 12
	s_add_u32 s18, s94, s18
	v_mov_b32_e32 v131, 0
	s_mov_b32 s11, 0x2f1e0000
	s_mov_b32 s22, 0x2f1e1000
	v_mov_b32_e32 v1, 0x358637bd
	s_mov_b32 s23, 0x1b500000
	v_mov_b32_e32 v132, 0x3a000000
	s_addc_u32 s19, s95, s19
	s_waitcnt vmcnt(9)
	v_mov_b64_e32 v[66:67], v[110:111]
	s_waitcnt vmcnt(8)
	v_mov_b64_e32 v[70:71], v[106:107]
	s_waitcnt vmcnt(7)
	v_mov_b64_e32 v[78:79], v[102:103]
	s_waitcnt vmcnt(6)
	v_mov_b64_e32 v[74:75], v[126:127]
	s_waitcnt vmcnt(5)
	v_mov_b64_e32 v[82:83], v[122:123]
	s_waitcnt vmcnt(4)
	v_mov_b64_e32 v[94:95], v[98:99]
	s_waitcnt vmcnt(3)
	v_mov_b64_e32 v[86:87], v[118:119]
	s_waitcnt vmcnt(2)
	v_mov_b64_e32 v[90:91], v[114:115]
	v_mov_b64_e32 v[68:69], v[112:113]
	v_mov_b64_e32 v[72:73], v[108:109]
	v_mov_b64_e32 v[80:81], v[104:105]
	v_mov_b64_e32 v[76:77], v[128:129]
	v_mov_b64_e32 v[84:85], v[124:125]
	v_mov_b64_e32 v[88:89], v[120:121]
	v_mov_b64_e32 v[92:93], v[116:117]
	v_mov_b64_e32 v[96:97], v[100:101]
	s_branch .LBB0_310

.LBB0_318:
	s_cbranch_execz .LBB0_325
	s_ashr_i32 s9, s90, 5
	s_abs_i32 s8, s9
	v_cvt_f32_u32_e32 v1, s8
	s_sub_i32 s12, 0, s8
	s_abs_i32 s10, s62
	s_xor_b32 s11, s62, s9
	v_rcp_iflag_f32_e32 v1, v1
	s_ashr_i32 s11, s11, 31
	v_mul_f32_e32 v1, 0x4f7ffffe, v1
	v_cvt_u32_f32_e32 v1, v1
	s_nop 0
	v_readfirstlane_b32 s13, v1
	s_mul_i32 s12, s12, s13
	s_mul_hi_u32 s12, s13, s12
	s_add_i32 s13, s13, s12
	s_mul_hi_u32 s12, s10, s13
	s_mul_i32 s13, s12, s8
	s_sub_i32 s10, s10, s13
	s_add_i32 s14, s12, 1
	s_sub_i32 s13, s10, s8
	s_cmp_ge_u32 s10, s8
	s_cselect_b32 s12, s14, s12
	s_cselect_b32 s10, s13, s10
	s_add_i32 s13, s12, 1
	s_cmp_ge_u32 s10, s8
	s_cselect_b32 s8, s13, s12
	s_xor_b32 s8, s8, s11
	s_sub_i32 s8, s8, s11
	s_mul_i32 s9, s8, s9
	s_sub_i32 s9, s62, s9
	s_cmp_lg_u32 s9, 0
	s_cbranch_scc1 .LBB0_325
	s_ashr_i32 s9, s8, 31
	s_lshl_b64 s[10:11], s[8:9], 13
	v_readlane_b32 s12, v254, 58
	v_readlane_b32 s13, v254, 59
	s_add_u32 s10, s12, s10
	s_addc_u32 s11, s13, s11
	v_mov_b32_e32 v13, 0
	v_lshlrev_b32_e32 v12, 4, v0
	v_lshl_add_u64 v[2:3], s[10:11], 0, v[12:13]
	v_add_co_u32_e32 v4, vcc, 0x40000, v2
	s_waitcnt vmcnt(0)
	v_mov_b32_e32 v18, v186
	v_mov_b32_e32 v19, v187
	v_mov_b32_e32 v20, v188
	v_mov_b32_e32 v21, v189
	s_nop 0
	v_addc_co_u32_e32 v5, vcc, 0, v3, vcc
	v_add_co_u32_e32 v6, vcc, 0x80000, v2
	s_addk_i32 s8, 0x2000
	s_nop 0
	v_addc_co_u32_e32 v7, vcc, 0, v3, vcc
	v_add_co_u32_e32 v2, vcc, 0xc0000, v2
	v_mov_b32_e32 v22, v190
	v_mov_b32_e32 v23, v191
	v_mov_b32_e32 v24, v192
	v_mov_b32_e32 v25, v193
	v_mov_b32_e32 v26, v194
	v_mov_b32_e32 v27, v195
	v_mov_b32_e32 v28, v196
	v_mov_b32_e32 v29, v197
	v_addc_co_u32_e32 v3, vcc, 0, v3, vcc
	v_mov_b32_e32 v30, v198
	v_mov_b32_e32 v31, v199
	v_mov_b32_e32 v32, v200
	v_mov_b32_e32 v33, v201
	s_ashr_i32 s9, s8, 31
	s_lshl_b64 s[10:11], s[8:9], 12
	v_readlane_b32 s12, v254, 54
	v_readlane_b32 s13, v254, 55
	s_add_u32 s10, s12, s10
	s_addc_u32 s11, s13, s11
	v_lshlrev_b32_e32 v10, 3, v0
	v_mov_b32_e32 v6, v174
	v_mov_b32_e32 v7, v175
	v_mov_b32_e32 v8, v176
	v_mov_b32_e32 v9, v177
	v_mov_b32_e32 v2, v170
	v_mov_b32_e32 v3, v171
	v_mov_b32_e32 v4, v172
	v_mov_b32_e32 v5, v173
	v_mov_b32_e32 v14, v182
	v_mov_b32_e32 v15, v183
	v_mov_b32_e32 v11, v13
	v_lshl_add_u64 v[16:17], s[10:11], 0, v[10:11]
	v_mov_b32_e32 v1, v13
	v_mov_b32_e32 v12, v13
	v_cmp_eq_u32_e32 vcc, 0, v166
	s_waitcnt vmcnt(5)
	v_pk_add_f32 v[20:21], v[20:21], v[24:25]
	v_pk_add_f32 v[22:23], v[18:19], v[22:23]
	s_waitcnt vmcnt(3)
	v_pk_add_f32 v[18:19], v[28:29], v[32:33]
	v_pk_add_f32 v[24:25], v[26:27], v[30:31]
	v_pk_add_f32 v[18:19], v[20:21], v[18:19]
	v_pk_add_f32 v[20:21], v[22:23], v[24:25]
	v_mul_f32_e32 v22, v19, v19
	v_mul_f32_e32 v11, v21, v21
	v_fmac_f32_e32 v11, v20, v20
	v_fmac_f32_e32 v22, v18, v18
	v_add_f32_e32 v11, v11, v22
	s_nop 1
	v_add_f32_dpp v11, v11, v11 quad_perm:[1,0,3,2] row_mask:0xf bank_mask:0xf bound_ctrl:1
	s_nop 1
	v_add_f32_dpp v11, v11, v11 quad_perm:[2,3,0,1] row_mask:0xf bank_mask:0xf bound_ctrl:1
	s_nop 1
	v_add_f32_dpp v11, v11, v11 row_half_mirror row_mask:0xf bank_mask:0xf bound_ctrl:1
	s_nop 1
	v_add_f32_dpp v11, v11, v11 row_mirror row_mask:0xf bank_mask:0xf bound_ctrl:1
	s_nop 1
	v_mov_b32_dpp v1, v11 row_bcast:15 row_mask:0xa bank_mask:0xf
	v_add_f32_e32 v1, v11, v1
	s_nop 1
	v_mov_b32_dpp v12, v1 row_bcast:31 row_mask:0xc bank_mask:0xf
	v_add_f32_e32 v1, v1, v12
	s_nop 0
	v_readlane_b32 s6, v1, 63
	s_and_saveexec_b64 s[4:5], vcc
	s_lshl_b32 s7, s96, 2
	s_add_i32 s7, s7, 0
	v_mov_b32_e32 v1, s7
	v_mov_b32_e32 v11, s6
	ds_write_b32 v1, v11
	s_or_b64 exec, exec, s[4:5]
	s_waitcnt lgkmcnt(0)
	s_barrier
	ds_read_b128 v[22:25], v13
	ds_read_b128 v[26:29], v13 offset:16
	s_waitcnt vmcnt(2)
	v_pk_mul_f32 v[6:7], v[6:7], v[20:21]
	v_pk_mul_f32 v[8:9], v[8:9], v[18:19]
	s_lshl_b64 s[4:5], s[8:9], 11
	s_waitcnt lgkmcnt(1)
	v_add_f32_e32 v1, 0, v22
	v_add_f32_e32 v1, v1, v23
	v_add_f32_e32 v1, v1, v24
	v_add_f32_e32 v1, v1, v25
	s_waitcnt lgkmcnt(0)
	v_add_f32_e32 v1, v1, v26
	v_add_f32_e32 v1, v1, v27
	v_add_f32_e32 v1, v1, v28
	v_add_f32_e32 v11, v1, v29
	v_mov_b32_e32 v1, 0x358637bd
	v_fmamk_f32 v11, v11, 0x3a000000, v1
	v_rsq_f32_e32 v11, v11
	s_waitcnt vmcnt(0)
	v_cvt_f32_f16_sdwa v23, v14 dst_sel:DWORD dst_unused:UNUSED_PAD src0_sel:WORD_1
	v_cvt_f32_f16_e32 v22, v14
	v_cvt_f32_f16_sdwa v25, v15 dst_sel:DWORD dst_unused:UNUSED_PAD src0_sel:WORD_1
	v_cvt_f32_f16_e32 v24, v15
	v_mul_f32_e32 v12, 0.5, v11
	v_pk_fma_f32 v[6:7], v[6:7], v[12:13], v[22:23] op_sel_hi:[1,0,1]
	v_pk_fma_f32 v[8:9], v[8:9], v[12:13], v[24:25] op_sel_hi:[1,0,1]
	v_cvt_f16_f32_e32 v11, v6
	v_cvt_f16_f32_sdwa v12, v7 dst_sel:WORD_1 dst_unused:UNUSED_PAD src0_sel:DWORD
	v_cvt_f16_f32_e32 v15, v8
	v_cvt_f16_f32_sdwa v18, v9 dst_sel:WORD_1 dst_unused:UNUSED_PAD src0_sel:DWORD
	v_or_b32_e32 v14, v12, v11
	v_mul_f32_e32 v11, v7, v7
	v_mul_f32_e32 v12, v9, v9
	v_fmac_f32_e32 v11, v6, v6
	v_fmac_f32_e32 v12, v8, v8
	v_add_f32_e32 v11, v11, v12
	v_mov_b32_e32 v12, 0
	v_or_b32_e32 v15, v18, v15
	v_add_f32_dpp v11, v11, v11 quad_perm:[1,0,3,2] row_mask:0xf bank_mask:0xf bound_ctrl:1
	global_store_dwordx2 v[16:17], v[14:15], off
	s_nop 0
	v_add_f32_dpp v11, v11, v11 quad_perm:[2,3,0,1] row_mask:0xf bank_mask:0xf bound_ctrl:1
	s_nop 1
	v_add_f32_dpp v11, v11, v11 row_half_mirror row_mask:0xf bank_mask:0xf bound_ctrl:1
	s_nop 1
	v_add_f32_dpp v11, v11, v11 row_mirror row_mask:0xf bank_mask:0xf bound_ctrl:1
	s_nop 1
	v_mov_b32_dpp v12, v11 row_bcast:15 row_mask:0xa bank_mask:0xf
	v_add_f32_e32 v11, v11, v12
	s_nop 1
	v_mov_b32_dpp v13, v11 row_bcast:31 row_mask:0xc bank_mask:0xf
	v_add_f32_e32 v11, v11, v13
	s_nop 0
	v_readlane_b32 s8, v11, 63
	s_and_saveexec_b64 s[6:7], vcc
	s_lshl_b32 s9, s96, 2
	s_add_i32 s9, s9, 0
	v_mov_b32_e32 v11, s9
	v_mov_b32_e32 v12, s8
	ds_write_b32 v11, v12 offset:32
	s_or_b64 exec, exec, s[6:7]
	v_mov_b32_e32 v11, 0
	s_waitcnt lgkmcnt(0)
	s_barrier
	ds_read_b128 v[12:15], v11 offset:32
	ds_read_b128 v[16:19], v11 offset:48
	s_lshl_b64 s[4:5], s[4:5], 1
	v_readlane_b32 s6, v254, 60
	v_pk_mul_f32 v[2:3], v[2:3], v[6:7]
	s_waitcnt lgkmcnt(1)
	v_add_f32_e32 v11, 0, v12
	v_add_f32_e32 v11, v11, v13
	v_add_f32_e32 v11, v11, v14
	v_add_f32_e32 v11, v11, v15
	s_waitcnt lgkmcnt(0)
	v_add_f32_e32 v11, v11, v16
	v_add_f32_e32 v11, v11, v17
	v_add_f32_e32 v11, v11, v18
	v_add_f32_e32 v11, v11, v19
	v_fmac_f32_e32 v1, 0x3a000000, v11
	v_rsq_f32_e32 v12, v1
	v_readlane_b32 s7, v254, 61
	s_add_u32 s4, s6, s4
	v_pk_mul_f32 v[4:5], v[4:5], v[8:9]
	v_pk_mul_f32 v[2:3], v[2:3], v[12:13] op_sel_hi:[1,0]
	s_addc_u32 s5, s7, s5
	v_pk_mul_f32 v[4:5], v[4:5], v[12:13] op_sel_hi:[1,0]
	v_cvt_pk_bf16_f32 v2, v2, v3
	s_nop 0
	v_cvt_pk_bf16_f32 v3, v4, v5
	global_store_dwordx2 v10, v[2:3], s[4:5]
	s_barrier

.LBB0_635:
	s_cmp_lt_i32 s42, 8
	s_cselect_b64 s[4:5], -1, 0
	s_cmp_gt_i32 s43, 7
	s_cselect_b64 s[6:7], -1, 0
	s_and_b64 s[4:5], s[4:5], s[6:7]
	s_andn2_b64 vcc, exec, s[4:5]
	s_cbranch_vccnz .LBB0_715
	s_load_dwordx16 s[4:19], s[0:1], 0x0
	s_waitcnt lgkmcnt(0)
	s_mov_b64 s[8:9], s[12:13]
	s_mov_b64 s[10:11], s[14:15]
	s_mov_b64 s[12:13], s[16:17]
	s_mov_b64 s[14:15], s[18:19]
	s_add_u32 s8, s14, 0x6000
	s_addc_u32 s9, s15, 0
	s_add_u32 s10, s14, 0x8000
	s_addc_u32 s11, s15, 0
	s_ashr_i32 s5, s90, 5
	s_abs_i32 s4, s5
	v_cvt_f32_u32_e32 v169, s4
	s_sub_i32 s12, 0, s4
	s_abs_i32 s6, s62
	s_xor_b32 s7, s62, s5
	v_rcp_iflag_f32_e32 v169, v169
	s_ashr_i32 s7, s7, 31
	v_mul_f32_e32 v169, 0x4f7ffffe, v169
	v_cvt_u32_f32_e32 v169, v169
	s_nop 0
	v_readfirstlane_b32 s13, v169
	s_mul_i32 s12, s12, s13
	s_mul_hi_u32 s12, s13, s12
	s_add_i32 s13, s13, s12
	s_mul_hi_u32 s12, s6, s13
	s_mul_i32 s13, s12, s4
	s_sub_i32 s6, s6, s13
	s_add_i32 s14, s12, 1
	s_sub_i32 s13, s6, s4
	s_cmp_ge_u32 s6, s4
	s_cselect_b32 s12, s14, s12
	s_cselect_b32 s6, s13, s6
	s_add_i32 s13, s12, 1
	s_cmp_ge_u32 s6, s4
	s_cselect_b32 s4, s13, s12
	s_xor_b32 s4, s4, s7
	s_sub_i32 s4, s4, s7
	s_mul_i32 s5, s4, s5
	s_sub_i32 s5, s62, s5
	s_cmp_lg_u32 s5, 0
	s_ashr_i32 s5, s4, 31
	s_lshl_b64 s[6:7], s[4:5], 13
	v_readlane_b32 s12, v254, 58
	v_readlane_b32 s13, v254, 59
	s_add_u32 s6, s12, s6
	s_addc_u32 s7, s13, s7
	v_mov_b32_e32 v179, 0
	v_lshlrev_b32_e32 v178, 4, v0
	v_lshl_add_u64 v[170:171], s[6:7], 0, v[178:179]
	v_add_co_u32_e32 v172, vcc, 0x40000, v170
	global_load_dwordx4 v[184:187], v178, s[6:7]
	s_nop 0
	v_addc_co_u32_e32 v173, vcc, 0, v171, vcc
	v_add_co_u32_e32 v174, vcc, 0x80000, v170
	s_add_i32 s6, s4, 0x2000
	s_nop 0
	v_addc_co_u32_e32 v175, vcc, 0, v171, vcc
	v_add_co_u32_e32 v170, vcc, 0xc0000, v170
	global_load_dwordx4 v[188:191], v[172:173], off
	global_load_dwordx4 v[192:195], v[174:175], off
	v_addc_co_u32_e32 v171, vcc, 0, v171, vcc
	global_load_dwordx4 v[196:199], v[170:171], off
	s_ashr_i32 s7, s6, 31
	s_lshl_b64 s[4:5], s[6:7], 12
	v_readlane_b32 s12, v254, 54
	v_readlane_b32 s13, v254, 55
	s_add_u32 s4, s12, s4
	s_addc_u32 s5, s13, s5
	v_lshlrev_b32_e32 v182, 3, v0
	global_load_dwordx4 v[174:177], v178, s[8:9]
	global_load_dwordx4 v[170:173], v178, s[10:11]
	global_load_dwordx2 v[180:181], v182, s[4:5]
	s_lshl_b32 s4, s62, 3
	s_add_i32 s12, s4, s96
	s_and_b32 s4, s4, 0xf8
	s_lshl_b32 s5, s62, 5
	s_add_i32 s4, s4, s96
	s_and_b32 s5, s5, 0xfffffc00
	s_add_i32 s13, s4, s5
	s_add_i32 s15, s13, 0x400
	s_cmpk_eq_i32 s90, 0x100
	s_cselect_b64 s[4:5], -1, 0
	s_and_b64 s[6:7], s[4:5], exec
	s_cselect_b32 s14, s13, s12
	s_cselect_b32 s13, s15, 0x2000
	s_cmp_ge_i32 s14, s13
	s_cbranch_scc1 .LBB0_643
	s_lshl_b32 s6, s90, 3
	v_lshlrev_b32_e32 v1, 5, v166
	s_and_b64 s[4:5], s[4:5], exec
	v_or_b32_e32 v46, 0x800, v1
	v_or_b32_e32 v54, 0x1000, v1
	v_or_b32_e32 v62, 0x1800, v1
	s_cselect_b32 s16, 0x100, s6
	s_ashr_i32 s15, s14, 31
	global_load_dwordx4 v[2:5], v1, s[8:9] offset:16
	global_load_dwordx4 v[6:9], v1, s[8:9]
	global_load_dwordx4 v[10:13], v46, s[8:9] offset:16
	global_load_dwordx4 v[14:17], v46, s[8:9]
	global_load_dwordx4 v[18:21], v54, s[8:9] offset:16
	global_load_dwordx4 v[22:25], v54, s[8:9]
	global_load_dwordx4 v[26:29], v62, s[8:9] offset:16
	global_load_dwordx4 v[30:33], v62, s[8:9]
	global_load_dwordx4 v[34:37], v1, s[10:11] offset:16
	global_load_dwordx4 v[38:41], v1, s[10:11]
	global_load_dwordx4 v[42:45], v46, s[10:11] offset:16
	s_nop 0
	global_load_dwordx4 v[46:49], v46, s[10:11]
	s_nop 0
	global_load_dwordx4 v[50:53], v54, s[10:11] offset:16
	s_nop 0
	global_load_dwordx4 v[54:57], v54, s[10:11]
	s_lshl_b64 s[6:7], s[14:15], 11
	s_lshl_b64 s[18:19], s[14:15], 12
	v_readlane_b32 s4, v254, 54
	v_readlane_b32 s5, v254, 55
	s_add_u32 s4, s4, s18
	s_addc_u32 s5, s5, s19
	s_add_u32 s20, s80, s18
	v_lshlrev_b32_e32 v66, 4, v166
	s_addc_u32 s21, s81, s19
	global_load_dwordx4 v[110:113], v66, s[4:5]
	global_load_dwordx4 v[106:109], v66, s[4:5] offset:1024
	global_load_dwordx4 v[102:105], v66, s[4:5] offset:2048
	global_load_dwordx4 v[126:129], v66, s[20:21]
	global_load_dwordx4 v[122:125], v66, s[20:21] offset:1024
	global_load_dwordx4 v[98:101], v66, s[4:5] offset:3072
	global_load_dwordx4 v[118:121], v66, s[20:21] offset:2048
	global_load_dwordx4 v[114:117], v66, s[20:21] offset:3072
	global_load_dwordx4 v[58:61], v62, s[10:11] offset:16
	s_nop 0
	global_load_dwordx4 v[62:65], v62, s[10:11]
	v_lshl_or_b32 v130, v166, 3, s6
	v_mov_b32_e32 v131, s7
	s_lshl_b64 s[6:7], s[14:15], 2
	s_add_u32 s15, s6, 0x2ee80000
	s_addc_u32 s37, s7, 0
	s_add_i32 s6, s14, s16
	s_ashr_i32 s7, s6, 31
	s_lshl_b64 s[6:7], s[6:7], 12
	v_or_b32_e32 v132, s18, v66
	s_ashr_i32 s17, s16, 31
	v_or_b32_e32 v134, s6, v66
	v_cmp_eq_u32_e64 s[4:5], 0, v166
	s_mov_b32 s28, 0x2f1e0000
	s_mov_b32 s29, 0x2f1e1000
	v_mov_b32_e32 v1, 0
	v_mov_b32_e32 v136, 0x358637bd
	s_mov_b32 s30, 0x42fe0000
	s_mov_b32 s31, 0xc0c0400
	s_mov_b32 s34, 0xc040100
	s_mov_b32 s35, 0x4020100
	s_mov_b32 s36, 0x2de00000
	v_mov_b32_e32 v137, 0x3a000000
	v_mov_b32_e32 v138, 0x3c010204
	v_mov_b32_e32 v139, 0x42fe0000
	v_mov_b32_e32 v133, s19
	s_lshl_b64 s[18:19], s[16:17], 2
	s_lshl_b64 s[20:21], s[16:17], 11
	s_lshl_b64 s[22:23], s[16:17], 12
	v_mov_b32_e32 v135, s7
	s_waitcnt vmcnt(9)
	v_mov_b64_e32 v[66:67], v[110:111]
	s_waitcnt vmcnt(8)
	v_mov_b64_e32 v[70:71], v[106:107]
	s_waitcnt vmcnt(7)
	v_mov_b64_e32 v[78:79], v[102:103]
	s_waitcnt vmcnt(6)
	v_mov_b64_e32 v[74:75], v[126:127]
	s_waitcnt vmcnt(5)
	v_mov_b64_e32 v[82:83], v[122:123]
	s_waitcnt vmcnt(4)
	v_mov_b64_e32 v[94:95], v[98:99]
	s_waitcnt vmcnt(3)
	v_mov_b64_e32 v[86:87], v[118:119]
	s_waitcnt vmcnt(2)
	v_mov_b64_e32 v[90:91], v[114:115]
	v_mov_b64_e32 v[68:69], v[112:113]
	v_mov_b64_e32 v[72:73], v[108:109]
	v_mov_b64_e32 v[80:81], v[104:105]
	v_mov_b64_e32 v[76:77], v[128:129]
	v_mov_b64_e32 v[84:85], v[124:125]
	v_mov_b64_e32 v[88:89], v[120:121]
	v_mov_b64_e32 v[92:93], v[116:117]
	v_mov_b64_e32 v[96:97], v[100:101]
	s_branch .LBB0_639

.LBB0_651:
	s_cbranch_execz .LBB0_662
	s_ashr_i32 s5, s90, 5
	s_abs_i32 s4, s5
	v_cvt_f32_u32_e32 v1, s4
	s_sub_i32 s12, 0, s4
	s_abs_i32 s6, s62
	s_xor_b32 s7, s62, s5
	v_rcp_iflag_f32_e32 v1, v1
	s_ashr_i32 s7, s7, 31
	v_mul_f32_e32 v1, 0x4f7ffffe, v1
	v_cvt_u32_f32_e32 v1, v1
	s_nop 0
	v_readfirstlane_b32 s13, v1
	s_mul_i32 s12, s12, s13
	s_mul_hi_u32 s12, s13, s12
	s_add_i32 s13, s13, s12
	s_mul_hi_u32 s12, s6, s13
	s_mul_i32 s13, s12, s4
	s_sub_i32 s6, s6, s13
	s_add_i32 s14, s12, 1
	s_sub_i32 s13, s6, s4
	s_cmp_ge_u32 s6, s4
	s_cselect_b32 s12, s14, s12
	s_cselect_b32 s6, s13, s6
	s_add_i32 s13, s12, 1
	s_cmp_ge_u32 s6, s4
	s_cselect_b32 s4, s13, s12
	s_xor_b32 s4, s4, s7
	s_sub_i32 s4, s4, s7
	s_mul_i32 s5, s4, s5
	s_sub_i32 s5, s62, s5
	s_cmp_lg_u32 s5, 0
	s_cbranch_scc1 .LBB0_662
	s_ashr_i32 s5, s4, 31
	s_lshl_b64 s[6:7], s[4:5], 13
	v_readlane_b32 s12, v254, 58
	v_readlane_b32 s13, v254, 59
	s_add_u32 s6, s12, s6
	s_addc_u32 s7, s13, s7
	v_mov_b32_e32 v11, 0
	v_lshlrev_b32_e32 v10, 4, v0
	v_lshl_add_u64 v[2:3], s[6:7], 0, v[10:11]
	v_add_co_u32_e32 v4, vcc, 0x40000, v2
	s_waitcnt vmcnt(0)
	v_mov_b32_e32 v16, v184
	v_mov_b32_e32 v17, v185
	v_mov_b32_e32 v18, v186
	v_mov_b32_e32 v19, v187
	s_nop 0
	v_addc_co_u32_e32 v5, vcc, 0, v3, vcc
	v_add_co_u32_e32 v6, vcc, 0x80000, v2
	s_add_i32 s6, s4, 0x2000
	s_nop 0
	v_addc_co_u32_e32 v7, vcc, 0, v3, vcc
	v_add_co_u32_e32 v2, vcc, 0xc0000, v2
	v_mov_b32_e32 v20, v188
	v_mov_b32_e32 v21, v189
	v_mov_b32_e32 v22, v190
	v_mov_b32_e32 v23, v191
	v_mov_b32_e32 v24, v192
	v_mov_b32_e32 v25, v193
	v_mov_b32_e32 v26, v194
	v_mov_b32_e32 v27, v195
	v_addc_co_u32_e32 v3, vcc, 0, v3, vcc
	v_mov_b32_e32 v28, v196
	v_mov_b32_e32 v29, v197
	v_mov_b32_e32 v30, v198
	v_mov_b32_e32 v31, v199
	s_ashr_i32 s7, s6, 31
	s_lshl_b64 s[4:5], s[6:7], 12
	v_readlane_b32 s12, v254, 54
	v_readlane_b32 s13, v254, 55
	s_add_u32 s4, s12, s4
	s_addc_u32 s5, s13, s5
	v_lshlrev_b32_e32 v14, 3, v0
	v_mov_b32_e32 v6, v174
	v_mov_b32_e32 v7, v175
	v_mov_b32_e32 v8, v176
	v_mov_b32_e32 v9, v177
	v_mov_b32_e32 v2, v170
	v_mov_b32_e32 v3, v171
	v_mov_b32_e32 v4, v172
	v_mov_b32_e32 v5, v173
	v_mov_b32_e32 v12, v180
	v_mov_b32_e32 v13, v181
	v_mov_b32_e32 v1, v11
	v_mov_b32_e32 v10, v11
	v_mov_b32_e32 v15, v11
	v_lshl_add_u64 v[14:15], s[4:5], 0, v[14:15]
	v_cmp_eq_u32_e32 vcc, 0, v166
	s_waitcnt vmcnt(5)
	v_pk_add_f32 v[18:19], v[18:19], v[22:23]
	v_pk_add_f32 v[20:21], v[16:17], v[20:21]
	s_waitcnt vmcnt(3)
	v_pk_add_f32 v[16:17], v[26:27], v[30:31]
	v_pk_add_f32 v[22:23], v[24:25], v[28:29]
	v_pk_add_f32 v[16:17], v[18:19], v[16:17]
	v_pk_add_f32 v[18:19], v[20:21], v[22:23]
	v_mul_f32_e32 v21, v17, v17
	v_mul_f32_e32 v20, v19, v19
	v_fmac_f32_e32 v20, v18, v18
	v_fmac_f32_e32 v21, v16, v16
	v_add_f32_e32 v20, v20, v21
	s_nop 1
	v_add_f32_dpp v20, v20, v20 quad_perm:[1,0,3,2] row_mask:0xf bank_mask:0xf bound_ctrl:1
	s_nop 1
	v_add_f32_dpp v20, v20, v20 quad_perm:[2,3,0,1] row_mask:0xf bank_mask:0xf bound_ctrl:1
	s_nop 1
	v_add_f32_dpp v20, v20, v20 row_half_mirror row_mask:0xf bank_mask:0xf bound_ctrl:1
	s_nop 1
	v_add_f32_dpp v20, v20, v20 row_mirror row_mask:0xf bank_mask:0xf bound_ctrl:1
	s_nop 1
	v_mov_b32_dpp v1, v20 row_bcast:15 row_mask:0xa bank_mask:0xf
	v_add_f32_e32 v1, v20, v1
	s_nop 1
	v_mov_b32_dpp v10, v1 row_bcast:31 row_mask:0xc bank_mask:0xf
	v_add_f32_e32 v1, v1, v10
	s_nop 0
	v_readlane_b32 s8, v1, 63
	s_and_saveexec_b64 s[4:5], vcc
	s_lshl_b32 s9, s96, 2
	s_add_i32 s9, s9, 0
	v_mov_b32_e32 v1, s9
	v_mov_b32_e32 v10, s8
	ds_write_b32 v1, v10
	s_or_b64 exec, exec, s[4:5]
	s_waitcnt lgkmcnt(0)
	s_barrier
	ds_read_b128 v[20:23], v11
	ds_read_b128 v[24:27], v11 offset:16
	s_waitcnt vmcnt(2)
	v_pk_mul_f32 v[8:9], v[8:9], v[16:17]
	v_pk_mul_f32 v[6:7], v[6:7], v[18:19]
	s_waitcnt lgkmcnt(1)
	v_add_f32_e32 v1, 0, v20
	v_add_f32_e32 v1, v1, v21
	v_add_f32_e32 v1, v1, v22
	v_add_f32_e32 v1, v1, v23
	s_waitcnt lgkmcnt(0)
	v_add_f32_e32 v1, v1, v24
	v_add_f32_e32 v1, v1, v25
	v_add_f32_e32 v1, v1, v26
	v_add_f32_e32 v10, v1, v27
	v_mov_b32_e32 v1, 0x358637bd
	v_fmamk_f32 v10, v10, 0x3a000000, v1
	v_rsq_f32_e32 v10, v10
	s_waitcnt vmcnt(0)
	v_cvt_f32_f16_sdwa v21, v12 dst_sel:DWORD dst_unused:UNUSED_PAD src0_sel:WORD_1
	v_cvt_f32_f16_e32 v20, v12
	v_cvt_f32_f16_sdwa v23, v13 dst_sel:DWORD dst_unused:UNUSED_PAD src0_sel:WORD_1
	v_cvt_f32_f16_e32 v22, v13
	v_pk_fma_f32 v[6:7], v[6:7], v[10:11], v[20:21] op_sel_hi:[1,0,1]
	s_nop 0
	v_cvt_f16_f32_sdwa v12, v7 dst_sel:WORD_1 dst_unused:UNUSED_PAD src0_sel:DWORD
	v_pk_fma_f32 v[8:9], v[8:9], v[10:11], v[22:23] op_sel_hi:[1,0,1]
	v_cvt_f16_f32_e32 v10, v6
	v_cvt_f16_f32_e32 v13, v8
	v_cvt_f16_f32_sdwa v16, v9 dst_sel:WORD_1 dst_unused:UNUSED_PAD src0_sel:DWORD
	v_or_b32_e32 v12, v12, v10
	v_mul_f32_e32 v10, v7, v7
	v_or_b32_e32 v13, v16, v13
	global_store_dwordx2 v[14:15], v[12:13], off
	v_mul_f32_e32 v12, v9, v9
	v_fmac_f32_e32 v10, v6, v6
	v_fmac_f32_e32 v12, v8, v8
	v_add_f32_e32 v10, v10, v12
	v_mov_b32_e32 v12, 0
	s_nop 0
	v_add_f32_dpp v10, v10, v10 quad_perm:[1,0,3,2] row_mask:0xf bank_mask:0xf bound_ctrl:1
	s_nop 1
	v_add_f32_dpp v10, v10, v10 quad_perm:[2,3,0,1] row_mask:0xf bank_mask:0xf bound_ctrl:1
	s_nop 1
	v_add_f32_dpp v10, v10, v10 row_half_mirror row_mask:0xf bank_mask:0xf bound_ctrl:1
	s_nop 1
	v_add_f32_dpp v10, v10, v10 row_mirror row_mask:0xf bank_mask:0xf bound_ctrl:1
	s_nop 1
	v_mov_b32_dpp v12, v10 row_bcast:15 row_mask:0xa bank_mask:0xf
	v_add_f32_e32 v10, v10, v12
	s_nop 1
	v_mov_b32_dpp v11, v10 row_bcast:31 row_mask:0xc bank_mask:0xf
	v_add_f32_e32 v10, v10, v11
	s_nop 0
	v_readlane_b32 s8, v10, 63
	s_and_saveexec_b64 s[4:5], vcc
	s_lshl_b32 s9, s96, 2
	s_add_i32 s9, s9, 0
	v_mov_b32_e32 v10, s9
	v_mov_b32_e32 v11, s8
	ds_write_b32 v10, v11 offset:32
	s_or_b64 exec, exec, s[4:5]
	v_mov_b32_e32 v10, 0
	s_waitcnt lgkmcnt(0)
	s_barrier
	ds_read_b128 v[12:15], v10 offset:32
	ds_read_b128 v[16:19], v10 offset:48
	v_pk_mul_f32 v[4:5], v[4:5], v[8:9]
	v_pk_mul_f32 v[6:7], v[2:3], v[6:7]
	s_waitcnt lgkmcnt(1)
	v_add_f32_e32 v11, 0, v12
	v_add_f32_e32 v11, v11, v13
	v_add_f32_e32 v11, v11, v14
	v_add_f32_e32 v11, v11, v15
	s_waitcnt lgkmcnt(0)
	v_add_f32_e32 v11, v11, v16
	v_add_f32_e32 v11, v11, v17
	v_add_f32_e32 v11, v11, v18
	v_add_f32_e32 v11, v11, v19
	v_fmac_f32_e32 v1, 0x3a000000, v11
	v_rsq_f32_e32 v12, v1
	s_nop 0
	v_pk_mul_f32 v[2:3], v[4:5], v[12:13] op_sel_hi:[1,0]
	v_pk_mul_f32 v[4:5], v[6:7], v[12:13] op_sel_hi:[1,0]
	v_max_f32_e64 v1, |v2|, |v3|
	v_max3_f32 v1, |v4|, |v5|, v1
	v_mov_b32_e32 v6, 0
	s_nop 1
	v_mov_b32_dpp v6, v1 quad_perm:[1,0,3,2] row_mask:0xf bank_mask:0xf
	v_max_f32_e32 v6, v6, v6
	v_max_f32_e32 v1, v1, v6
	v_mov_b32_e32 v6, 0
	s_nop 1
	v_mov_b32_dpp v6, v1 quad_perm:[2,3,0,1] row_mask:0xf bank_mask:0xf
	v_max_f32_e32 v6, v6, v6
	v_max_f32_e32 v1, v1, v6
	v_mov_b32_e32 v6, 0
	s_nop 1
	v_mov_b32_dpp v6, v1 row_half_mirror row_mask:0xf bank_mask:0xf
	v_max_f32_e32 v6, v6, v6
	v_max_f32_e32 v1, v1, v6
	v_mov_b32_e32 v6, 0
	s_nop 1
	v_mov_b32_dpp v6, v1 row_mirror row_mask:0xf bank_mask:0xf
	v_max_f32_e32 v6, v6, v6
	v_max_f32_e32 v1, v1, v6
	v_mov_b32_e32 v6, 0
	s_nop 1
	v_mov_b32_dpp v6, v1 row_bcast:15 row_mask:0xa bank_mask:0xf
	v_max_f32_e32 v6, v6, v6
	v_max_f32_e32 v1, v1, v6
	v_mov_b32_e32 v6, 0
	s_nop 1
	v_mov_b32_dpp v6, v1 row_bcast:31 row_mask:0xc bank_mask:0xf
	v_max_f32_e32 v6, v6, v6
	v_max_f32_e32 v1, v1, v6
	s_nop 0
	v_readlane_b32 s8, v1, 63
	s_and_saveexec_b64 s[4:5], vcc
	s_lshl_b32 s9, s96, 2
	s_add_i32 s9, s9, 0
	v_mov_b32_e32 v1, s9
	v_mov_b32_e32 v6, s8
	ds_write_b32 v1, v6 offset:64
	s_or_b64 exec, exec, s[4:5]
	s_waitcnt lgkmcnt(0)
	s_barrier
	ds_read_b128 v[6:9], v10 offset:64
	ds_read_b128 v[10:13], v10 offset:80
	s_lshl_b64 s[8:9], s[6:7], 11
	s_waitcnt lgkmcnt(1)
	v_max3_f32 v1, v6, 0, v7
	v_max3_f32 v1, v1, v8, v9
	s_waitcnt lgkmcnt(0)
	v_max3_f32 v1, v1, v10, v11
	v_max3_f32 v1, v1, v12, v13
	v_cmp_lt_f32_e64 s[4:5], 0, v1
	s_mov_b64 s[10:11], exec
	v_readlane_b32 s12, v254, 36
	v_readlane_b32 s13, v254, 37
	s_and_b64 s[12:13], s[10:11], s[12:13]
	s_mov_b64 exec, s[12:13]
	s_cbranch_execz .LBB0_661
	s_lshl_b64 s[6:7], s[6:7], 2
	v_mul_f32_e32 v6, 0x3c010204, v1
	s_add_u32 s6, s86, s6
	v_cndmask_b32_e64 v6, 1.0, v6, s[4:5]
	s_addc_u32 s7, s87, s7
	v_mov_b32_e32 v7, 0
	global_store_dword v7, v6, s[6:7]

.LBB0_906:
	s_cmp_lt_i32 s42, 11
	s_cselect_b64 s[4:5], -1, 0
	s_cmp_gt_i32 s43, 10
	s_cselect_b64 s[6:7], -1, 0
	s_and_b64 s[4:5], s[4:5], s[6:7]
	s_andn2_b64 vcc, exec, s[4:5]
	s_cbranch_vccnz .LBB0_986
	s_load_dwordx16 s[4:19], s[0:1], 0x0
	s_waitcnt lgkmcnt(0)
	s_mov_b64 s[8:9], s[12:13]
	s_mov_b64 s[10:11], s[14:15]
	s_mov_b64 s[12:13], s[16:17]
	s_mov_b64 s[14:15], s[18:19]
	s_add_u32 s8, s14, 0xa000
	s_addc_u32 s9, s15, 0
	s_add_u32 s10, s14, 0xc000
	s_addc_u32 s11, s15, 0
	s_ashr_i32 s5, s90, 5
	s_abs_i32 s4, s5
	v_cvt_f32_u32_e32 v169, s4
	s_sub_i32 s12, 0, s4
	s_abs_i32 s6, s62
	s_xor_b32 s7, s62, s5
	v_rcp_iflag_f32_e32 v169, v169
	s_ashr_i32 s7, s7, 31
	v_mul_f32_e32 v169, 0x4f7ffffe, v169
	v_cvt_u32_f32_e32 v169, v169
	s_nop 0
	v_readfirstlane_b32 s13, v169
	s_mul_i32 s12, s12, s13
	s_mul_hi_u32 s12, s13, s12
	s_add_i32 s13, s13, s12
	s_mul_hi_u32 s12, s6, s13
	s_mul_i32 s13, s12, s4
	s_sub_i32 s6, s6, s13
	s_add_i32 s14, s12, 1
	s_sub_i32 s13, s6, s4
	s_cmp_ge_u32 s6, s4
	s_cselect_b32 s12, s14, s12
	s_cselect_b32 s6, s13, s6
	s_add_i32 s13, s12, 1
	s_cmp_ge_u32 s6, s4
	s_cselect_b32 s4, s13, s12
	s_xor_b32 s4, s4, s7
	s_sub_i32 s4, s4, s7
	s_mul_i32 s5, s4, s5
	s_sub_i32 s5, s62, s5
	s_cmp_lg_u32 s5, 0
	s_ashr_i32 s5, s4, 31
	s_lshl_b64 s[6:7], s[4:5], 13
	v_readlane_b32 s12, v254, 58
	v_readlane_b32 s13, v254, 59
	s_add_u32 s6, s12, s6
	s_addc_u32 s7, s13, s7
	v_mov_b32_e32 v179, 0
	v_lshlrev_b32_e32 v178, 4, v0
	v_lshl_add_u64 v[170:171], s[6:7], 0, v[178:179]
	v_add_co_u32_e32 v172, vcc, 0x40000, v170
	global_load_dwordx4 v[184:187], v178, s[6:7]
	s_nop 0
	v_addc_co_u32_e32 v173, vcc, 0, v171, vcc
	v_add_co_u32_e32 v174, vcc, 0x80000, v170
	s_add_i32 s6, s4, 0x2000
	s_nop 0
	v_addc_co_u32_e32 v175, vcc, 0, v171, vcc
	v_add_co_u32_e32 v170, vcc, 0xc0000, v170
	global_load_dwordx4 v[188:191], v[172:173], off
	global_load_dwordx4 v[192:195], v[174:175], off
	v_addc_co_u32_e32 v171, vcc, 0, v171, vcc
	global_load_dwordx4 v[196:199], v[170:171], off
	s_ashr_i32 s7, s6, 31
	s_lshl_b64 s[4:5], s[6:7], 12
	v_readlane_b32 s12, v254, 54
	v_readlane_b32 s13, v254, 55
	s_add_u32 s4, s12, s4
	s_addc_u32 s5, s13, s5
	v_lshlrev_b32_e32 v182, 3, v0
	global_load_dwordx4 v[174:177], v178, s[8:9]
	global_load_dwordx4 v[170:173], v178, s[10:11]
	global_load_dwordx2 v[180:181], v182, s[4:5]
	s_lshl_b32 s4, s62, 3
	s_add_i32 s12, s4, s96
	s_and_b32 s4, s4, 0xf8
	s_lshl_b32 s5, s62, 5
	s_add_i32 s4, s4, s96
	s_and_b32 s5, s5, 0xfffffc00
	s_add_i32 s13, s4, s5
	s_add_i32 s15, s13, 0x400
	s_cmpk_eq_i32 s90, 0x100
	s_cselect_b64 s[4:5], -1, 0
	s_and_b64 s[6:7], s[4:5], exec
	s_cselect_b32 s14, s13, s12
	s_cselect_b32 s13, s15, 0x2000
	s_cmp_ge_i32 s14, s13
	s_cbranch_scc1 .LBB0_914
	s_lshl_b32 s6, s90, 3
	v_lshlrev_b32_e32 v1, 5, v166
	s_and_b64 s[4:5], s[4:5], exec
	v_or_b32_e32 v46, 0x800, v1
	v_or_b32_e32 v54, 0x1000, v1
	v_or_b32_e32 v62, 0x1800, v1
	s_cselect_b32 s16, 0x100, s6
	s_ashr_i32 s15, s14, 31
	global_load_dwordx4 v[2:5], v1, s[8:9] offset:16
	global_load_dwordx4 v[6:9], v1, s[8:9]
	global_load_dwordx4 v[10:13], v46, s[8:9] offset:16
	global_load_dwordx4 v[14:17], v46, s[8:9]
	global_load_dwordx4 v[18:21], v54, s[8:9] offset:16
	global_load_dwordx4 v[22:25], v54, s[8:9]
	global_load_dwordx4 v[26:29], v62, s[8:9] offset:16
	global_load_dwordx4 v[30:33], v62, s[8:9]
	global_load_dwordx4 v[34:37], v1, s[10:11] offset:16
	global_load_dwordx4 v[38:41], v1, s[10:11]
	global_load_dwordx4 v[42:45], v46, s[10:11] offset:16
	s_nop 0
	global_load_dwordx4 v[46:49], v46, s[10:11]
	s_nop 0
	global_load_dwordx4 v[50:53], v54, s[10:11] offset:16
	s_nop 0
	global_load_dwordx4 v[54:57], v54, s[10:11]
	s_lshl_b64 s[6:7], s[14:15], 11
	s_lshl_b64 s[18:19], s[14:15], 12
	v_readlane_b32 s4, v254, 54
	v_readlane_b32 s5, v254, 55
	s_add_u32 s4, s4, s18
	s_addc_u32 s5, s5, s19
	s_add_u32 s20, s80, s18
	v_lshlrev_b32_e32 v66, 4, v166
	s_addc_u32 s21, s81, s19
	global_load_dwordx4 v[110:113], v66, s[4:5]
	global_load_dwordx4 v[106:109], v66, s[4:5] offset:1024
	global_load_dwordx4 v[102:105], v66, s[4:5] offset:2048
	global_load_dwordx4 v[126:129], v66, s[20:21]
	global_load_dwordx4 v[122:125], v66, s[20:21] offset:1024
	global_load_dwordx4 v[98:101], v66, s[4:5] offset:3072
	global_load_dwordx4 v[118:121], v66, s[20:21] offset:2048
	global_load_dwordx4 v[114:117], v66, s[20:21] offset:3072
	global_load_dwordx4 v[58:61], v62, s[10:11] offset:16
	s_nop 0
	global_load_dwordx4 v[62:65], v62, s[10:11]
	v_lshl_or_b32 v130, v166, 3, s6
	v_mov_b32_e32 v131, s7
	s_lshl_b64 s[6:7], s[14:15], 2
	s_add_u32 s15, s6, 0x2ee80000
	s_addc_u32 s37, s7, 0
	s_add_i32 s6, s14, s16
	s_ashr_i32 s7, s6, 31
	s_lshl_b64 s[6:7], s[6:7], 12
	v_or_b32_e32 v132, s18, v66
	s_ashr_i32 s17, s16, 31
	v_or_b32_e32 v134, s6, v66
	v_cmp_eq_u32_e64 s[4:5], 0, v166
	s_mov_b32 s28, 0x2f1e0000
	s_mov_b32 s29, 0x2f1e1000
	v_mov_b32_e32 v1, 0
	v_mov_b32_e32 v136, 0x358637bd
	s_mov_b32 s30, 0x42fe0000
	s_mov_b32 s31, 0xc0c0400
	s_mov_b32 s34, 0xc040100
	s_mov_b32 s35, 0x4020100
	s_mov_b32 s36, 0x2de00000
	v_mov_b32_e32 v137, 0x3a000000
	v_mov_b32_e32 v138, 0x3c010204
	v_mov_b32_e32 v139, 0x42fe0000
	v_mov_b32_e32 v133, s19
	s_lshl_b64 s[18:19], s[16:17], 2
	s_lshl_b64 s[20:21], s[16:17], 11
	s_lshl_b64 s[22:23], s[16:17], 12
	v_mov_b32_e32 v135, s7
	s_waitcnt vmcnt(9)
	v_mov_b64_e32 v[66:67], v[110:111]
	s_waitcnt vmcnt(8)
	v_mov_b64_e32 v[70:71], v[106:107]
	s_waitcnt vmcnt(7)
	v_mov_b64_e32 v[78:79], v[102:103]
	s_waitcnt vmcnt(6)
	v_mov_b64_e32 v[74:75], v[126:127]
	s_waitcnt vmcnt(5)
	v_mov_b64_e32 v[82:83], v[122:123]
	s_waitcnt vmcnt(4)
	v_mov_b64_e32 v[94:95], v[98:99]
	s_waitcnt vmcnt(3)
	v_mov_b64_e32 v[86:87], v[118:119]
	s_waitcnt vmcnt(2)
	v_mov_b64_e32 v[90:91], v[114:115]
	v_mov_b64_e32 v[68:69], v[112:113]
	v_mov_b64_e32 v[72:73], v[108:109]
	v_mov_b64_e32 v[80:81], v[104:105]
	v_mov_b64_e32 v[76:77], v[128:129]
	v_mov_b64_e32 v[84:85], v[124:125]
	v_mov_b64_e32 v[88:89], v[120:121]
	v_mov_b64_e32 v[92:93], v[116:117]
	v_mov_b64_e32 v[96:97], v[100:101]
	s_branch .LBB0_910

.LBB0_922:
	s_cbranch_execz .LBB0_933
	s_ashr_i32 s5, s90, 5
	s_abs_i32 s4, s5
	v_cvt_f32_u32_e32 v1, s4
	s_sub_i32 s12, 0, s4
	s_abs_i32 s6, s62
	s_xor_b32 s7, s62, s5
	v_rcp_iflag_f32_e32 v1, v1
	s_ashr_i32 s7, s7, 31
	v_mul_f32_e32 v1, 0x4f7ffffe, v1
	v_cvt_u32_f32_e32 v1, v1
	s_nop 0
	v_readfirstlane_b32 s13, v1
	s_mul_i32 s12, s12, s13
	s_mul_hi_u32 s12, s13, s12
	s_add_i32 s13, s13, s12
	s_mul_hi_u32 s12, s6, s13
	s_mul_i32 s13, s12, s4
	s_sub_i32 s6, s6, s13
	s_add_i32 s14, s12, 1
	s_sub_i32 s13, s6, s4
	s_cmp_ge_u32 s6, s4
	s_cselect_b32 s12, s14, s12
	s_cselect_b32 s6, s13, s6
	s_add_i32 s13, s12, 1
	s_cmp_ge_u32 s6, s4
	s_cselect_b32 s4, s13, s12
	s_xor_b32 s4, s4, s7
	s_sub_i32 s4, s4, s7
	s_mul_i32 s5, s4, s5
	s_sub_i32 s5, s62, s5
	s_cmp_lg_u32 s5, 0
	s_cbranch_scc1 .LBB0_933
	s_ashr_i32 s5, s4, 31
	s_lshl_b64 s[6:7], s[4:5], 13
	v_readlane_b32 s12, v254, 58
	v_readlane_b32 s13, v254, 59
	s_add_u32 s6, s12, s6
	s_addc_u32 s7, s13, s7
	v_mov_b32_e32 v11, 0
	v_lshlrev_b32_e32 v10, 4, v0
	v_lshl_add_u64 v[2:3], s[6:7], 0, v[10:11]
	v_add_co_u32_e32 v4, vcc, 0x40000, v2
	s_waitcnt vmcnt(0)
	v_mov_b32_e32 v16, v184
	v_mov_b32_e32 v17, v185
	v_mov_b32_e32 v18, v186
	v_mov_b32_e32 v19, v187
	s_nop 0
	v_addc_co_u32_e32 v5, vcc, 0, v3, vcc
	v_add_co_u32_e32 v6, vcc, 0x80000, v2
	s_add_i32 s6, s4, 0x2000
	s_nop 0
	v_addc_co_u32_e32 v7, vcc, 0, v3, vcc
	v_add_co_u32_e32 v2, vcc, 0xc0000, v2
	v_mov_b32_e32 v20, v188
	v_mov_b32_e32 v21, v189
	v_mov_b32_e32 v22, v190
	v_mov_b32_e32 v23, v191
	v_mov_b32_e32 v24, v192
	v_mov_b32_e32 v25, v193
	v_mov_b32_e32 v26, v194
	v_mov_b32_e32 v27, v195
	v_addc_co_u32_e32 v3, vcc, 0, v3, vcc
	v_mov_b32_e32 v28, v196
	v_mov_b32_e32 v29, v197
	v_mov_b32_e32 v30, v198
	v_mov_b32_e32 v31, v199
	s_ashr_i32 s7, s6, 31
	s_lshl_b64 s[4:5], s[6:7], 12
	v_readlane_b32 s12, v254, 54
	v_readlane_b32 s13, v254, 55
	s_add_u32 s4, s12, s4
	s_addc_u32 s5, s13, s5
	v_lshlrev_b32_e32 v14, 3, v0
	v_mov_b32_e32 v6, v174
	v_mov_b32_e32 v7, v175
	v_mov_b32_e32 v8, v176
	v_mov_b32_e32 v9, v177
	v_mov_b32_e32 v2, v170
	v_mov_b32_e32 v3, v171
	v_mov_b32_e32 v4, v172
	v_mov_b32_e32 v5, v173
	v_mov_b32_e32 v12, v180
	v_mov_b32_e32 v13, v181
	v_mov_b32_e32 v1, v11
	v_mov_b32_e32 v10, v11
	v_mov_b32_e32 v15, v11
	v_lshl_add_u64 v[14:15], s[4:5], 0, v[14:15]
	v_cmp_eq_u32_e32 vcc, 0, v166
	s_waitcnt vmcnt(5)
	v_pk_add_f32 v[18:19], v[18:19], v[22:23]
	v_pk_add_f32 v[20:21], v[16:17], v[20:21]
	s_waitcnt vmcnt(3)
	v_pk_add_f32 v[16:17], v[26:27], v[30:31]
	v_pk_add_f32 v[22:23], v[24:25], v[28:29]
	v_pk_add_f32 v[16:17], v[18:19], v[16:17]
	v_pk_add_f32 v[18:19], v[20:21], v[22:23]
	v_mul_f32_e32 v21, v17, v17
	v_mul_f32_e32 v20, v19, v19
	v_fmac_f32_e32 v20, v18, v18
	v_fmac_f32_e32 v21, v16, v16
	v_add_f32_e32 v20, v20, v21
	s_nop 1
	v_add_f32_dpp v20, v20, v20 quad_perm:[1,0,3,2] row_mask:0xf bank_mask:0xf bound_ctrl:1
	s_nop 1
	v_add_f32_dpp v20, v20, v20 quad_perm:[2,3,0,1] row_mask:0xf bank_mask:0xf bound_ctrl:1
	s_nop 1
	v_add_f32_dpp v20, v20, v20 row_half_mirror row_mask:0xf bank_mask:0xf bound_ctrl:1
	s_nop 1
	v_add_f32_dpp v20, v20, v20 row_mirror row_mask:0xf bank_mask:0xf bound_ctrl:1
	s_nop 1
	v_mov_b32_dpp v1, v20 row_bcast:15 row_mask:0xa bank_mask:0xf
	v_add_f32_e32 v1, v20, v1
	s_nop 1
	v_mov_b32_dpp v10, v1 row_bcast:31 row_mask:0xc bank_mask:0xf
	v_add_f32_e32 v1, v1, v10
	s_nop 0
	v_readlane_b32 s8, v1, 63
	s_and_saveexec_b64 s[4:5], vcc
	s_lshl_b32 s9, s96, 2
	s_add_i32 s9, s9, 0
	v_mov_b32_e32 v1, s9
	v_mov_b32_e32 v10, s8
	ds_write_b32 v1, v10
	s_or_b64 exec, exec, s[4:5]
	s_waitcnt lgkmcnt(0)
	s_barrier
	ds_read_b128 v[20:23], v11
	ds_read_b128 v[24:27], v11 offset:16
	s_waitcnt vmcnt(2)
	v_pk_mul_f32 v[8:9], v[8:9], v[16:17]
	v_pk_mul_f32 v[6:7], v[6:7], v[18:19]
	s_waitcnt lgkmcnt(1)
	v_add_f32_e32 v1, 0, v20
	v_add_f32_e32 v1, v1, v21
	v_add_f32_e32 v1, v1, v22
	v_add_f32_e32 v1, v1, v23
	s_waitcnt lgkmcnt(0)
	v_add_f32_e32 v1, v1, v24
	v_add_f32_e32 v1, v1, v25
	v_add_f32_e32 v1, v1, v26
	v_add_f32_e32 v10, v1, v27
	v_mov_b32_e32 v1, 0x358637bd
	v_fmamk_f32 v10, v10, 0x3a000000, v1
	v_rsq_f32_e32 v10, v10
	s_waitcnt vmcnt(0)
	v_cvt_f32_f16_sdwa v21, v12 dst_sel:DWORD dst_unused:UNUSED_PAD src0_sel:WORD_1
	v_cvt_f32_f16_e32 v20, v12
	v_cvt_f32_f16_sdwa v23, v13 dst_sel:DWORD dst_unused:UNUSED_PAD src0_sel:WORD_1
	v_cvt_f32_f16_e32 v22, v13
	v_mul_f32_e32 v10, 0.5, v10
	v_pk_fma_f32 v[6:7], v[6:7], v[10:11], v[20:21] op_sel_hi:[1,0,1]
	v_pk_fma_f32 v[8:9], v[8:9], v[10:11], v[22:23] op_sel_hi:[1,0,1]
	v_cvt_f16_f32_e32 v10, v6
	v_cvt_f16_f32_sdwa v12, v7 dst_sel:WORD_1 dst_unused:UNUSED_PAD src0_sel:DWORD
	v_cvt_f16_f32_e32 v13, v8
	v_cvt_f16_f32_sdwa v16, v9 dst_sel:WORD_1 dst_unused:UNUSED_PAD src0_sel:DWORD
	v_or_b32_e32 v12, v12, v10
	v_mul_f32_e32 v10, v7, v7
	v_or_b32_e32 v13, v16, v13
	global_store_dwordx2 v[14:15], v[12:13], off
	v_mul_f32_e32 v12, v9, v9
	v_fmac_f32_e32 v10, v6, v6
	v_fmac_f32_e32 v12, v8, v8
	v_add_f32_e32 v10, v10, v12
	v_mov_b32_e32 v12, 0
	s_nop 0
	v_add_f32_dpp v10, v10, v10 quad_perm:[1,0,3,2] row_mask:0xf bank_mask:0xf bound_ctrl:1
	s_nop 1
	v_add_f32_dpp v10, v10, v10 quad_perm:[2,3,0,1] row_mask:0xf bank_mask:0xf bound_ctrl:1
	s_nop 1
	v_add_f32_dpp v10, v10, v10 row_half_mirror row_mask:0xf bank_mask:0xf bound_ctrl:1
	s_nop 1
	v_add_f32_dpp v10, v10, v10 row_mirror row_mask:0xf bank_mask:0xf bound_ctrl:1
	s_nop 1
	v_mov_b32_dpp v12, v10 row_bcast:15 row_mask:0xa bank_mask:0xf
	v_add_f32_e32 v10, v10, v12
	s_nop 1
	v_mov_b32_dpp v11, v10 row_bcast:31 row_mask:0xc bank_mask:0xf
	v_add_f32_e32 v10, v10, v11
	s_nop 0
	v_readlane_b32 s8, v10, 63
	s_and_saveexec_b64 s[4:5], vcc
	s_lshl_b32 s9, s96, 2
	s_add_i32 s9, s9, 0
	v_mov_b32_e32 v10, s9
	v_mov_b32_e32 v11, s8
	ds_write_b32 v10, v11 offset:32
	s_or_b64 exec, exec, s[4:5]
	v_mov_b32_e32 v10, 0
	s_waitcnt lgkmcnt(0)
	s_barrier
	ds_read_b128 v[12:15], v10 offset:32
	ds_read_b128 v[16:19], v10 offset:48
	v_pk_mul_f32 v[4:5], v[4:5], v[8:9]
	v_pk_mul_f32 v[6:7], v[2:3], v[6:7]
	s_waitcnt lgkmcnt(1)
	v_add_f32_e32 v11, 0, v12
	v_add_f32_e32 v11, v11, v13
	v_add_f32_e32 v11, v11, v14
	v_add_f32_e32 v11, v11, v15
	s_waitcnt lgkmcnt(0)
	v_add_f32_e32 v11, v11, v16
	v_add_f32_e32 v11, v11, v17
	v_add_f32_e32 v11, v11, v18
	v_add_f32_e32 v11, v11, v19
	v_fmac_f32_e32 v1, 0x3a000000, v11
	v_rsq_f32_e32 v12, v1
	s_nop 0
	v_pk_mul_f32 v[2:3], v[4:5], v[12:13] op_sel_hi:[1,0]
	v_pk_mul_f32 v[4:5], v[6:7], v[12:13] op_sel_hi:[1,0]
	v_max_f32_e64 v1, |v2|, |v3|
	v_max3_f32 v1, |v4|, |v5|, v1
	v_mov_b32_e32 v6, 0
	s_nop 1
	v_mov_b32_dpp v6, v1 quad_perm:[1,0,3,2] row_mask:0xf bank_mask:0xf
	v_max_f32_e32 v6, v6, v6
	v_max_f32_e32 v1, v1, v6
	v_mov_b32_e32 v6, 0
	s_nop 1
	v_mov_b32_dpp v6, v1 quad_perm:[2,3,0,1] row_mask:0xf bank_mask:0xf
	v_max_f32_e32 v6, v6, v6
	v_max_f32_e32 v1, v1, v6
	v_mov_b32_e32 v6, 0
	s_nop 1
	v_mov_b32_dpp v6, v1 row_half_mirror row_mask:0xf bank_mask:0xf
	v_max_f32_e32 v6, v6, v6
	v_max_f32_e32 v1, v1, v6
	v_mov_b32_e32 v6, 0
	s_nop 1
	v_mov_b32_dpp v6, v1 row_mirror row_mask:0xf bank_mask:0xf
	v_max_f32_e32 v6, v6, v6
	v_max_f32_e32 v1, v1, v6
	v_mov_b32_e32 v6, 0
	s_nop 1
	v_mov_b32_dpp v6, v1 row_bcast:15 row_mask:0xa bank_mask:0xf
	v_max_f32_e32 v6, v6, v6
	v_max_f32_e32 v1, v1, v6
	v_mov_b32_e32 v6, 0
	s_nop 1
	v_mov_b32_dpp v6, v1 row_bcast:31 row_mask:0xc bank_mask:0xf
	v_max_f32_e32 v6, v6, v6
	v_max_f32_e32 v1, v1, v6
	s_nop 0
	v_readlane_b32 s8, v1, 63
	s_and_saveexec_b64 s[4:5], vcc
	s_lshl_b32 s9, s96, 2
	s_add_i32 s9, s9, 0
	v_mov_b32_e32 v1, s9
	v_mov_b32_e32 v6, s8
	ds_write_b32 v1, v6 offset:64
	s_or_b64 exec, exec, s[4:5]
	s_waitcnt lgkmcnt(0)
	s_barrier
	ds_read_b128 v[6:9], v10 offset:64
	ds_read_b128 v[10:13], v10 offset:80
	s_lshl_b64 s[8:9], s[6:7], 11
	s_waitcnt lgkmcnt(1)
	v_max3_f32 v1, v6, 0, v7
	v_max3_f32 v1, v1, v8, v9
	s_waitcnt lgkmcnt(0)
	v_max3_f32 v1, v1, v10, v11
	v_max3_f32 v1, v1, v12, v13
	v_cmp_lt_f32_e64 s[4:5], 0, v1
	s_mov_b64 s[10:11], exec
	v_readlane_b32 s12, v254, 36
	v_readlane_b32 s13, v254, 37
	s_and_b64 s[12:13], s[10:11], s[12:13]
	s_mov_b64 exec, s[12:13]
	s_cbranch_execz .LBB0_932
	s_lshl_b64 s[6:7], s[6:7], 2
	v_mul_f32_e32 v6, 0x3c010204, v1
	s_add_u32 s6, s86, s6
	v_cndmask_b32_e64 v6, 1.0, v6, s[4:5]
	s_addc_u32 s7, s87, s7
	v_mov_b32_e32 v7, 0
	global_store_dword v7, v6, s[6:7]

.LBB0_1177:
	s_cmp_lt_i32 s42, 14
	s_cselect_b64 s[4:5], -1, 0
	s_cmp_gt_i32 s43, 13
	s_cselect_b64 s[6:7], -1, 0
	s_and_b64 s[4:5], s[4:5], s[6:7]
	s_andn2_b64 vcc, exec, s[4:5]
	s_cbranch_vccnz .LBB0_1249
	s_load_dwordx16 s[4:19], s[0:1], 0x0
	s_waitcnt lgkmcnt(0)
	s_mov_b64 s[8:9], s[12:13]
	s_mov_b64 s[10:11], s[14:15]
	s_mov_b64 s[12:13], s[16:17]
	s_mov_b64 s[14:15], s[18:19]
	s_add_u32 s4, s14, 0xe000
	s_addc_u32 s5, s15, 0
	s_add_u32 s6, s14, 0x10000
	s_addc_u32 s7, s15, 0
	s_ashr_i32 s9, s90, 5
	s_abs_i32 s8, s9
	v_cvt_f32_u32_e32 v169, s8
	s_sub_i32 s12, 0, s8
	s_abs_i32 s10, s62
	s_xor_b32 s11, s62, s9
	v_rcp_iflag_f32_e32 v169, v169
	s_ashr_i32 s11, s11, 31
	v_mul_f32_e32 v169, 0x4f7ffffe, v169
	v_cvt_u32_f32_e32 v169, v169
	s_nop 0
	v_readfirstlane_b32 s13, v169
	s_mul_i32 s12, s12, s13
	s_mul_hi_u32 s12, s13, s12
	s_add_i32 s13, s13, s12
	s_mul_hi_u32 s12, s10, s13
	s_mul_i32 s13, s12, s8
	s_sub_i32 s10, s10, s13
	s_add_i32 s14, s12, 1
	s_sub_i32 s13, s10, s8
	s_cmp_ge_u32 s10, s8
	s_cselect_b32 s12, s14, s12
	s_cselect_b32 s10, s13, s10
	s_add_i32 s13, s12, 1
	s_cmp_ge_u32 s10, s8
	s_cselect_b32 s8, s13, s12
	s_xor_b32 s8, s8, s11
	s_sub_i32 s8, s8, s11
	s_mul_i32 s9, s8, s9
	s_sub_i32 s9, s62, s9
	s_cmp_lg_u32 s9, 0
	s_ashr_i32 s9, s8, 31
	s_lshl_b64 s[10:11], s[8:9], 13
	v_readlane_b32 s12, v254, 58
	v_readlane_b32 s13, v254, 59
	s_add_u32 s10, s12, s10
	s_addc_u32 s11, s13, s11
	v_mov_b32_e32 v181, 0
	v_lshlrev_b32_e32 v180, 4, v0
	v_lshl_add_u64 v[170:171], s[10:11], 0, v[180:181]
	v_add_co_u32_e32 v172, vcc, 0x40000, v170
	global_load_dwordx4 v[186:189], v180, s[10:11]
	s_nop 0
	v_addc_co_u32_e32 v173, vcc, 0, v171, vcc
	v_add_co_u32_e32 v174, vcc, 0x80000, v170
	s_addk_i32 s8, 0x2000
	s_nop 0
	v_addc_co_u32_e32 v175, vcc, 0, v171, vcc
	v_add_co_u32_e32 v170, vcc, 0xc0000, v170
	global_load_dwordx4 v[190:193], v[172:173], off
	global_load_dwordx4 v[194:197], v[174:175], off
	v_addc_co_u32_e32 v171, vcc, 0, v171, vcc
	global_load_dwordx4 v[198:201], v[170:171], off
	s_ashr_i32 s9, s8, 31
	s_lshl_b64 s[10:11], s[8:9], 12
	v_readlane_b32 s12, v254, 54
	v_readlane_b32 s13, v254, 55
	s_add_u32 s10, s12, s10
	s_addc_u32 s11, s13, s11
	v_lshlrev_b32_e32 v178, 3, v0
	global_load_dwordx4 v[174:177], v180, s[4:5]
	global_load_dwordx4 v[170:173], v180, s[6:7]
	global_load_dwordx2 v[182:183], v178, s[10:11]
	s_lshl_b32 s9, s62, 3
	s_add_i32 s8, s9, s96
	s_and_b32 s9, s9, 0xf8
	s_lshl_b32 s10, s62, 5
	s_add_i32 s9, s9, s96
	s_and_b32 s10, s10, 0xfffffc00
	s_add_i32 s9, s9, s10
	s_add_i32 s14, s9, 0x400
	s_cmpk_eq_i32 s90, 0x100
	s_cselect_b64 s[12:13], -1, 0
	s_and_b64 s[10:11], s[12:13], exec
	s_cselect_b32 s10, s9, s8
	s_cselect_b32 s9, s14, 0x2000
	s_cmp_ge_i32 s10, s9
	s_cbranch_scc1 .LBB0_1183
	s_lshl_b32 s11, s90, 3
	v_lshlrev_b32_e32 v1, 5, v166
	s_and_b64 s[12:13], s[12:13], exec
	v_or_b32_e32 v46, 0x800, v1
	v_or_b32_e32 v54, 0x1000, v1
	v_or_b32_e32 v62, 0x1800, v1
	s_cselect_b32 s12, 0x100, s11
	s_ashr_i32 s11, s10, 31
	global_load_dwordx4 v[2:5], v1, s[4:5] offset:16
	global_load_dwordx4 v[6:9], v1, s[4:5]
	global_load_dwordx4 v[10:13], v46, s[4:5] offset:16
	global_load_dwordx4 v[14:17], v46, s[4:5]
	global_load_dwordx4 v[18:21], v54, s[4:5] offset:16
	global_load_dwordx4 v[22:25], v54, s[4:5]
	global_load_dwordx4 v[26:29], v62, s[4:5] offset:16
	global_load_dwordx4 v[30:33], v62, s[4:5]
	global_load_dwordx4 v[34:37], v1, s[6:7] offset:16
	global_load_dwordx4 v[38:41], v1, s[6:7]
	global_load_dwordx4 v[42:45], v46, s[6:7] offset:16
	s_nop 0
	global_load_dwordx4 v[46:49], v46, s[6:7]
	s_nop 0
	global_load_dwordx4 v[50:53], v54, s[6:7] offset:16
	s_nop 0
	global_load_dwordx4 v[54:57], v54, s[6:7]
	s_lshl_b64 s[14:15], s[10:11], 12
	v_readlane_b32 s16, v254, 54
	v_readlane_b32 s17, v254, 55
	s_add_u32 s16, s16, s14
	s_addc_u32 s17, s17, s15
	s_add_u32 s18, s80, s14
	v_lshlrev_b32_e32 v130, 4, v166
	s_addc_u32 s19, s81, s15
	global_load_dwordx4 v[110:113], v130, s[16:17]
	global_load_dwordx4 v[106:109], v130, s[16:17] offset:1024
	global_load_dwordx4 v[102:105], v130, s[16:17] offset:2048
	global_load_dwordx4 v[126:129], v130, s[18:19]
	global_load_dwordx4 v[122:125], v130, s[18:19] offset:1024
	global_load_dwordx4 v[98:101], v130, s[16:17] offset:3072
	global_load_dwordx4 v[118:121], v130, s[18:19] offset:2048
	global_load_dwordx4 v[114:117], v130, s[18:19] offset:3072
	global_load_dwordx4 v[58:61], v62, s[6:7] offset:16
	s_nop 0
	global_load_dwordx4 v[62:65], v62, s[6:7]
	s_add_u32 s14, s94, s14
	s_addc_u32 s15, s95, s15
	s_add_i32 s18, s10, s12
	s_ashr_i32 s13, s12, 31
	s_ashr_i32 s19, s18, 31
	s_lshl_b64 s[16:17], s[12:13], 12
	s_lshl_b64 s[18:19], s[18:19], 12
	s_add_u32 s18, s94, s18
	v_mov_b32_e32 v131, 0
	s_mov_b32 s11, 0x2f1e0000
	s_mov_b32 s22, 0x2f1e1000
	v_mov_b32_e32 v1, 0x358637bd
	s_mov_b32 s23, 0x1b500000
	v_mov_b32_e32 v132, 0x3a000000
	s_addc_u32 s19, s95, s19
	s_waitcnt vmcnt(9)
	v_mov_b64_e32 v[66:67], v[110:111]
	s_waitcnt vmcnt(8)
	v_mov_b64_e32 v[70:71], v[106:107]
	s_waitcnt vmcnt(7)
	v_mov_b64_e32 v[78:79], v[102:103]
	s_waitcnt vmcnt(6)
	v_mov_b64_e32 v[74:75], v[126:127]
	s_waitcnt vmcnt(5)
	v_mov_b64_e32 v[82:83], v[122:123]
	s_waitcnt vmcnt(4)
	v_mov_b64_e32 v[94:95], v[98:99]
	s_waitcnt vmcnt(3)
	v_mov_b64_e32 v[86:87], v[118:119]
	s_waitcnt vmcnt(2)
	v_mov_b64_e32 v[90:91], v[114:115]
	v_mov_b64_e32 v[68:69], v[112:113]
	v_mov_b64_e32 v[72:73], v[108:109]
	v_mov_b64_e32 v[80:81], v[104:105]
	v_mov_b64_e32 v[76:77], v[128:129]
	v_mov_b64_e32 v[84:85], v[124:125]
	v_mov_b64_e32 v[88:89], v[120:121]
	v_mov_b64_e32 v[92:93], v[116:117]
	v_mov_b64_e32 v[96:97], v[100:101]
	s_branch .LBB0_1181

.LBB0_1493:
	s_cmp_lt_i32 s42, 18
	s_cselect_b64 s[4:5], -1, 0
	s_cmp_gt_i32 s43, 17
	s_cselect_b64 s[6:7], -1, 0
	s_and_b64 s[4:5], s[4:5], s[6:7]
	s_andn2_b64 vcc, exec, s[4:5]
	s_cbranch_vccnz .LBB0_1573
	s_load_dwordx16 s[64:79], s[0:1], 0x0
	s_waitcnt lgkmcnt(0)
	s_mov_b64 s[12:13], s[76:77]
	s_mov_b64 s[14:15], s[78:79]
	s_add_u32 s8, s14, 0x12000
	s_addc_u32 s9, s15, 0
	s_add_u32 s10, s14, 0x14000
	s_addc_u32 s11, s15, 0
	s_ashr_i32 s5, s90, 5
	s_abs_i32 s4, s5
	v_cvt_f32_u32_e32 v169, s4
	s_sub_i32 s12, 0, s4
	s_abs_i32 s6, s62
	s_xor_b32 s7, s62, s5
	v_rcp_iflag_f32_e32 v169, v169
	s_ashr_i32 s7, s7, 31
	v_mul_f32_e32 v169, 0x4f7ffffe, v169
	v_cvt_u32_f32_e32 v169, v169
	s_nop 0
	v_readfirstlane_b32 s13, v169
	s_mul_i32 s12, s12, s13
	s_mul_hi_u32 s12, s13, s12
	s_add_i32 s13, s13, s12
	s_mul_hi_u32 s12, s6, s13
	s_mul_i32 s13, s12, s4
	s_sub_i32 s6, s6, s13
	s_add_i32 s14, s12, 1
	s_sub_i32 s13, s6, s4
	s_cmp_ge_u32 s6, s4
	s_cselect_b32 s12, s14, s12
	s_cselect_b32 s6, s13, s6
	s_add_i32 s13, s12, 1
	s_cmp_ge_u32 s6, s4
	s_cselect_b32 s4, s13, s12
	s_xor_b32 s4, s4, s7
	s_sub_i32 s4, s4, s7
	s_mul_i32 s5, s4, s5
	s_sub_i32 s5, s62, s5
	s_cmp_lg_u32 s5, 0
	s_ashr_i32 s5, s4, 31
	s_lshl_b64 s[6:7], s[4:5], 13
	v_readlane_b32 s12, v254, 58
	v_readlane_b32 s13, v254, 59
	s_add_u32 s6, s12, s6
	s_addc_u32 s7, s13, s7
	v_mov_b32_e32 v179, 0
	v_lshlrev_b32_e32 v178, 4, v0
	v_lshl_add_u64 v[170:171], s[6:7], 0, v[178:179]
	v_add_co_u32_e32 v172, vcc, 0x40000, v170
	global_load_dwordx4 v[184:187], v178, s[6:7]
	s_nop 0
	v_addc_co_u32_e32 v173, vcc, 0, v171, vcc
	v_add_co_u32_e32 v174, vcc, 0x80000, v170
	s_add_i32 s6, s4, 0x2000
	s_nop 0
	v_addc_co_u32_e32 v175, vcc, 0, v171, vcc
	v_add_co_u32_e32 v170, vcc, 0xc0000, v170
	global_load_dwordx4 v[188:191], v[172:173], off
	global_load_dwordx4 v[192:195], v[174:175], off
	v_addc_co_u32_e32 v171, vcc, 0, v171, vcc
	global_load_dwordx4 v[196:199], v[170:171], off
	s_ashr_i32 s7, s6, 31
	s_lshl_b64 s[4:5], s[6:7], 12
	v_readlane_b32 s12, v254, 54
	v_readlane_b32 s13, v254, 55
	s_add_u32 s4, s12, s4
	s_addc_u32 s5, s13, s5
	v_lshlrev_b32_e32 v182, 3, v0
	global_load_dwordx4 v[174:177], v178, s[8:9]
	global_load_dwordx4 v[170:173], v178, s[10:11]
	global_load_dwordx2 v[180:181], v182, s[4:5]
	s_lshl_b32 s4, s62, 3
	s_add_i32 s12, s4, s96
	s_and_b32 s4, s4, 0xf8
	s_lshl_b32 s5, s62, 5
	s_add_i32 s4, s4, s96
	s_and_b32 s5, s5, 0xfffffc00
	s_add_i32 s13, s4, s5
	s_add_i32 s15, s13, 0x400
	s_cmpk_eq_i32 s90, 0x100
	s_cselect_b64 s[4:5], -1, 0
	s_and_b64 s[6:7], s[4:5], exec
	s_cselect_b32 s14, s13, s12
	s_cselect_b32 s13, s15, 0x2000
	s_cmp_ge_i32 s14, s13
	s_cbranch_scc1 .LBB0_1501
	s_lshl_b32 s6, s90, 3
	v_lshlrev_b32_e32 v1, 5, v166
	s_and_b64 s[4:5], s[4:5], exec
	v_or_b32_e32 v46, 0x800, v1
	v_or_b32_e32 v54, 0x1000, v1
	v_or_b32_e32 v62, 0x1800, v1
	s_cselect_b32 s16, 0x100, s6
	s_ashr_i32 s15, s14, 31
	global_load_dwordx4 v[2:5], v1, s[8:9] offset:16
	global_load_dwordx4 v[6:9], v1, s[8:9]
	global_load_dwordx4 v[10:13], v46, s[8:9] offset:16
	global_load_dwordx4 v[14:17], v46, s[8:9]
	global_load_dwordx4 v[18:21], v54, s[8:9] offset:16
	global_load_dwordx4 v[22:25], v54, s[8:9]
	global_load_dwordx4 v[26:29], v62, s[8:9] offset:16
	global_load_dwordx4 v[30:33], v62, s[8:9]
	global_load_dwordx4 v[34:37], v1, s[10:11] offset:16
	global_load_dwordx4 v[38:41], v1, s[10:11]
	global_load_dwordx4 v[42:45], v46, s[10:11] offset:16
	s_nop 0
	global_load_dwordx4 v[46:49], v46, s[10:11]
	s_nop 0
	global_load_dwordx4 v[50:53], v54, s[10:11] offset:16
	s_nop 0
	global_load_dwordx4 v[54:57], v54, s[10:11]
	s_lshl_b64 s[6:7], s[14:15], 11
	s_lshl_b64 s[20:21], s[14:15], 12
	v_readlane_b32 s4, v254, 54
	v_readlane_b32 s5, v254, 55
	s_add_u32 s4, s4, s20
	s_addc_u32 s5, s5, s21
	s_add_u32 s22, s80, s20
	v_lshlrev_b32_e32 v66, 4, v166
	s_addc_u32 s23, s81, s21
	global_load_dwordx4 v[110:113], v66, s[4:5]
	global_load_dwordx4 v[106:109], v66, s[4:5] offset:1024
	global_load_dwordx4 v[102:105], v66, s[4:5] offset:2048
	global_load_dwordx4 v[126:129], v66, s[22:23]
	global_load_dwordx4 v[122:125], v66, s[22:23] offset:1024
	global_load_dwordx4 v[98:101], v66, s[4:5] offset:3072
	global_load_dwordx4 v[118:121], v66, s[22:23] offset:2048
	global_load_dwordx4 v[114:117], v66, s[22:23] offset:3072
	global_load_dwordx4 v[58:61], v62, s[10:11] offset:16
	s_nop 0
	global_load_dwordx4 v[62:65], v62, s[10:11]
	v_lshl_or_b32 v130, v166, 3, s6
	v_mov_b32_e32 v131, s7
	s_lshl_b64 s[6:7], s[14:15], 2
	s_add_u32 s15, s6, 0x2ee80000
	s_addc_u32 s39, s7, 0
	s_add_i32 s6, s14, s16
	s_ashr_i32 s7, s6, 31
	s_lshl_b64 s[6:7], s[6:7], 12
	v_or_b32_e32 v132, s20, v66
	s_ashr_i32 s17, s16, 31
	v_or_b32_e32 v134, s6, v66
	v_cmp_eq_u32_e64 s[4:5], 0, v166
	s_mov_b32 s30, 0x2f1e0000
	s_mov_b32 s31, 0x2f1e1000
	v_mov_b32_e32 v1, 0
	v_mov_b32_e32 v136, 0x358637bd
	s_mov_b32 s34, 0x42fe0000
	s_mov_b32 s35, 0xc0c0400
	s_mov_b32 s36, 0xc040100
	s_mov_b32 s37, 0x4020100
	s_mov_b32 s38, 0x2de00000
	v_mov_b32_e32 v137, 0x3a000000
	v_mov_b32_e32 v138, 0x3c010204
	v_mov_b32_e32 v139, 0x42fe0000
	v_mov_b32_e32 v133, s21
	s_lshl_b64 s[20:21], s[16:17], 2
	s_lshl_b64 s[22:23], s[16:17], 11
	s_lshl_b64 s[24:25], s[16:17], 12
	v_mov_b32_e32 v135, s7
	s_waitcnt vmcnt(9)
	v_mov_b64_e32 v[66:67], v[110:111]
	s_waitcnt vmcnt(8)
	v_mov_b64_e32 v[70:71], v[106:107]
	s_waitcnt vmcnt(7)
	v_mov_b64_e32 v[78:79], v[102:103]
	s_waitcnt vmcnt(6)
	v_mov_b64_e32 v[74:75], v[126:127]
	s_waitcnt vmcnt(5)
	v_mov_b64_e32 v[82:83], v[122:123]
	s_waitcnt vmcnt(4)
	v_mov_b64_e32 v[94:95], v[98:99]
	s_waitcnt vmcnt(3)
	v_mov_b64_e32 v[86:87], v[118:119]
	s_waitcnt vmcnt(2)
	v_mov_b64_e32 v[90:91], v[114:115]
	v_mov_b64_e32 v[68:69], v[112:113]
	v_mov_b64_e32 v[72:73], v[108:109]
	v_mov_b64_e32 v[80:81], v[104:105]
	v_mov_b64_e32 v[76:77], v[128:129]
	v_mov_b64_e32 v[84:85], v[124:125]
	v_mov_b64_e32 v[88:89], v[120:121]
	v_mov_b64_e32 v[92:93], v[116:117]
	v_mov_b64_e32 v[96:97], v[100:101]
	s_branch .LBB0_1497

.LBB0_1764:
	s_cmp_lt_i32 s42, 21
	s_cselect_b64 s[4:5], -1, 0
	s_cmp_gt_i32 s43, 20
	s_cselect_b64 s[6:7], -1, 0
	s_and_b64 s[4:5], s[4:5], s[6:7]
	s_andn2_b64 vcc, exec, s[4:5]
	s_cbranch_vccnz .LBB0_1844
	s_load_dwordx16 s[64:79], s[0:1], 0x0
	s_waitcnt lgkmcnt(0)
	s_mov_b64 s[12:13], s[76:77]
	s_mov_b64 s[14:15], s[78:79]
	s_add_u32 s8, s14, 0x16000
	s_addc_u32 s9, s15, 0
	s_add_u32 s10, s14, 0x18000
	s_addc_u32 s11, s15, 0
	s_ashr_i32 s5, s90, 5
	s_abs_i32 s4, s5
	v_cvt_f32_u32_e32 v169, s4
	s_sub_i32 s12, 0, s4
	s_abs_i32 s6, s62
	s_xor_b32 s7, s62, s5
	v_rcp_iflag_f32_e32 v169, v169
	s_ashr_i32 s7, s7, 31
	v_mul_f32_e32 v169, 0x4f7ffffe, v169
	v_cvt_u32_f32_e32 v169, v169
	s_nop 0
	v_readfirstlane_b32 s13, v169
	s_mul_i32 s12, s12, s13
	s_mul_hi_u32 s12, s13, s12
	s_add_i32 s13, s13, s12
	s_mul_hi_u32 s12, s6, s13
	s_mul_i32 s13, s12, s4
	s_sub_i32 s6, s6, s13
	s_add_i32 s14, s12, 1
	s_sub_i32 s13, s6, s4
	s_cmp_ge_u32 s6, s4
	s_cselect_b32 s12, s14, s12
	s_cselect_b32 s6, s13, s6
	s_add_i32 s13, s12, 1
	s_cmp_ge_u32 s6, s4
	s_cselect_b32 s4, s13, s12
	s_xor_b32 s4, s4, s7
	s_sub_i32 s4, s4, s7
	s_mul_i32 s5, s4, s5
	s_sub_i32 s5, s62, s5
	s_cmp_lg_u32 s5, 0
	s_ashr_i32 s5, s4, 31
	s_lshl_b64 s[6:7], s[4:5], 13
	v_readlane_b32 s12, v254, 58
	v_readlane_b32 s13, v254, 59
	s_add_u32 s6, s12, s6
	s_addc_u32 s7, s13, s7
	v_mov_b32_e32 v179, 0
	v_lshlrev_b32_e32 v178, 4, v0
	v_lshl_add_u64 v[170:171], s[6:7], 0, v[178:179]
	v_add_co_u32_e32 v172, vcc, 0x40000, v170
	global_load_dwordx4 v[184:187], v178, s[6:7]
	s_nop 0
	v_addc_co_u32_e32 v173, vcc, 0, v171, vcc
	v_add_co_u32_e32 v174, vcc, 0x80000, v170
	s_add_i32 s6, s4, 0x2000
	s_nop 0
	v_addc_co_u32_e32 v175, vcc, 0, v171, vcc
	v_add_co_u32_e32 v170, vcc, 0xc0000, v170
	global_load_dwordx4 v[188:191], v[172:173], off
	global_load_dwordx4 v[192:195], v[174:175], off
	v_addc_co_u32_e32 v171, vcc, 0, v171, vcc
	global_load_dwordx4 v[196:199], v[170:171], off
	s_ashr_i32 s7, s6, 31
	s_lshl_b64 s[4:5], s[6:7], 12
	v_readlane_b32 s12, v254, 54
	v_readlane_b32 s13, v254, 55
	s_add_u32 s4, s12, s4
	s_addc_u32 s5, s13, s5
	v_lshlrev_b32_e32 v182, 3, v0
	global_load_dwordx4 v[174:177], v178, s[8:9]
	global_load_dwordx4 v[170:173], v178, s[10:11]
	global_load_dwordx2 v[180:181], v182, s[4:5]
	s_lshl_b32 s4, s62, 3
	s_add_i32 s12, s4, s96
	s_and_b32 s4, s4, 0xf8
	s_lshl_b32 s5, s62, 5
	s_add_i32 s4, s4, s96
	s_and_b32 s5, s5, 0xfffffc00
	s_add_i32 s13, s4, s5
	s_add_i32 s15, s13, 0x400
	s_cmpk_eq_i32 s90, 0x100
	s_cselect_b64 s[4:5], -1, 0
	s_and_b64 s[6:7], s[4:5], exec
	s_cselect_b32 s14, s13, s12
	s_cselect_b32 s13, s15, 0x2000
	s_cmp_ge_i32 s14, s13
	s_cbranch_scc1 .LBB0_1772
	s_lshl_b32 s6, s90, 3
	v_lshlrev_b32_e32 v1, 5, v166
	s_and_b64 s[4:5], s[4:5], exec
	v_or_b32_e32 v46, 0x800, v1
	v_or_b32_e32 v54, 0x1000, v1
	v_or_b32_e32 v62, 0x1800, v1
	s_cselect_b32 s16, 0x100, s6
	s_ashr_i32 s15, s14, 31
	global_load_dwordx4 v[2:5], v1, s[8:9] offset:16
	global_load_dwordx4 v[6:9], v1, s[8:9]
	global_load_dwordx4 v[10:13], v46, s[8:9] offset:16
	global_load_dwordx4 v[14:17], v46, s[8:9]
	global_load_dwordx4 v[18:21], v54, s[8:9] offset:16
	global_load_dwordx4 v[22:25], v54, s[8:9]
	global_load_dwordx4 v[26:29], v62, s[8:9] offset:16
	global_load_dwordx4 v[30:33], v62, s[8:9]
	global_load_dwordx4 v[34:37], v1, s[10:11] offset:16
	global_load_dwordx4 v[38:41], v1, s[10:11]
	global_load_dwordx4 v[42:45], v46, s[10:11] offset:16
	s_nop 0
	global_load_dwordx4 v[46:49], v46, s[10:11]
	s_nop 0
	global_load_dwordx4 v[50:53], v54, s[10:11] offset:16
	s_nop 0
	global_load_dwordx4 v[54:57], v54, s[10:11]
	s_lshl_b64 s[6:7], s[14:15], 11
	s_lshl_b64 s[20:21], s[14:15], 12
	v_readlane_b32 s4, v254, 54
	v_readlane_b32 s5, v254, 55
	s_add_u32 s4, s4, s20
	s_addc_u32 s5, s5, s21
	s_add_u32 s22, s80, s20
	v_lshlrev_b32_e32 v66, 4, v166
	s_addc_u32 s23, s81, s21
	global_load_dwordx4 v[110:113], v66, s[4:5]
	global_load_dwordx4 v[106:109], v66, s[4:5] offset:1024
	global_load_dwordx4 v[102:105], v66, s[4:5] offset:2048
	global_load_dwordx4 v[126:129], v66, s[22:23]
	global_load_dwordx4 v[122:125], v66, s[22:23] offset:1024
	global_load_dwordx4 v[98:101], v66, s[4:5] offset:3072
	global_load_dwordx4 v[118:121], v66, s[22:23] offset:2048
	global_load_dwordx4 v[114:117], v66, s[22:23] offset:3072
	global_load_dwordx4 v[58:61], v62, s[10:11] offset:16
	s_nop 0
	global_load_dwordx4 v[62:65], v62, s[10:11]
	v_lshl_or_b32 v130, v166, 3, s6
	v_mov_b32_e32 v131, s7
	s_lshl_b64 s[6:7], s[14:15], 2
	s_add_u32 s15, s6, 0x2ee80000
	s_addc_u32 s39, s7, 0
	s_add_i32 s6, s14, s16
	s_ashr_i32 s7, s6, 31
	s_lshl_b64 s[6:7], s[6:7], 12
	v_or_b32_e32 v132, s20, v66
	s_ashr_i32 s17, s16, 31
	v_or_b32_e32 v134, s6, v66
	v_cmp_eq_u32_e64 s[4:5], 0, v166
	s_mov_b32 s30, 0x2f1e0000
	s_mov_b32 s31, 0x2f1e1000
	v_mov_b32_e32 v1, 0
	v_mov_b32_e32 v136, 0x358637bd
	s_mov_b32 s34, 0x42fe0000
	s_mov_b32 s35, 0xc0c0400
	s_mov_b32 s36, 0xc040100
	s_mov_b32 s37, 0x4020100
	s_mov_b32 s38, 0x2de00000
	v_mov_b32_e32 v137, 0x3a000000
	v_mov_b32_e32 v138, 0x3c010204
	v_mov_b32_e32 v139, 0x42fe0000
	v_mov_b32_e32 v133, s21
	s_lshl_b64 s[20:21], s[16:17], 2
	s_lshl_b64 s[22:23], s[16:17], 11
	s_lshl_b64 s[24:25], s[16:17], 12
	v_mov_b32_e32 v135, s7
	s_waitcnt vmcnt(9)
	v_mov_b64_e32 v[66:67], v[110:111]
	s_waitcnt vmcnt(8)
	v_mov_b64_e32 v[70:71], v[106:107]
	s_waitcnt vmcnt(7)
	v_mov_b64_e32 v[78:79], v[102:103]
	s_waitcnt vmcnt(6)
	v_mov_b64_e32 v[74:75], v[126:127]
	s_waitcnt vmcnt(5)
	v_mov_b64_e32 v[82:83], v[122:123]
	s_waitcnt vmcnt(4)
	v_mov_b64_e32 v[94:95], v[98:99]
	s_waitcnt vmcnt(3)
	v_mov_b64_e32 v[86:87], v[118:119]
	s_waitcnt vmcnt(2)
	v_mov_b64_e32 v[90:91], v[114:115]
	v_mov_b64_e32 v[68:69], v[112:113]
	v_mov_b64_e32 v[72:73], v[108:109]
	v_mov_b64_e32 v[80:81], v[104:105]
	v_mov_b64_e32 v[76:77], v[128:129]
	v_mov_b64_e32 v[84:85], v[124:125]
	v_mov_b64_e32 v[88:89], v[120:121]
	v_mov_b64_e32 v[92:93], v[116:117]
	v_mov_b64_e32 v[96:97], v[100:101]
	s_branch .LBB0_1768

.LBB0_2035:
	s_cmp_lt_i32 s42, 24
	s_cselect_b64 s[4:5], -1, 0
	s_cmp_gt_i32 s43, 23
	s_cselect_b64 s[6:7], -1, 0
	s_and_b64 s[4:5], s[4:5], s[6:7]
	s_andn2_b64 vcc, exec, s[4:5]
	s_cbranch_vccnz .LBB0_2107
	s_load_dwordx16 s[64:79], s[0:1], 0x0
	s_waitcnt lgkmcnt(0)
	s_mov_b64 s[12:13], s[76:77]
	s_mov_b64 s[14:15], s[78:79]
	s_add_u32 s4, s14, 0x1a000
	s_addc_u32 s5, s15, 0
	s_add_u32 s6, s14, 0x1c000
	s_addc_u32 s7, s15, 0
	s_ashr_i32 s9, s90, 5
	s_abs_i32 s8, s9
	v_cvt_f32_u32_e32 v169, s8
	s_sub_i32 s12, 0, s8
	s_abs_i32 s10, s62
	s_xor_b32 s11, s62, s9
	v_rcp_iflag_f32_e32 v169, v169
	s_ashr_i32 s11, s11, 31
	v_mul_f32_e32 v169, 0x4f7ffffe, v169
	v_cvt_u32_f32_e32 v169, v169
	s_nop 0
	v_readfirstlane_b32 s13, v169
	s_mul_i32 s12, s12, s13
	s_mul_hi_u32 s12, s13, s12
	s_add_i32 s13, s13, s12
	s_mul_hi_u32 s12, s10, s13
	s_mul_i32 s13, s12, s8
	s_sub_i32 s10, s10, s13
	s_add_i32 s14, s12, 1
	s_sub_i32 s13, s10, s8
	s_cmp_ge_u32 s10, s8
	s_cselect_b32 s12, s14, s12
	s_cselect_b32 s10, s13, s10
	s_add_i32 s13, s12, 1
	s_cmp_ge_u32 s10, s8
	s_cselect_b32 s8, s13, s12
	s_xor_b32 s8, s8, s11
	s_sub_i32 s8, s8, s11
	s_mul_i32 s9, s8, s9
	s_sub_i32 s9, s62, s9
	s_cmp_lg_u32 s9, 0
	s_ashr_i32 s9, s8, 31
	s_lshl_b64 s[10:11], s[8:9], 13
	v_readlane_b32 s12, v254, 58
	v_readlane_b32 s13, v254, 59
	s_add_u32 s10, s12, s10
	s_addc_u32 s11, s13, s11
	v_mov_b32_e32 v181, 0
	v_lshlrev_b32_e32 v180, 4, v0
	v_lshl_add_u64 v[170:171], s[10:11], 0, v[180:181]
	v_add_co_u32_e32 v172, vcc, 0x40000, v170
	global_load_dwordx4 v[186:189], v180, s[10:11]
	s_nop 0
	v_addc_co_u32_e32 v173, vcc, 0, v171, vcc
	v_add_co_u32_e32 v174, vcc, 0x80000, v170
	s_addk_i32 s8, 0x2000
	s_nop 0
	v_addc_co_u32_e32 v175, vcc, 0, v171, vcc
	v_add_co_u32_e32 v170, vcc, 0xc0000, v170
	global_load_dwordx4 v[190:193], v[172:173], off
	global_load_dwordx4 v[194:197], v[174:175], off
	v_addc_co_u32_e32 v171, vcc, 0, v171, vcc
	global_load_dwordx4 v[198:201], v[170:171], off
	s_ashr_i32 s9, s8, 31
	s_lshl_b64 s[10:11], s[8:9], 12
	v_readlane_b32 s12, v254, 54
	v_readlane_b32 s13, v254, 55
	s_add_u32 s10, s12, s10
	s_addc_u32 s11, s13, s11
	v_lshlrev_b32_e32 v178, 3, v0
	global_load_dwordx4 v[174:177], v180, s[4:5]
	global_load_dwordx4 v[170:173], v180, s[6:7]
	global_load_dwordx2 v[182:183], v178, s[10:11]
	s_lshl_b32 s9, s62, 3
	s_add_i32 s8, s9, s96
	s_and_b32 s9, s9, 0xf8
	s_lshl_b32 s10, s62, 5
	s_add_i32 s9, s9, s96
	s_and_b32 s10, s10, 0xfffffc00
	s_add_i32 s9, s9, s10
	s_add_i32 s14, s9, 0x400
	s_cmpk_eq_i32 s90, 0x100
	s_cselect_b64 s[12:13], -1, 0
	s_and_b64 s[10:11], s[12:13], exec
	s_cselect_b32 s10, s9, s8
	s_cselect_b32 s9, s14, 0x2000
	s_cmp_ge_i32 s10, s9
	s_cbranch_scc1 .LBB0_2041
	s_lshl_b32 s11, s90, 3
	v_lshlrev_b32_e32 v1, 5, v166
	s_and_b64 s[12:13], s[12:13], exec
	v_or_b32_e32 v46, 0x800, v1
	v_or_b32_e32 v54, 0x1000, v1
	v_or_b32_e32 v62, 0x1800, v1
	s_cselect_b32 s12, 0x100, s11
	s_ashr_i32 s11, s10, 31
	global_load_dwordx4 v[2:5], v1, s[4:5] offset:16
	global_load_dwordx4 v[6:9], v1, s[4:5]
	global_load_dwordx4 v[10:13], v46, s[4:5] offset:16
	global_load_dwordx4 v[14:17], v46, s[4:5]
	global_load_dwordx4 v[18:21], v54, s[4:5] offset:16
	global_load_dwordx4 v[22:25], v54, s[4:5]
	global_load_dwordx4 v[26:29], v62, s[4:5] offset:16
	global_load_dwordx4 v[30:33], v62, s[4:5]
	global_load_dwordx4 v[34:37], v1, s[6:7] offset:16
	global_load_dwordx4 v[38:41], v1, s[6:7]
	global_load_dwordx4 v[42:45], v46, s[6:7] offset:16
	s_nop 0
	global_load_dwordx4 v[46:49], v46, s[6:7]
	s_nop 0
	global_load_dwordx4 v[50:53], v54, s[6:7] offset:16
	s_nop 0
	global_load_dwordx4 v[54:57], v54, s[6:7]
	s_lshl_b64 s[14:15], s[10:11], 12
	v_readlane_b32 s16, v254, 54
	v_readlane_b32 s17, v254, 55
	s_add_u32 s16, s16, s14
	s_addc_u32 s17, s17, s15
	s_add_u32 s20, s80, s14
	v_lshlrev_b32_e32 v130, 4, v166
	s_addc_u32 s21, s81, s15
	global_load_dwordx4 v[110:113], v130, s[16:17]
	global_load_dwordx4 v[106:109], v130, s[16:17] offset:1024
	global_load_dwordx4 v[102:105], v130, s[16:17] offset:2048
	global_load_dwordx4 v[126:129], v130, s[20:21]
	global_load_dwordx4 v[122:125], v130, s[20:21] offset:1024
	global_load_dwordx4 v[98:101], v130, s[16:17] offset:3072
	global_load_dwordx4 v[118:121], v130, s[20:21] offset:2048
	global_load_dwordx4 v[114:117], v130, s[20:21] offset:3072
	global_load_dwordx4 v[58:61], v62, s[6:7] offset:16
	s_nop 0
	global_load_dwordx4 v[62:65], v62, s[6:7]
	s_add_u32 s14, s94, s14
	s_addc_u32 s15, s95, s15
	s_add_i32 s20, s10, s12
	s_ashr_i32 s13, s12, 31
	s_ashr_i32 s21, s20, 31
	s_lshl_b64 s[16:17], s[12:13], 12
	s_lshl_b64 s[20:21], s[20:21], 12
	s_add_u32 s20, s94, s20
	v_mov_b32_e32 v131, 0
	s_mov_b32 s11, 0x2f1e0000
	s_mov_b32 s24, 0x2f1e1000
	v_mov_b32_e32 v1, 0x358637bd
	s_mov_b32 s25, 0x1b500000
	v_mov_b32_e32 v132, 0x3a000000
	s_addc_u32 s21, s95, s21
	s_waitcnt vmcnt(9)
	v_mov_b64_e32 v[66:67], v[110:111]
	s_waitcnt vmcnt(8)
	v_mov_b64_e32 v[70:71], v[106:107]
	s_waitcnt vmcnt(7)
	v_mov_b64_e32 v[78:79], v[102:103]
	s_waitcnt vmcnt(6)
	v_mov_b64_e32 v[74:75], v[126:127]
	s_waitcnt vmcnt(5)
	v_mov_b64_e32 v[82:83], v[122:123]
	s_waitcnt vmcnt(4)
	v_mov_b64_e32 v[94:95], v[98:99]
	s_waitcnt vmcnt(3)
	v_mov_b64_e32 v[86:87], v[118:119]
	s_waitcnt vmcnt(2)
	v_mov_b64_e32 v[90:91], v[114:115]
	v_mov_b64_e32 v[68:69], v[112:113]
	v_mov_b64_e32 v[72:73], v[108:109]
	v_mov_b64_e32 v[80:81], v[104:105]
	v_mov_b64_e32 v[76:77], v[128:129]
	v_mov_b64_e32 v[84:85], v[124:125]
	v_mov_b64_e32 v[88:89], v[120:121]
	v_mov_b64_e32 v[92:93], v[116:117]
	v_mov_b64_e32 v[96:97], v[100:101]
	s_branch .LBB0_2039

.LBB0_2368:
	s_cmp_lt_i32 s42, 27
	s_cselect_b64 s[0:1], -1, 0
	s_cmp_gt_i32 s43, 26
	s_cselect_b64 s[4:5], -1, 0
	s_and_b64 s[0:1], s[0:1], s[4:5]
	s_andn2_b64 vcc, exec, s[0:1]
	s_cbranch_vccnz .LBB0_2448
	v_readlane_b32 s64, v254, 2
	v_readlane_b32 s78, v254, 16
	v_readlane_b32 s79, v254, 17
	s_mov_b64 s[14:15], s[78:79]
	s_add_u32 s6, s14, 0x1e000
	s_addc_u32 s7, s15, 0
	s_add_u32 s8, s14, 0x20000
	s_addc_u32 s9, s15, 0
	s_ashr_i32 s1, s90, 5
	s_abs_i32 s0, s1
	v_cvt_f32_u32_e32 v175, s0
	s_sub_i32 s10, 0, s0
	s_abs_i32 s4, s62
	s_xor_b32 s5, s62, s1
	v_rcp_iflag_f32_e32 v175, v175
	s_ashr_i32 s5, s5, 31
	v_mul_f32_e32 v175, 0x4f7ffffe, v175
	v_cvt_u32_f32_e32 v175, v175
	s_nop 0
	v_readfirstlane_b32 s11, v175
	s_mul_i32 s10, s10, s11
	s_mul_hi_u32 s10, s11, s10
	s_add_i32 s11, s11, s10
	s_mul_hi_u32 s10, s4, s11
	s_mul_i32 s11, s10, s0
	s_sub_i32 s4, s4, s11
	s_add_i32 s12, s10, 1
	s_sub_i32 s11, s4, s0
	s_cmp_ge_u32 s4, s0
	s_cselect_b32 s10, s12, s10
	s_cselect_b32 s4, s11, s4
	s_add_i32 s11, s10, 1
	s_cmp_ge_u32 s4, s0
	s_cselect_b32 s0, s11, s10
	s_xor_b32 s0, s0, s5
	s_sub_i32 s0, s0, s5
	s_mul_i32 s1, s0, s1
	s_sub_i32 s1, s62, s1
	s_cmp_lg_u32 s1, 0
	s_ashr_i32 s1, s0, 31
	s_lshl_b64 s[4:5], s[0:1], 13
	v_readlane_b32 s10, v254, 58
	v_readlane_b32 s11, v254, 59
	s_add_u32 s4, s10, s4
	s_addc_u32 s5, s11, s5
	v_mov_b32_e32 v185, 0
	v_lshlrev_b32_e32 v184, 4, v0
	v_lshl_add_u64 v[176:177], s[4:5], 0, v[184:185]
	v_add_co_u32_e32 v178, vcc, 0x40000, v176
	global_load_dwordx4 v[190:193], v184, s[4:5]
	s_nop 0
	v_addc_co_u32_e32 v179, vcc, 0, v177, vcc
	v_add_co_u32_e32 v180, vcc, 0x80000, v176
	s_add_i32 s4, s0, 0x2000
	s_nop 0
	v_addc_co_u32_e32 v181, vcc, 0, v177, vcc
	v_add_co_u32_e32 v176, vcc, 0xc0000, v176
	s_ashr_i32 s5, s4, 31
	s_nop 0
	v_addc_co_u32_e32 v177, vcc, 0, v177, vcc
	global_load_dwordx4 v[194:197], v[178:179], off
	global_load_dwordx4 v[198:201], v[180:181], off
	global_load_dwordx4 v[202:205], v[176:177], off
	s_lshl_b64 s[0:1], s[4:5], 12
	v_readlane_b32 s10, v254, 54
	v_readlane_b32 s11, v254, 55
	s_add_u32 s10, s10, s0
	s_addc_u32 s11, s11, s1
	s_add_u32 s0, s84, s0
	v_readlane_b32 s64, v254, 18
	v_lshlrev_b32_e32 v188, 3, v0
	s_addc_u32 s1, s85, s1
	v_readlane_b32 s66, v254, 20
	v_readlane_b32 s67, v254, 21
	global_load_dwordx2 v[210:211], v188, s[0:1]
	s_nop 3
	global_load_dwordx4 v[206:209], v184, s[66:67]
	global_load_dwordx4 v[180:183], v184, s[6:7]
	global_load_dwordx4 v[176:179], v184, s[8:9]
	global_load_dwordx2 v[186:187], v188, s[10:11]
	s_lshl_b32 s0, s62, 3
	s_add_i32 s10, s0, s96
	s_and_b32 s0, s0, 0xf8
	s_lshl_b32 s1, s62, 5
	s_add_i32 s0, s0, s96
	s_and_b32 s1, s1, 0xfffffc00
	s_add_i32 s11, s0, s1
	s_add_i32 s13, s11, 0x400
	s_cmpk_eq_i32 s90, 0x100
	s_cselect_b64 s[0:1], -1, 0
	s_and_b64 s[4:5], s[0:1], exec
	s_cselect_b32 s12, s11, s10
	s_cselect_b32 s11, s13, 0x2000
	s_cmp_ge_i32 s12, s11
	v_readlane_b32 s65, v254, 3
	v_readlane_b32 s66, v254, 4
	v_readlane_b32 s67, v254, 5
	v_readlane_b32 s68, v254, 6
	v_readlane_b32 s69, v254, 7
	v_readlane_b32 s70, v254, 8
	v_readlane_b32 s71, v254, 9
	v_readlane_b32 s72, v254, 10
	v_readlane_b32 s73, v254, 11
	v_readlane_b32 s74, v254, 12
	v_readlane_b32 s75, v254, 13
	v_readlane_b32 s76, v254, 14
	v_readlane_b32 s77, v254, 15
	s_cbranch_scc1 .LBB0_2376
	s_lshl_b32 s4, s90, 3
	v_lshlrev_b32_e32 v1, 5, v166
	s_and_b64 s[0:1], s[0:1], exec
	v_or_b32_e32 v46, 0x800, v1
	v_or_b32_e32 v54, 0x1000, v1
	v_or_b32_e32 v62, 0x1800, v1
	s_cselect_b32 s14, 0x100, s4
	s_ashr_i32 s13, s12, 31
	global_load_dwordx4 v[2:5], v1, s[6:7] offset:16
	global_load_dwordx4 v[6:9], v1, s[6:7]
	global_load_dwordx4 v[10:13], v46, s[6:7] offset:16
	global_load_dwordx4 v[14:17], v46, s[6:7]
	global_load_dwordx4 v[18:21], v54, s[6:7] offset:16
	global_load_dwordx4 v[22:25], v54, s[6:7]
	global_load_dwordx4 v[26:29], v62, s[6:7] offset:16
	global_load_dwordx4 v[30:33], v62, s[6:7]
	global_load_dwordx4 v[34:37], v1, s[8:9] offset:16
	global_load_dwordx4 v[38:41], v1, s[8:9]
	global_load_dwordx4 v[42:45], v46, s[8:9] offset:16
	s_nop 0
	global_load_dwordx4 v[46:49], v46, s[8:9]
	s_nop 0
	global_load_dwordx4 v[50:53], v54, s[8:9] offset:16
	s_nop 0
	global_load_dwordx4 v[54:57], v54, s[8:9]
	s_lshl_b64 s[4:5], s[12:13], 11
	s_lshl_b64 s[16:17], s[12:13], 12
	v_readlane_b32 s0, v254, 54
	v_readlane_b32 s1, v254, 55
	s_add_u32 s0, s0, s16
	s_addc_u32 s1, s1, s17
	s_add_u32 s20, s80, s16
	v_lshlrev_b32_e32 v66, 4, v166
	s_addc_u32 s21, s81, s17
	global_load_dwordx4 v[110:113], v66, s[0:1]
	global_load_dwordx4 v[106:109], v66, s[0:1] offset:1024
	global_load_dwordx4 v[102:105], v66, s[0:1] offset:2048
	global_load_dwordx4 v[126:129], v66, s[20:21]
	global_load_dwordx4 v[122:125], v66, s[20:21] offset:1024
	global_load_dwordx4 v[98:101], v66, s[0:1] offset:3072
	global_load_dwordx4 v[118:121], v66, s[20:21] offset:2048
	global_load_dwordx4 v[114:117], v66, s[20:21] offset:3072
	global_load_dwordx4 v[58:61], v62, s[8:9] offset:16
	s_nop 0
	global_load_dwordx4 v[62:65], v62, s[8:9]
	v_lshl_or_b32 v130, v166, 3, s4
	v_mov_b32_e32 v131, s5
	s_lshl_b64 s[4:5], s[12:13], 2
	s_add_u32 s13, s4, 0x2ee80000
	s_addc_u32 s37, s5, 0
	s_add_i32 s4, s12, s14
	s_ashr_i32 s5, s4, 31
	s_lshl_b64 s[4:5], s[4:5], 12
	v_or_b32_e32 v132, s16, v66
	s_ashr_i32 s15, s14, 31
	v_or_b32_e32 v134, s4, v66
	v_cmp_eq_u32_e64 s[0:1], 0, v166
	s_mov_b32 s28, 0x2f1e0000
	s_mov_b32 s29, 0x2f1e1000
	v_mov_b32_e32 v1, 0
	v_mov_b32_e32 v136, 0x358637bd
	s_mov_b32 s30, 0x42fe0000
	s_mov_b32 s31, 0xc0c0400
	s_mov_b32 s34, 0xc040100
	s_mov_b32 s35, 0x4020100
	s_mov_b32 s36, 0x2de00000
	v_mov_b32_e32 v137, 0x3a000000
	v_mov_b32_e32 v138, 0x3c010204
	v_mov_b32_e32 v139, 0x42fe0000
	v_mov_b32_e32 v133, s17
	s_lshl_b64 s[16:17], s[14:15], 2
	s_lshl_b64 s[20:21], s[14:15], 11
	s_lshl_b64 s[22:23], s[14:15], 12
	v_mov_b32_e32 v135, s5
	s_waitcnt vmcnt(9)
	v_mov_b64_e32 v[66:67], v[110:111]
	s_waitcnt vmcnt(8)
	v_mov_b64_e32 v[70:71], v[106:107]
	s_waitcnt vmcnt(7)
	v_mov_b64_e32 v[78:79], v[102:103]
	s_waitcnt vmcnt(6)
	v_mov_b64_e32 v[74:75], v[126:127]
	s_waitcnt vmcnt(5)
	v_mov_b64_e32 v[82:83], v[122:123]
	s_waitcnt vmcnt(4)
	v_mov_b64_e32 v[94:95], v[98:99]
	s_waitcnt vmcnt(3)
	v_mov_b64_e32 v[86:87], v[118:119]
	s_waitcnt vmcnt(2)
	v_mov_b64_e32 v[90:91], v[114:115]
	v_mov_b64_e32 v[68:69], v[112:113]
	v_mov_b64_e32 v[72:73], v[108:109]
	v_mov_b64_e32 v[80:81], v[104:105]
	v_mov_b64_e32 v[76:77], v[128:129]
	v_mov_b64_e32 v[84:85], v[124:125]
	v_mov_b64_e32 v[88:89], v[120:121]
	v_mov_b64_e32 v[92:93], v[116:117]
	v_mov_b64_e32 v[96:97], v[100:101]
	s_branch .LBB0_2372

.LBB0_2384:
	s_cbranch_execz .LBB0_2395
	s_ashr_i32 s1, s90, 5
	s_abs_i32 s0, s1
	v_cvt_f32_u32_e32 v1, s0
	s_sub_i32 s10, 0, s0
	s_abs_i32 s4, s62
	s_xor_b32 s5, s62, s1
	v_rcp_iflag_f32_e32 v1, v1
	s_ashr_i32 s5, s5, 31
	v_mul_f32_e32 v1, 0x4f7ffffe, v1
	v_cvt_u32_f32_e32 v1, v1
	s_nop 0
	v_readfirstlane_b32 s11, v1
	s_mul_i32 s10, s10, s11
	s_mul_hi_u32 s10, s11, s10
	s_add_i32 s11, s11, s10
	s_mul_hi_u32 s10, s4, s11
	s_mul_i32 s11, s10, s0
	s_sub_i32 s4, s4, s11
	s_add_i32 s12, s10, 1
	s_sub_i32 s11, s4, s0
	s_cmp_ge_u32 s4, s0
	s_cselect_b32 s10, s12, s10
	s_cselect_b32 s4, s11, s4
	s_add_i32 s11, s10, 1
	s_cmp_ge_u32 s4, s0
	s_cselect_b32 s0, s11, s10
	s_xor_b32 s0, s0, s5
	s_sub_i32 s0, s0, s5
	s_mul_i32 s1, s0, s1
	s_sub_i32 s1, s62, s1
	s_cmp_lg_u32 s1, 0
	s_cbranch_scc1 .LBB0_2395
	s_ashr_i32 s1, s0, 31
	s_lshl_b64 s[4:5], s[0:1], 13
	v_readlane_b32 s10, v254, 58
	v_readlane_b32 s11, v254, 59
	s_add_u32 s4, s10, s4
	s_addc_u32 s5, s11, s5
	v_mov_b32_e32 v11, 0
	v_lshlrev_b32_e32 v10, 4, v0
	v_lshl_add_u64 v[2:3], s[4:5], 0, v[10:11]
	v_add_co_u32_e32 v4, vcc, 0x40000, v2
	s_waitcnt vmcnt(0)
	v_mov_b32_e32 v16, v190
	v_mov_b32_e32 v17, v191
	v_mov_b32_e32 v18, v192
	v_mov_b32_e32 v19, v193
	s_nop 0
	v_addc_co_u32_e32 v5, vcc, 0, v3, vcc
	v_add_co_u32_e32 v6, vcc, 0x80000, v2
	s_add_i32 s4, s0, 0x2000
	s_nop 0
	v_addc_co_u32_e32 v7, vcc, 0, v3, vcc
	v_add_co_u32_e32 v2, vcc, 0xc0000, v2
	s_ashr_i32 s5, s4, 31
	s_nop 0
	v_addc_co_u32_e32 v3, vcc, 0, v3, vcc
	v_mov_b32_e32 v20, v194
	v_mov_b32_e32 v21, v195
	v_mov_b32_e32 v22, v196
	v_mov_b32_e32 v23, v197
	v_mov_b32_e32 v24, v198
	v_mov_b32_e32 v25, v199
	v_mov_b32_e32 v26, v200
	v_mov_b32_e32 v27, v201
	v_mov_b32_e32 v28, v202
	v_mov_b32_e32 v29, v203
	v_mov_b32_e32 v30, v204
	v_mov_b32_e32 v31, v205
	s_lshl_b64 s[0:1], s[4:5], 12
	v_readlane_b32 s10, v254, 54
	v_readlane_b32 s11, v254, 55
	s_add_u32 s10, s10, s0
	s_addc_u32 s11, s11, s1
	s_add_u32 s0, s84, s0
	v_readlane_b32 s64, v254, 18
	v_lshlrev_b32_e32 v14, 3, v0
	s_addc_u32 s1, s85, s1
	v_readlane_b32 s66, v254, 20
	v_readlane_b32 s67, v254, 21
	v_mov_b32_e32 v36, v210
	v_mov_b32_e32 v37, v211
	s_nop 3
	v_mov_b32_e32 v32, v206
	v_mov_b32_e32 v33, v207
	v_mov_b32_e32 v34, v208
	v_mov_b32_e32 v35, v209
	v_mov_b32_e32 v6, v180
	v_mov_b32_e32 v7, v181
	v_mov_b32_e32 v8, v182
	v_mov_b32_e32 v9, v183
	v_mov_b32_e32 v2, v176
	v_mov_b32_e32 v3, v177
	v_mov_b32_e32 v4, v178
	v_mov_b32_e32 v5, v179
	v_mov_b32_e32 v12, v186
	v_mov_b32_e32 v13, v187
	v_mov_b32_e32 v1, v11
	v_mov_b32_e32 v10, v11
	v_mov_b32_e32 v15, v11
	v_lshl_add_u64 v[14:15], s[10:11], 0, v[14:15]
	v_cmp_eq_u32_e32 vcc, 0, v166
	v_readlane_b32 s65, v254, 19
	v_readlane_b32 s68, v254, 22
	v_readlane_b32 s69, v254, 23
	v_readlane_b32 s70, v254, 24
	v_readlane_b32 s71, v254, 25
	v_readlane_b32 s72, v254, 26
	v_readlane_b32 s73, v254, 27
	v_readlane_b32 s74, v254, 28
	v_readlane_b32 s75, v254, 29
	v_readlane_b32 s76, v254, 30
	v_readlane_b32 s77, v254, 31
	v_readlane_b32 s78, v254, 32
	v_readlane_b32 s79, v254, 33
	s_waitcnt vmcnt(7)
	v_pk_add_f32 v[18:19], v[18:19], v[22:23]
	v_pk_add_f32 v[16:17], v[16:17], v[20:21]
	s_waitcnt vmcnt(5)
	v_pk_add_f32 v[20:21], v[26:27], v[30:31]
	v_pk_add_f32 v[22:23], v[24:25], v[28:29]
	v_pk_add_f32 v[18:19], v[18:19], v[20:21]
	v_pk_add_f32 v[16:17], v[16:17], v[22:23]
	s_waitcnt vmcnt(3)
	v_add_f32_e32 v18, v18, v34
	v_add_f32_e32 v16, v16, v32
	v_add_f32_e32 v17, v17, v33
	v_add_f32_e32 v19, v19, v35
	v_mul_f32_e32 v16, 0xbfb8aa3b, v16
	v_mul_f32_e32 v17, 0xbfb8aa3b, v17
	v_mul_f32_e32 v18, 0xbfb8aa3b, v18
	v_mul_f32_e32 v19, 0xbfb8aa3b, v19
	v_exp_f32_e32 v16, v16
	v_exp_f32_e32 v17, v17
	v_exp_f32_e32 v18, v18
	v_exp_f32_e32 v19, v19
	v_add_f32_e32 v16, 1.0, v16
	v_add_f32_e32 v17, 1.0, v17
	v_add_f32_e32 v18, 1.0, v18
	v_add_f32_e32 v19, 1.0, v19
	v_rcp_f32_e32 v16, v16
	v_rcp_f32_e32 v17, v17
	v_rcp_f32_e32 v22, v18
	v_rcp_f32_e32 v23, v19
	v_and_b32_e32 v21, 0xffff0000, v36
	v_lshlrev_b32_e32 v20, 16, v36
	v_and_b32_e32 v25, 0xffff0000, v37
	v_lshlrev_b32_e32 v24, 16, v37
	v_pk_mul_f32 v[18:19], v[16:17], v[20:21]
	v_pk_mul_f32 v[16:17], v[22:23], v[24:25]
	v_pk_mul_f32 v[20:21], v[18:19], v[18:19]
	v_pk_mul_f32 v[22:23], v[16:17], v[16:17]
	v_add_f32_e32 v20, v20, v21
	v_add_f32_e32 v22, v22, v23
	v_add_f32_e32 v20, v20, v22
	s_nop 1
	v_add_f32_dpp v20, v20, v20 quad_perm:[1,0,3,2] row_mask:0xf bank_mask:0xf bound_ctrl:1
	s_nop 1
	v_add_f32_dpp v20, v20, v20 quad_perm:[2,3,0,1] row_mask:0xf bank_mask:0xf bound_ctrl:1
	s_nop 1
	v_add_f32_dpp v20, v20, v20 row_half_mirror row_mask:0xf bank_mask:0xf bound_ctrl:1
	s_nop 1
	v_add_f32_dpp v20, v20, v20 row_mirror row_mask:0xf bank_mask:0xf bound_ctrl:1
	s_nop 1
	v_mov_b32_dpp v1, v20 row_bcast:15 row_mask:0xa bank_mask:0xf
	v_add_f32_e32 v1, v20, v1
	s_nop 1
	v_mov_b32_dpp v10, v1 row_bcast:31 row_mask:0xc bank_mask:0xf
	v_add_f32_e32 v1, v1, v10
	s_nop 0
	v_readlane_b32 s6, v1, 63
	s_and_saveexec_b64 s[0:1], vcc
	s_lshl_b32 s7, s96, 2
	s_add_i32 s7, s7, 0
	v_mov_b32_e32 v1, s7
	v_mov_b32_e32 v10, s6
	ds_write_b32 v1, v10
	s_or_b64 exec, exec, s[0:1]
	s_waitcnt lgkmcnt(0)
	s_barrier
	ds_read_b128 v[20:23], v11
	ds_read_b128 v[24:27], v11 offset:16
	s_waitcnt lgkmcnt(1)
	v_add_f32_e32 v1, 0, v20
	v_add_f32_e32 v1, v1, v21
	v_add_f32_e32 v1, v1, v22
	v_add_f32_e32 v1, v1, v23
	s_waitcnt lgkmcnt(0)
	v_add_f32_e32 v1, v1, v24
	v_add_f32_e32 v1, v1, v25
	v_add_f32_e32 v1, v1, v26
	v_add_f32_e32 v10, v1, v27
	v_mov_b32_e32 v1, 0x358637bd
	v_fmamk_f32 v10, v10, 0x3a000000, v1
	v_rsq_f32_e32 v10, v10
	s_waitcnt vmcnt(0)
	v_cvt_f32_f16_sdwa v21, v12 dst_sel:DWORD dst_unused:UNUSED_PAD src0_sel:WORD_1
	v_cvt_f32_f16_sdwa v23, v13 dst_sel:DWORD dst_unused:UNUSED_PAD src0_sel:WORD_1
	v_cvt_f32_f16_e32 v22, v13
	v_cvt_f32_f16_e32 v20, v12
	v_pk_mul_f32 v[12:13], v[6:7], v[18:19]
	v_pk_mul_f32 v[6:7], v[8:9], v[16:17]
	v_pk_fma_f32 v[8:9], v[12:13], v[10:11], v[20:21] op_sel_hi:[1,0,1]
	v_pk_fma_f32 v[6:7], v[6:7], v[10:11], v[22:23] op_sel_hi:[1,0,1]
	v_cvt_f16_f32_e32 v10, v8
	v_cvt_f16_f32_sdwa v12, v9 dst_sel:WORD_1 dst_unused:UNUSED_PAD src0_sel:DWORD
	v_cvt_f16_f32_e32 v13, v6
	v_cvt_f16_f32_sdwa v16, v7 dst_sel:WORD_1 dst_unused:UNUSED_PAD src0_sel:DWORD
	v_or_b32_e32 v12, v12, v10
	v_mul_f32_e32 v10, v9, v9
	v_or_b32_e32 v13, v16, v13
	global_store_dwordx2 v[14:15], v[12:13], off
	v_mul_f32_e32 v12, v7, v7
	v_fmac_f32_e32 v10, v8, v8
	v_fmac_f32_e32 v12, v6, v6
	v_add_f32_e32 v10, v10, v12
	v_mov_b32_e32 v12, 0
	s_nop 0
	v_add_f32_dpp v10, v10, v10 quad_perm:[1,0,3,2] row_mask:0xf bank_mask:0xf bound_ctrl:1
	s_nop 1
	v_add_f32_dpp v10, v10, v10 quad_perm:[2,3,0,1] row_mask:0xf bank_mask:0xf bound_ctrl:1
	s_nop 1
	v_add_f32_dpp v10, v10, v10 row_half_mirror row_mask:0xf bank_mask:0xf bound_ctrl:1
	s_nop 1
	v_add_f32_dpp v10, v10, v10 row_mirror row_mask:0xf bank_mask:0xf bound_ctrl:1
	s_nop 1
	v_mov_b32_dpp v12, v10 row_bcast:15 row_mask:0xa bank_mask:0xf
	v_add_f32_e32 v10, v10, v12
	s_nop 1
	v_mov_b32_dpp v11, v10 row_bcast:31 row_mask:0xc bank_mask:0xf
	v_add_f32_e32 v10, v10, v11
	s_nop 0
	v_readlane_b32 s6, v10, 63
	s_and_saveexec_b64 s[0:1], vcc
	s_lshl_b32 s7, s96, 2
	s_add_i32 s7, s7, 0
	v_mov_b32_e32 v10, s7
	v_mov_b32_e32 v11, s6
	ds_write_b32 v10, v11 offset:32
	s_or_b64 exec, exec, s[0:1]
	v_mov_b32_e32 v10, 0
	s_waitcnt lgkmcnt(0)
	s_barrier
	ds_read_b128 v[12:15], v10 offset:32
	ds_read_b128 v[16:19], v10 offset:48
	v_pk_mul_f32 v[4:5], v[4:5], v[6:7]
	v_pk_mul_f32 v[6:7], v[2:3], v[8:9]
	s_waitcnt lgkmcnt(1)
	v_add_f32_e32 v11, 0, v12
	v_add_f32_e32 v11, v11, v13
	v_add_f32_e32 v11, v11, v14
	v_add_f32_e32 v11, v11, v15
	s_waitcnt lgkmcnt(0)
	v_add_f32_e32 v11, v11, v16
	v_add_f32_e32 v11, v11, v17
	v_add_f32_e32 v11, v11, v18
	v_add_f32_e32 v11, v11, v19
	v_fmac_f32_e32 v1, 0x3a000000, v11
	v_rsq_f32_e32 v12, v1
	s_nop 0
	v_pk_mul_f32 v[2:3], v[4:5], v[12:13] op_sel_hi:[1,0]
	v_pk_mul_f32 v[4:5], v[6:7], v[12:13] op_sel_hi:[1,0]
	v_max_f32_e64 v1, |v2|, |v3|
	v_max3_f32 v1, |v4|, |v5|, v1
	v_mov_b32_e32 v6, 0
	s_nop 1
	v_mov_b32_dpp v6, v1 quad_perm:[1,0,3,2] row_mask:0xf bank_mask:0xf
	v_max_f32_e32 v6, v6, v6
	v_max_f32_e32 v1, v1, v6
	v_mov_b32_e32 v6, 0
	s_nop 1
	v_mov_b32_dpp v6, v1 quad_perm:[2,3,0,1] row_mask:0xf bank_mask:0xf
	v_max_f32_e32 v6, v6, v6
	v_max_f32_e32 v1, v1, v6
	v_mov_b32_e32 v6, 0
	s_nop 1
	v_mov_b32_dpp v6, v1 row_half_mirror row_mask:0xf bank_mask:0xf
	v_max_f32_e32 v6, v6, v6
	v_max_f32_e32 v1, v1, v6
	v_mov_b32_e32 v6, 0
	s_nop 1
	v_mov_b32_dpp v6, v1 row_mirror row_mask:0xf bank_mask:0xf
	v_max_f32_e32 v6, v6, v6
	v_max_f32_e32 v1, v1, v6
	v_mov_b32_e32 v6, 0
	s_nop 1
	v_mov_b32_dpp v6, v1 row_bcast:15 row_mask:0xa bank_mask:0xf
	v_max_f32_e32 v6, v6, v6
	v_max_f32_e32 v1, v1, v6
	v_mov_b32_e32 v6, 0
	s_nop 1
	v_mov_b32_dpp v6, v1 row_bcast:31 row_mask:0xc bank_mask:0xf
	v_max_f32_e32 v6, v6, v6
	v_max_f32_e32 v1, v1, v6
	s_nop 0
	v_readlane_b32 s6, v1, 63
	s_and_saveexec_b64 s[0:1], vcc
	s_lshl_b32 s7, s96, 2
	s_add_i32 s7, s7, 0
	v_mov_b32_e32 v1, s7
	v_mov_b32_e32 v6, s6
	ds_write_b32 v1, v6 offset:64
	s_or_b64 exec, exec, s[0:1]
	s_waitcnt lgkmcnt(0)
	s_barrier
	ds_read_b128 v[6:9], v10 offset:64
	ds_read_b128 v[10:13], v10 offset:80
	s_lshl_b64 s[6:7], s[4:5], 11
	s_waitcnt lgkmcnt(1)
	v_max3_f32 v1, v6, 0, v7
	v_max3_f32 v1, v1, v8, v9
	s_waitcnt lgkmcnt(0)
	v_max3_f32 v1, v1, v10, v11
	v_max3_f32 v1, v1, v12, v13
	v_cmp_lt_f32_e64 s[0:1], 0, v1
	s_mov_b64 s[8:9], exec
	v_readlane_b32 s10, v254, 36
	v_readlane_b32 s11, v254, 37
	s_and_b64 s[10:11], s[8:9], s[10:11]
	s_mov_b64 exec, s[10:11]
	s_cbranch_execz .LBB0_2394
	s_lshl_b64 s[4:5], s[4:5], 2
	v_mul_f32_e32 v6, 0x3c010204, v1
	s_add_u32 s4, s86, s4
	v_cndmask_b32_e64 v6, 1.0, v6, s[0:1]
	s_addc_u32 s5, s87, s5
	v_mov_b32_e32 v7, 0
	global_store_dword v7, v6, s[4:5]

.LBB0_2639:
	s_cmp_lt_i32 s42, 30
	s_cselect_b64 s[0:1], -1, 0
	s_cmp_gt_i32 s43, 29
	s_cselect_b64 s[4:5], -1, 0
	s_and_b64 s[0:1], s[0:1], s[4:5]
	s_andn2_b64 vcc, exec, s[0:1]
	s_cbranch_vccnz .LBB0_2719
	v_readlane_b32 s64, v254, 2
	v_readlane_b32 s78, v254, 16
	v_readlane_b32 s79, v254, 17
	s_mov_b64 s[14:15], s[78:79]
	s_add_u32 s6, s14, 0x22000
	s_addc_u32 s7, s15, 0
	s_add_u32 s8, s14, 0x24000
	s_addc_u32 s9, s15, 0
	s_ashr_i32 s1, s90, 5
	s_abs_i32 s0, s1
	v_cvt_f32_u32_e32 v169, s0
	s_sub_i32 s10, 0, s0
	s_abs_i32 s4, s62
	s_xor_b32 s5, s62, s1
	v_rcp_iflag_f32_e32 v169, v169
	s_ashr_i32 s5, s5, 31
	v_mul_f32_e32 v169, 0x4f7ffffe, v169
	v_cvt_u32_f32_e32 v169, v169
	s_nop 0
	v_readfirstlane_b32 s11, v169
	s_mul_i32 s10, s10, s11
	s_mul_hi_u32 s10, s11, s10
	s_add_i32 s11, s11, s10
	s_mul_hi_u32 s10, s4, s11
	s_mul_i32 s11, s10, s0
	s_sub_i32 s4, s4, s11
	s_add_i32 s12, s10, 1
	s_sub_i32 s11, s4, s0
	s_cmp_ge_u32 s4, s0
	s_cselect_b32 s10, s12, s10
	s_cselect_b32 s4, s11, s4
	s_add_i32 s11, s10, 1
	s_cmp_ge_u32 s4, s0
	s_cselect_b32 s0, s11, s10
	s_xor_b32 s0, s0, s5
	s_sub_i32 s0, s0, s5
	s_mul_i32 s1, s0, s1
	s_sub_i32 s1, s62, s1
	s_cmp_lg_u32 s1, 0
	s_ashr_i32 s1, s0, 31
	s_lshl_b64 s[4:5], s[0:1], 13
	v_readlane_b32 s10, v254, 58
	v_readlane_b32 s11, v254, 59
	s_add_u32 s4, s10, s4
	s_addc_u32 s5, s11, s5
	v_mov_b32_e32 v179, 0
	v_lshlrev_b32_e32 v178, 4, v0
	v_lshl_add_u64 v[170:171], s[4:5], 0, v[178:179]
	v_add_co_u32_e32 v172, vcc, 0x40000, v170
	global_load_dwordx4 v[184:187], v178, s[4:5]
	s_nop 0
	v_addc_co_u32_e32 v173, vcc, 0, v171, vcc
	v_add_co_u32_e32 v174, vcc, 0x80000, v170
	s_add_i32 s4, s0, 0x2000
	s_nop 0
	v_addc_co_u32_e32 v175, vcc, 0, v171, vcc
	v_add_co_u32_e32 v170, vcc, 0xc0000, v170
	global_load_dwordx4 v[188:191], v[172:173], off
	global_load_dwordx4 v[192:195], v[174:175], off
	v_addc_co_u32_e32 v171, vcc, 0, v171, vcc
	global_load_dwordx4 v[196:199], v[170:171], off
	s_ashr_i32 s5, s4, 31
	s_lshl_b64 s[0:1], s[4:5], 12
	v_readlane_b32 s10, v254, 54
	v_readlane_b32 s11, v254, 55
	s_add_u32 s0, s10, s0
	s_addc_u32 s1, s11, s1
	v_lshlrev_b32_e32 v182, 3, v0
	global_load_dwordx4 v[174:177], v178, s[6:7]
	global_load_dwordx4 v[170:173], v178, s[8:9]
	global_load_dwordx2 v[180:181], v182, s[0:1]
	s_lshl_b32 s0, s62, 3
	s_add_i32 s10, s0, s96
	s_and_b32 s0, s0, 0xf8
	s_lshl_b32 s1, s62, 5
	s_add_i32 s0, s0, s96
	s_and_b32 s1, s1, 0xfffffc00
	s_add_i32 s11, s0, s1
	s_add_i32 s13, s11, 0x400
	s_cmpk_eq_i32 s90, 0x100
	s_cselect_b64 s[0:1], -1, 0
	s_and_b64 s[4:5], s[0:1], exec
	s_cselect_b32 s12, s11, s10
	s_cselect_b32 s11, s13, 0x2000
	s_cmp_ge_i32 s12, s11
	v_readlane_b32 s65, v254, 3
	v_readlane_b32 s66, v254, 4
	v_readlane_b32 s67, v254, 5
	v_readlane_b32 s68, v254, 6
	v_readlane_b32 s69, v254, 7
	v_readlane_b32 s70, v254, 8
	v_readlane_b32 s71, v254, 9
	v_readlane_b32 s72, v254, 10
	v_readlane_b32 s73, v254, 11
	v_readlane_b32 s74, v254, 12
	v_readlane_b32 s75, v254, 13
	v_readlane_b32 s76, v254, 14
	v_readlane_b32 s77, v254, 15
	s_cbranch_scc1 .LBB0_2647
	s_lshl_b32 s4, s90, 3
	v_lshlrev_b32_e32 v1, 5, v166
	s_and_b64 s[0:1], s[0:1], exec
	v_or_b32_e32 v46, 0x800, v1
	v_or_b32_e32 v54, 0x1000, v1
	v_or_b32_e32 v62, 0x1800, v1
	s_cselect_b32 s14, 0x100, s4
	s_ashr_i32 s13, s12, 31
	global_load_dwordx4 v[2:5], v1, s[6:7] offset:16
	global_load_dwordx4 v[6:9], v1, s[6:7]
	global_load_dwordx4 v[10:13], v46, s[6:7] offset:16
	global_load_dwordx4 v[14:17], v46, s[6:7]
	global_load_dwordx4 v[18:21], v54, s[6:7] offset:16
	global_load_dwordx4 v[22:25], v54, s[6:7]
	global_load_dwordx4 v[26:29], v62, s[6:7] offset:16
	global_load_dwordx4 v[30:33], v62, s[6:7]
	global_load_dwordx4 v[34:37], v1, s[8:9] offset:16
	global_load_dwordx4 v[38:41], v1, s[8:9]
	global_load_dwordx4 v[42:45], v46, s[8:9] offset:16
	s_nop 0
	global_load_dwordx4 v[46:49], v46, s[8:9]
	s_nop 0
	global_load_dwordx4 v[50:53], v54, s[8:9] offset:16
	s_nop 0
	global_load_dwordx4 v[54:57], v54, s[8:9]
	s_lshl_b64 s[4:5], s[12:13], 11
	s_lshl_b64 s[16:17], s[12:13], 12
	v_readlane_b32 s0, v254, 54
	v_readlane_b32 s1, v254, 55
	s_add_u32 s0, s0, s16
	s_addc_u32 s1, s1, s17
	s_add_u32 s20, s80, s16
	v_lshlrev_b32_e32 v66, 4, v166
	s_addc_u32 s21, s81, s17
	global_load_dwordx4 v[110:113], v66, s[0:1]
	global_load_dwordx4 v[106:109], v66, s[0:1] offset:1024
	global_load_dwordx4 v[102:105], v66, s[0:1] offset:2048
	global_load_dwordx4 v[126:129], v66, s[20:21]
	global_load_dwordx4 v[122:125], v66, s[20:21] offset:1024
	global_load_dwordx4 v[98:101], v66, s[0:1] offset:3072
	global_load_dwordx4 v[118:121], v66, s[20:21] offset:2048
	global_load_dwordx4 v[114:117], v66, s[20:21] offset:3072
	global_load_dwordx4 v[58:61], v62, s[8:9] offset:16
	s_nop 0
	global_load_dwordx4 v[62:65], v62, s[8:9]
	v_lshl_or_b32 v130, v166, 3, s4
	v_mov_b32_e32 v131, s5
	s_lshl_b64 s[4:5], s[12:13], 2
	s_add_u32 s13, s4, 0x2ee80000
	s_addc_u32 s37, s5, 0
	s_add_i32 s4, s12, s14
	s_ashr_i32 s5, s4, 31
	s_lshl_b64 s[4:5], s[4:5], 12
	v_or_b32_e32 v132, s16, v66
	s_ashr_i32 s15, s14, 31
	v_or_b32_e32 v134, s4, v66
	v_cmp_eq_u32_e64 s[0:1], 0, v166
	s_mov_b32 s28, 0x2f1e0000
	s_mov_b32 s29, 0x2f1e1000
	v_mov_b32_e32 v1, 0
	v_mov_b32_e32 v136, 0x358637bd
	s_mov_b32 s30, 0x42fe0000
	s_mov_b32 s31, 0xc0c0400
	s_mov_b32 s34, 0xc040100
	s_mov_b32 s35, 0x4020100
	s_mov_b32 s36, 0x2de00000
	v_mov_b32_e32 v137, 0x3a000000
	v_mov_b32_e32 v138, 0x3c010204
	v_mov_b32_e32 v139, 0x42fe0000
	v_mov_b32_e32 v133, s17
	s_lshl_b64 s[16:17], s[14:15], 2
	s_lshl_b64 s[20:21], s[14:15], 11
	s_lshl_b64 s[22:23], s[14:15], 12
	v_mov_b32_e32 v135, s5
	s_waitcnt vmcnt(9)
	v_mov_b64_e32 v[66:67], v[110:111]
	s_waitcnt vmcnt(8)
	v_mov_b64_e32 v[70:71], v[106:107]
	s_waitcnt vmcnt(7)
	v_mov_b64_e32 v[78:79], v[102:103]
	s_waitcnt vmcnt(6)
	v_mov_b64_e32 v[74:75], v[126:127]
	s_waitcnt vmcnt(5)
	v_mov_b64_e32 v[82:83], v[122:123]
	s_waitcnt vmcnt(4)
	v_mov_b64_e32 v[94:95], v[98:99]
	s_waitcnt vmcnt(3)
	v_mov_b64_e32 v[86:87], v[118:119]
	s_waitcnt vmcnt(2)
	v_mov_b64_e32 v[90:91], v[114:115]
	v_mov_b64_e32 v[68:69], v[112:113]
	v_mov_b64_e32 v[72:73], v[108:109]
	v_mov_b64_e32 v[80:81], v[104:105]
	v_mov_b64_e32 v[76:77], v[128:129]
	v_mov_b64_e32 v[84:85], v[124:125]
	v_mov_b64_e32 v[88:89], v[120:121]
	v_mov_b64_e32 v[92:93], v[116:117]
	v_mov_b64_e32 v[96:97], v[100:101]
	s_branch .LBB0_2643

.LBB0_2655:
	s_cbranch_execz .LBB0_2666
	s_ashr_i32 s1, s90, 5
	s_abs_i32 s0, s1
	v_cvt_f32_u32_e32 v1, s0
	s_sub_i32 s10, 0, s0
	s_abs_i32 s4, s62
	s_xor_b32 s5, s62, s1
	v_rcp_iflag_f32_e32 v1, v1
	s_ashr_i32 s5, s5, 31
	v_mul_f32_e32 v1, 0x4f7ffffe, v1
	v_cvt_u32_f32_e32 v1, v1
	s_nop 0
	v_readfirstlane_b32 s11, v1
	s_mul_i32 s10, s10, s11
	s_mul_hi_u32 s10, s11, s10
	s_add_i32 s11, s11, s10
	s_mul_hi_u32 s10, s4, s11
	s_mul_i32 s11, s10, s0
	s_sub_i32 s4, s4, s11
	s_add_i32 s12, s10, 1
	s_sub_i32 s11, s4, s0
	s_cmp_ge_u32 s4, s0
	s_cselect_b32 s10, s12, s10
	s_cselect_b32 s4, s11, s4
	s_add_i32 s11, s10, 1
	s_cmp_ge_u32 s4, s0
	s_cselect_b32 s0, s11, s10
	s_xor_b32 s0, s0, s5
	s_sub_i32 s0, s0, s5
	s_mul_i32 s1, s0, s1
	s_sub_i32 s1, s62, s1
	s_cmp_lg_u32 s1, 0
	s_cbranch_scc1 .LBB0_2666
	s_ashr_i32 s1, s0, 31
	s_lshl_b64 s[4:5], s[0:1], 13
	v_readlane_b32 s10, v254, 58
	v_readlane_b32 s11, v254, 59
	s_add_u32 s4, s10, s4
	s_addc_u32 s5, s11, s5
	v_mov_b32_e32 v11, 0
	v_lshlrev_b32_e32 v10, 4, v0
	v_lshl_add_u64 v[2:3], s[4:5], 0, v[10:11]
	v_add_co_u32_e32 v4, vcc, 0x40000, v2
	s_waitcnt vmcnt(0)
	v_mov_b32_e32 v16, v184
	v_mov_b32_e32 v17, v185
	v_mov_b32_e32 v18, v186
	v_mov_b32_e32 v19, v187
	s_nop 0
	v_addc_co_u32_e32 v5, vcc, 0, v3, vcc
	v_add_co_u32_e32 v6, vcc, 0x80000, v2
	s_add_i32 s4, s0, 0x2000
	s_nop 0
	v_addc_co_u32_e32 v7, vcc, 0, v3, vcc
	v_add_co_u32_e32 v2, vcc, 0xc0000, v2
	v_mov_b32_e32 v20, v188
	v_mov_b32_e32 v21, v189
	v_mov_b32_e32 v22, v190
	v_mov_b32_e32 v23, v191
	v_mov_b32_e32 v24, v192
	v_mov_b32_e32 v25, v193
	v_mov_b32_e32 v26, v194
	v_mov_b32_e32 v27, v195
	v_addc_co_u32_e32 v3, vcc, 0, v3, vcc
	v_mov_b32_e32 v28, v196
	v_mov_b32_e32 v29, v197
	v_mov_b32_e32 v30, v198
	v_mov_b32_e32 v31, v199
	s_ashr_i32 s5, s4, 31
	s_lshl_b64 s[0:1], s[4:5], 12
	v_readlane_b32 s10, v254, 54
	v_readlane_b32 s11, v254, 55
	s_add_u32 s0, s10, s0
	s_addc_u32 s1, s11, s1
	v_lshlrev_b32_e32 v14, 3, v0
	v_mov_b32_e32 v6, v174
	v_mov_b32_e32 v7, v175
	v_mov_b32_e32 v8, v176
	v_mov_b32_e32 v9, v177
	v_mov_b32_e32 v2, v170
	v_mov_b32_e32 v3, v171
	v_mov_b32_e32 v4, v172
	v_mov_b32_e32 v5, v173
	v_mov_b32_e32 v12, v180
	v_mov_b32_e32 v13, v181
	v_mov_b32_e32 v1, v11
	v_mov_b32_e32 v10, v11
	v_mov_b32_e32 v15, v11
	v_lshl_add_u64 v[14:15], s[0:1], 0, v[14:15]
	v_cmp_eq_u32_e32 vcc, 0, v166
	s_waitcnt vmcnt(5)
	v_pk_add_f32 v[18:19], v[18:19], v[22:23]
	v_pk_add_f32 v[20:21], v[16:17], v[20:21]
	s_waitcnt vmcnt(3)
	v_pk_add_f32 v[16:17], v[26:27], v[30:31]
	v_pk_add_f32 v[22:23], v[24:25], v[28:29]
	v_pk_add_f32 v[16:17], v[18:19], v[16:17]
	v_pk_add_f32 v[18:19], v[20:21], v[22:23]
	v_mul_f32_e32 v21, v17, v17
	v_mul_f32_e32 v20, v19, v19
	v_fmac_f32_e32 v20, v18, v18
	v_fmac_f32_e32 v21, v16, v16
	v_add_f32_e32 v20, v20, v21
	s_nop 1
	v_add_f32_dpp v20, v20, v20 quad_perm:[1,0,3,2] row_mask:0xf bank_mask:0xf bound_ctrl:1
	s_nop 1
	v_add_f32_dpp v20, v20, v20 quad_perm:[2,3,0,1] row_mask:0xf bank_mask:0xf bound_ctrl:1
	s_nop 1
	v_add_f32_dpp v20, v20, v20 row_half_mirror row_mask:0xf bank_mask:0xf bound_ctrl:1
	s_nop 1
	v_add_f32_dpp v20, v20, v20 row_mirror row_mask:0xf bank_mask:0xf bound_ctrl:1
	s_nop 1
	v_mov_b32_dpp v1, v20 row_bcast:15 row_mask:0xa bank_mask:0xf
	v_add_f32_e32 v1, v20, v1
	s_nop 1
	v_mov_b32_dpp v10, v1 row_bcast:31 row_mask:0xc bank_mask:0xf
	v_add_f32_e32 v1, v1, v10
	s_nop 0
	v_readlane_b32 s6, v1, 63
	s_and_saveexec_b64 s[0:1], vcc
	s_lshl_b32 s7, s96, 2
	s_add_i32 s7, s7, 0
	v_mov_b32_e32 v1, s7
	v_mov_b32_e32 v10, s6
	ds_write_b32 v1, v10
	s_or_b64 exec, exec, s[0:1]
	s_waitcnt lgkmcnt(0)
	s_barrier
	ds_read_b128 v[20:23], v11
	ds_read_b128 v[24:27], v11 offset:16
	s_waitcnt vmcnt(2)
	v_pk_mul_f32 v[8:9], v[8:9], v[16:17]
	v_pk_mul_f32 v[6:7], v[6:7], v[18:19]
	s_waitcnt lgkmcnt(1)
	v_add_f32_e32 v1, 0, v20
	v_add_f32_e32 v1, v1, v21
	v_add_f32_e32 v1, v1, v22
	v_add_f32_e32 v1, v1, v23
	s_waitcnt lgkmcnt(0)
	v_add_f32_e32 v1, v1, v24
	v_add_f32_e32 v1, v1, v25
	v_add_f32_e32 v1, v1, v26
	v_add_f32_e32 v10, v1, v27
	v_mov_b32_e32 v1, 0x358637bd
	v_fmamk_f32 v10, v10, 0x3a000000, v1
	v_rsq_f32_e32 v10, v10
	s_waitcnt vmcnt(0)
	v_cvt_f32_f16_sdwa v21, v12 dst_sel:DWORD dst_unused:UNUSED_PAD src0_sel:WORD_1
	v_cvt_f32_f16_e32 v20, v12
	v_cvt_f32_f16_sdwa v23, v13 dst_sel:DWORD dst_unused:UNUSED_PAD src0_sel:WORD_1
	v_cvt_f32_f16_e32 v22, v13
	v_mul_f32_e32 v10, 0.5, v10
	v_pk_fma_f32 v[6:7], v[6:7], v[10:11], v[20:21] op_sel_hi:[1,0,1]
	v_pk_fma_f32 v[8:9], v[8:9], v[10:11], v[22:23] op_sel_hi:[1,0,1]
	v_cvt_f16_f32_e32 v10, v6
	v_cvt_f16_f32_sdwa v12, v7 dst_sel:WORD_1 dst_unused:UNUSED_PAD src0_sel:DWORD
	v_cvt_f16_f32_e32 v13, v8
	v_cvt_f16_f32_sdwa v16, v9 dst_sel:WORD_1 dst_unused:UNUSED_PAD src0_sel:DWORD
	v_or_b32_e32 v12, v12, v10
	v_mul_f32_e32 v10, v7, v7
	v_or_b32_e32 v13, v16, v13
	global_store_dwordx2 v[14:15], v[12:13], off
	v_mul_f32_e32 v12, v9, v9
	v_fmac_f32_e32 v10, v6, v6
	v_fmac_f32_e32 v12, v8, v8
	v_add_f32_e32 v10, v10, v12
	v_mov_b32_e32 v12, 0
	s_nop 0
	v_add_f32_dpp v10, v10, v10 quad_perm:[1,0,3,2] row_mask:0xf bank_mask:0xf bound_ctrl:1
	s_nop 1
	v_add_f32_dpp v10, v10, v10 quad_perm:[2,3,0,1] row_mask:0xf bank_mask:0xf bound_ctrl:1
	s_nop 1
	v_add_f32_dpp v10, v10, v10 row_half_mirror row_mask:0xf bank_mask:0xf bound_ctrl:1
	s_nop 1
	v_add_f32_dpp v10, v10, v10 row_mirror row_mask:0xf bank_mask:0xf bound_ctrl:1
	s_nop 1
	v_mov_b32_dpp v12, v10 row_bcast:15 row_mask:0xa bank_mask:0xf
	v_add_f32_e32 v10, v10, v12
	s_nop 1
	v_mov_b32_dpp v11, v10 row_bcast:31 row_mask:0xc bank_mask:0xf
	v_add_f32_e32 v10, v10, v11
	s_nop 0
	v_readlane_b32 s6, v10, 63
	s_and_saveexec_b64 s[0:1], vcc
	s_lshl_b32 s7, s96, 2
	s_add_i32 s7, s7, 0
	v_mov_b32_e32 v10, s7
	v_mov_b32_e32 v11, s6
	ds_write_b32 v10, v11 offset:32
	s_or_b64 exec, exec, s[0:1]
	v_mov_b32_e32 v10, 0
	s_waitcnt lgkmcnt(0)
	s_barrier
	ds_read_b128 v[12:15], v10 offset:32
	ds_read_b128 v[16:19], v10 offset:48
	v_pk_mul_f32 v[4:5], v[4:5], v[8:9]
	v_pk_mul_f32 v[6:7], v[2:3], v[6:7]
	s_waitcnt lgkmcnt(1)
	v_add_f32_e32 v11, 0, v12
	v_add_f32_e32 v11, v11, v13
	v_add_f32_e32 v11, v11, v14
	v_add_f32_e32 v11, v11, v15
	s_waitcnt lgkmcnt(0)
	v_add_f32_e32 v11, v11, v16
	v_add_f32_e32 v11, v11, v17
	v_add_f32_e32 v11, v11, v18
	v_add_f32_e32 v11, v11, v19
	v_fmac_f32_e32 v1, 0x3a000000, v11
	v_rsq_f32_e32 v12, v1
	s_nop 0
	v_pk_mul_f32 v[2:3], v[4:5], v[12:13] op_sel_hi:[1,0]
	v_pk_mul_f32 v[4:5], v[6:7], v[12:13] op_sel_hi:[1,0]
	v_max_f32_e64 v1, |v2|, |v3|
	v_max3_f32 v1, |v4|, |v5|, v1
	v_mov_b32_e32 v6, 0
	s_nop 1
	v_mov_b32_dpp v6, v1 quad_perm:[1,0,3,2] row_mask:0xf bank_mask:0xf
	v_max_f32_e32 v6, v6, v6
	v_max_f32_e32 v1, v1, v6
	v_mov_b32_e32 v6, 0
	s_nop 1
	v_mov_b32_dpp v6, v1 quad_perm:[2,3,0,1] row_mask:0xf bank_mask:0xf
	v_max_f32_e32 v6, v6, v6
	v_max_f32_e32 v1, v1, v6
	v_mov_b32_e32 v6, 0
	s_nop 1
	v_mov_b32_dpp v6, v1 row_half_mirror row_mask:0xf bank_mask:0xf
	v_max_f32_e32 v6, v6, v6
	v_max_f32_e32 v1, v1, v6
	v_mov_b32_e32 v6, 0
	s_nop 1
	v_mov_b32_dpp v6, v1 row_mirror row_mask:0xf bank_mask:0xf
	v_max_f32_e32 v6, v6, v6
	v_max_f32_e32 v1, v1, v6
	v_mov_b32_e32 v6, 0
	s_nop 1
	v_mov_b32_dpp v6, v1 row_bcast:15 row_mask:0xa bank_mask:0xf
	v_max_f32_e32 v6, v6, v6
	v_max_f32_e32 v1, v1, v6
	v_mov_b32_e32 v6, 0
	s_nop 1
	v_mov_b32_dpp v6, v1 row_bcast:31 row_mask:0xc bank_mask:0xf
	v_max_f32_e32 v6, v6, v6
	v_max_f32_e32 v1, v1, v6
	s_nop 0
	v_readlane_b32 s6, v1, 63
	s_and_saveexec_b64 s[0:1], vcc
	s_lshl_b32 s7, s96, 2
	s_add_i32 s7, s7, 0
	v_mov_b32_e32 v1, s7
	v_mov_b32_e32 v6, s6
	ds_write_b32 v1, v6 offset:64
	s_or_b64 exec, exec, s[0:1]
	s_waitcnt lgkmcnt(0)
	s_barrier
	ds_read_b128 v[6:9], v10 offset:64
	ds_read_b128 v[10:13], v10 offset:80
	s_lshl_b64 s[6:7], s[4:5], 11
	s_waitcnt lgkmcnt(1)
	v_max3_f32 v1, v6, 0, v7
	v_max3_f32 v1, v1, v8, v9
	s_waitcnt lgkmcnt(0)
	v_max3_f32 v1, v1, v10, v11
	v_max3_f32 v1, v1, v12, v13
	v_cmp_lt_f32_e64 s[0:1], 0, v1
	s_mov_b64 s[8:9], exec
	v_readlane_b32 s10, v254, 36
	v_readlane_b32 s11, v254, 37
	s_and_b64 s[10:11], s[8:9], s[10:11]
	s_mov_b64 exec, s[10:11]
	s_cbranch_execz .LBB0_2665
	s_lshl_b64 s[4:5], s[4:5], 2
	v_mul_f32_e32 v6, 0x3c010204, v1
	s_add_u32 s4, s86, s4
	v_cndmask_b32_e64 v6, 1.0, v6, s[0:1]
	s_addc_u32 s5, s87, s5
	v_mov_b32_e32 v7, 0
	global_store_dword v7, v6, s[4:5]

.LBB0_2910:
	s_cmp_lt_i32 s42, 33
	s_cselect_b64 s[0:1], -1, 0
	s_cmp_gt_i32 s43, 32
	s_cselect_b64 s[4:5], -1, 0
	s_and_b64 s[0:1], s[0:1], s[4:5]
	s_andn2_b64 vcc, exec, s[0:1]
	s_cbranch_vccnz .LBB0_2982
	v_readlane_b32 s64, v254, 2
	v_readlane_b32 s78, v254, 16
	v_readlane_b32 s79, v254, 17
	s_mov_b64 s[14:15], s[78:79]
	s_add_u32 s0, s14, 0x26000
	s_addc_u32 s1, s15, 0
	s_add_u32 s4, s14, 0x28000
	s_addc_u32 s5, s15, 0
	s_ashr_i32 s7, s90, 5
	s_abs_i32 s6, s7
	v_cvt_f32_u32_e32 v169, s6
	s_sub_i32 s10, 0, s6
	s_abs_i32 s8, s62
	s_xor_b32 s9, s62, s7
	v_rcp_iflag_f32_e32 v169, v169
	s_ashr_i32 s9, s9, 31
	v_mul_f32_e32 v169, 0x4f7ffffe, v169
	v_cvt_u32_f32_e32 v169, v169
	s_nop 0
	v_readfirstlane_b32 s11, v169
	s_mul_i32 s10, s10, s11
	s_mul_hi_u32 s10, s11, s10
	s_add_i32 s11, s11, s10
	s_mul_hi_u32 s10, s8, s11
	s_mul_i32 s11, s10, s6
	s_sub_i32 s8, s8, s11
	s_add_i32 s12, s10, 1
	s_sub_i32 s11, s8, s6
	s_cmp_ge_u32 s8, s6
	s_cselect_b32 s10, s12, s10
	s_cselect_b32 s8, s11, s8
	s_add_i32 s11, s10, 1
	s_cmp_ge_u32 s8, s6
	s_cselect_b32 s6, s11, s10
	s_xor_b32 s6, s6, s9
	s_sub_i32 s6, s6, s9
	s_mul_i32 s7, s6, s7
	s_sub_i32 s7, s62, s7
	s_cmp_lg_u32 s7, 0
	s_ashr_i32 s7, s6, 31
	s_lshl_b64 s[8:9], s[6:7], 13
	v_readlane_b32 s10, v254, 58
	v_readlane_b32 s11, v254, 59
	s_add_u32 s8, s10, s8
	s_addc_u32 s9, s11, s9
	v_mov_b32_e32 v181, 0
	v_lshlrev_b32_e32 v180, 4, v0
	v_lshl_add_u64 v[170:171], s[8:9], 0, v[180:181]
	v_add_co_u32_e32 v172, vcc, 0x40000, v170
	global_load_dwordx4 v[186:189], v180, s[8:9]
	s_nop 0
	v_addc_co_u32_e32 v173, vcc, 0, v171, vcc
	v_add_co_u32_e32 v174, vcc, 0x80000, v170
	s_addk_i32 s6, 0x2000
	s_nop 0
	v_addc_co_u32_e32 v175, vcc, 0, v171, vcc
	v_add_co_u32_e32 v170, vcc, 0xc0000, v170
	global_load_dwordx4 v[190:193], v[172:173], off
	global_load_dwordx4 v[194:197], v[174:175], off
	v_addc_co_u32_e32 v171, vcc, 0, v171, vcc
	global_load_dwordx4 v[198:201], v[170:171], off
	s_ashr_i32 s7, s6, 31
	s_lshl_b64 s[8:9], s[6:7], 12
	v_readlane_b32 s10, v254, 54
	v_readlane_b32 s11, v254, 55
	s_add_u32 s8, s10, s8
	s_addc_u32 s9, s11, s9
	v_lshlrev_b32_e32 v178, 3, v0
	global_load_dwordx4 v[174:177], v180, s[0:1]
	global_load_dwordx4 v[170:173], v180, s[4:5]
	global_load_dwordx2 v[182:183], v178, s[8:9]
	s_lshl_b32 s7, s62, 3
	s_add_i32 s6, s7, s96
	s_and_b32 s7, s7, 0xf8
	s_lshl_b32 s8, s62, 5
	s_add_i32 s7, s7, s96
	s_and_b32 s8, s8, 0xfffffc00
	s_add_i32 s7, s7, s8
	s_add_i32 s12, s7, 0x400
	s_cmpk_eq_i32 s90, 0x100
	s_cselect_b64 s[10:11], -1, 0
	s_and_b64 s[8:9], s[10:11], exec
	s_cselect_b32 s8, s7, s6
	s_cselect_b32 s7, s12, 0x2000
	s_cmp_ge_i32 s8, s7
	v_readlane_b32 s65, v254, 3
	v_readlane_b32 s66, v254, 4
	v_readlane_b32 s67, v254, 5
	v_readlane_b32 s68, v254, 6
	v_readlane_b32 s69, v254, 7
	v_readlane_b32 s70, v254, 8
	v_readlane_b32 s71, v254, 9
	v_readlane_b32 s72, v254, 10
	v_readlane_b32 s73, v254, 11
	v_readlane_b32 s74, v254, 12
	v_readlane_b32 s75, v254, 13
	v_readlane_b32 s76, v254, 14
	v_readlane_b32 s77, v254, 15
	s_cbranch_scc1 .LBB0_2916
	s_lshl_b32 s9, s90, 3
	v_lshlrev_b32_e32 v1, 5, v166
	s_and_b64 s[10:11], s[10:11], exec
	v_or_b32_e32 v46, 0x800, v1
	v_or_b32_e32 v54, 0x1000, v1
	v_or_b32_e32 v62, 0x1800, v1
	s_cselect_b32 s10, 0x100, s9
	s_ashr_i32 s9, s8, 31
	global_load_dwordx4 v[2:5], v1, s[0:1] offset:16
	global_load_dwordx4 v[6:9], v1, s[0:1]
	global_load_dwordx4 v[10:13], v46, s[0:1] offset:16
	global_load_dwordx4 v[14:17], v46, s[0:1]
	global_load_dwordx4 v[18:21], v54, s[0:1] offset:16
	global_load_dwordx4 v[22:25], v54, s[0:1]
	global_load_dwordx4 v[26:29], v62, s[0:1] offset:16
	global_load_dwordx4 v[30:33], v62, s[0:1]
	global_load_dwordx4 v[34:37], v1, s[4:5] offset:16
	global_load_dwordx4 v[38:41], v1, s[4:5]
	global_load_dwordx4 v[42:45], v46, s[4:5] offset:16
	s_nop 0
	global_load_dwordx4 v[46:49], v46, s[4:5]
	s_nop 0
	global_load_dwordx4 v[50:53], v54, s[4:5] offset:16
	s_nop 0
	global_load_dwordx4 v[54:57], v54, s[4:5]
	s_lshl_b64 s[12:13], s[8:9], 12
	v_readlane_b32 s14, v254, 54
	v_readlane_b32 s15, v254, 55
	s_add_u32 s14, s14, s12
	s_addc_u32 s15, s15, s13
	s_add_u32 s16, s80, s12
	v_lshlrev_b32_e32 v130, 4, v166
	s_addc_u32 s17, s81, s13
	global_load_dwordx4 v[110:113], v130, s[14:15]
	global_load_dwordx4 v[106:109], v130, s[14:15] offset:1024
	global_load_dwordx4 v[102:105], v130, s[14:15] offset:2048
	global_load_dwordx4 v[126:129], v130, s[16:17]
	global_load_dwordx4 v[122:125], v130, s[16:17] offset:1024
	global_load_dwordx4 v[98:101], v130, s[14:15] offset:3072
	global_load_dwordx4 v[118:121], v130, s[16:17] offset:2048
	global_load_dwordx4 v[114:117], v130, s[16:17] offset:3072
	global_load_dwordx4 v[58:61], v62, s[4:5] offset:16
	s_nop 0
	global_load_dwordx4 v[62:65], v62, s[4:5]
	s_add_u32 s12, s94, s12
	s_addc_u32 s13, s95, s13
	s_add_i32 s16, s8, s10
	s_ashr_i32 s11, s10, 31
	s_ashr_i32 s17, s16, 31
	s_lshl_b64 s[14:15], s[10:11], 12
	s_lshl_b64 s[16:17], s[16:17], 12
	s_add_u32 s16, s94, s16
	v_mov_b32_e32 v131, 0
	s_mov_b32 s9, 0x2f1e0000
	s_mov_b32 s22, 0x2f1e1000
	v_mov_b32_e32 v1, 0x358637bd
	s_mov_b32 s23, 0x1b500000
	v_mov_b32_e32 v132, 0x3a000000
	s_addc_u32 s17, s95, s17
	s_waitcnt vmcnt(9)
	v_mov_b64_e32 v[66:67], v[110:111]
	s_waitcnt vmcnt(8)
	v_mov_b64_e32 v[70:71], v[106:107]
	s_waitcnt vmcnt(7)
	v_mov_b64_e32 v[78:79], v[102:103]
	s_waitcnt vmcnt(6)
	v_mov_b64_e32 v[74:75], v[126:127]
	s_waitcnt vmcnt(5)
	v_mov_b64_e32 v[82:83], v[122:123]
	s_waitcnt vmcnt(4)
	v_mov_b64_e32 v[94:95], v[98:99]
	s_waitcnt vmcnt(3)
	v_mov_b64_e32 v[86:87], v[118:119]
	s_waitcnt vmcnt(2)
	v_mov_b64_e32 v[90:91], v[114:115]
	v_mov_b64_e32 v[68:69], v[112:113]
	v_mov_b64_e32 v[72:73], v[108:109]
	v_mov_b64_e32 v[80:81], v[104:105]
	v_mov_b64_e32 v[76:77], v[128:129]
	v_mov_b64_e32 v[84:85], v[124:125]
	v_mov_b64_e32 v[88:89], v[120:121]
	v_mov_b64_e32 v[92:93], v[116:117]
	v_mov_b64_e32 v[96:97], v[100:101]
	s_branch .LBB0_2914

.LBB0_2922:
	s_cbranch_execz .LBB0_2929
	s_ashr_i32 s7, s90, 5
	s_abs_i32 s6, s7
	v_cvt_f32_u32_e32 v1, s6
	s_sub_i32 s10, 0, s6
	s_abs_i32 s8, s62
	s_xor_b32 s9, s62, s7
	v_rcp_iflag_f32_e32 v1, v1
	s_ashr_i32 s9, s9, 31
	v_mul_f32_e32 v1, 0x4f7ffffe, v1
	v_cvt_u32_f32_e32 v1, v1
	s_nop 0
	v_readfirstlane_b32 s11, v1
	s_mul_i32 s10, s10, s11
	s_mul_hi_u32 s10, s11, s10
	s_add_i32 s11, s11, s10
	s_mul_hi_u32 s10, s8, s11
	s_mul_i32 s11, s10, s6
	s_sub_i32 s8, s8, s11
	s_add_i32 s12, s10, 1
	s_sub_i32 s11, s8, s6
	s_cmp_ge_u32 s8, s6
	s_cselect_b32 s10, s12, s10
	s_cselect_b32 s8, s11, s8
	s_add_i32 s11, s10, 1
	s_cmp_ge_u32 s8, s6
	s_cselect_b32 s6, s11, s10
	s_xor_b32 s6, s6, s9
	s_sub_i32 s6, s6, s9
	s_mul_i32 s7, s6, s7
	s_sub_i32 s7, s62, s7
	s_cmp_lg_u32 s7, 0
	s_cbranch_scc1 .LBB0_2929
	s_ashr_i32 s7, s6, 31
	s_lshl_b64 s[8:9], s[6:7], 13
	v_readlane_b32 s10, v254, 58
	v_readlane_b32 s11, v254, 59
	s_add_u32 s8, s10, s8
	s_addc_u32 s9, s11, s9
	v_mov_b32_e32 v13, 0
	v_lshlrev_b32_e32 v12, 4, v0
	v_lshl_add_u64 v[2:3], s[8:9], 0, v[12:13]
	v_add_co_u32_e32 v4, vcc, 0x40000, v2
	s_waitcnt vmcnt(0)
	v_mov_b32_e32 v18, v186
	v_mov_b32_e32 v19, v187
	v_mov_b32_e32 v20, v188
	v_mov_b32_e32 v21, v189
	s_nop 0
	v_addc_co_u32_e32 v5, vcc, 0, v3, vcc
	v_add_co_u32_e32 v6, vcc, 0x80000, v2
	s_addk_i32 s6, 0x2000
	s_nop 0
	v_addc_co_u32_e32 v7, vcc, 0, v3, vcc
	v_add_co_u32_e32 v2, vcc, 0xc0000, v2
	v_mov_b32_e32 v22, v190
	v_mov_b32_e32 v23, v191
	v_mov_b32_e32 v24, v192
	v_mov_b32_e32 v25, v193
	v_mov_b32_e32 v26, v194
	v_mov_b32_e32 v27, v195
	v_mov_b32_e32 v28, v196
	v_mov_b32_e32 v29, v197
	v_addc_co_u32_e32 v3, vcc, 0, v3, vcc
	v_mov_b32_e32 v30, v198
	v_mov_b32_e32 v31, v199
	v_mov_b32_e32 v32, v200
	v_mov_b32_e32 v33, v201
	s_ashr_i32 s7, s6, 31
	s_lshl_b64 s[8:9], s[6:7], 12
	v_readlane_b32 s10, v254, 54
	v_readlane_b32 s11, v254, 55
	s_add_u32 s8, s10, s8
	s_addc_u32 s9, s11, s9
	v_lshlrev_b32_e32 v10, 3, v0
	v_mov_b32_e32 v6, v174
	v_mov_b32_e32 v7, v175
	v_mov_b32_e32 v8, v176
	v_mov_b32_e32 v9, v177
	v_mov_b32_e32 v2, v170
	v_mov_b32_e32 v3, v171
	v_mov_b32_e32 v4, v172
	v_mov_b32_e32 v5, v173
	v_mov_b32_e32 v14, v182
	v_mov_b32_e32 v15, v183
	v_mov_b32_e32 v11, v13
	v_lshl_add_u64 v[16:17], s[8:9], 0, v[10:11]
	v_mov_b32_e32 v1, v13
	v_mov_b32_e32 v12, v13
	v_cmp_eq_u32_e32 vcc, 0, v166
	s_waitcnt vmcnt(5)
	v_pk_add_f32 v[20:21], v[20:21], v[24:25]
	v_pk_add_f32 v[22:23], v[18:19], v[22:23]
	s_waitcnt vmcnt(3)
	v_pk_add_f32 v[18:19], v[28:29], v[32:33]
	v_pk_add_f32 v[24:25], v[26:27], v[30:31]
	v_pk_add_f32 v[18:19], v[20:21], v[18:19]
	v_pk_add_f32 v[20:21], v[22:23], v[24:25]
	v_mul_f32_e32 v22, v19, v19
	v_mul_f32_e32 v11, v21, v21
	v_fmac_f32_e32 v11, v20, v20
	v_fmac_f32_e32 v22, v18, v18
	v_add_f32_e32 v11, v11, v22
	s_nop 1
	v_add_f32_dpp v11, v11, v11 quad_perm:[1,0,3,2] row_mask:0xf bank_mask:0xf bound_ctrl:1
	s_nop 1
	v_add_f32_dpp v11, v11, v11 quad_perm:[2,3,0,1] row_mask:0xf bank_mask:0xf bound_ctrl:1
	s_nop 1
	v_add_f32_dpp v11, v11, v11 row_half_mirror row_mask:0xf bank_mask:0xf bound_ctrl:1
	s_nop 1
	v_add_f32_dpp v11, v11, v11 row_mirror row_mask:0xf bank_mask:0xf bound_ctrl:1
	s_nop 1
	v_mov_b32_dpp v1, v11 row_bcast:15 row_mask:0xa bank_mask:0xf
	v_add_f32_e32 v1, v11, v1
	s_nop 1
	v_mov_b32_dpp v12, v1 row_bcast:31 row_mask:0xc bank_mask:0xf
	v_add_f32_e32 v1, v1, v12
	s_nop 0
	v_readlane_b32 s4, v1, 63
	s_and_saveexec_b64 s[0:1], vcc
	s_lshl_b32 s5, s96, 2
	s_add_i32 s5, s5, 0
	v_mov_b32_e32 v1, s5
	v_mov_b32_e32 v11, s4
	ds_write_b32 v1, v11
	s_or_b64 exec, exec, s[0:1]
	s_waitcnt lgkmcnt(0)
	s_barrier
	ds_read_b128 v[22:25], v13
	ds_read_b128 v[26:29], v13 offset:16
	s_waitcnt vmcnt(2)
	v_pk_mul_f32 v[6:7], v[6:7], v[20:21]
	v_pk_mul_f32 v[8:9], v[8:9], v[18:19]
	s_lshl_b64 s[0:1], s[6:7], 11
	s_waitcnt lgkmcnt(1)
	v_add_f32_e32 v1, 0, v22
	v_add_f32_e32 v1, v1, v23
	v_add_f32_e32 v1, v1, v24
	v_add_f32_e32 v1, v1, v25
	s_waitcnt lgkmcnt(0)
	v_add_f32_e32 v1, v1, v26
	v_add_f32_e32 v1, v1, v27
	v_add_f32_e32 v1, v1, v28
	v_add_f32_e32 v11, v1, v29
	v_mov_b32_e32 v1, 0x358637bd
	v_fmamk_f32 v11, v11, 0x3a000000, v1
	v_rsq_f32_e32 v11, v11
	s_waitcnt vmcnt(0)
	v_cvt_f32_f16_sdwa v23, v14 dst_sel:DWORD dst_unused:UNUSED_PAD src0_sel:WORD_1
	v_cvt_f32_f16_e32 v22, v14
	v_cvt_f32_f16_sdwa v25, v15 dst_sel:DWORD dst_unused:UNUSED_PAD src0_sel:WORD_1
	v_cvt_f32_f16_e32 v24, v15
	v_mul_f32_e32 v12, 0.5, v11
	v_pk_fma_f32 v[6:7], v[6:7], v[12:13], v[22:23] op_sel_hi:[1,0,1]
	v_pk_fma_f32 v[8:9], v[8:9], v[12:13], v[24:25] op_sel_hi:[1,0,1]
	v_cvt_f16_f32_e32 v11, v6
	v_cvt_f16_f32_sdwa v12, v7 dst_sel:WORD_1 dst_unused:UNUSED_PAD src0_sel:DWORD
	v_cvt_f16_f32_e32 v15, v8
	v_cvt_f16_f32_sdwa v18, v9 dst_sel:WORD_1 dst_unused:UNUSED_PAD src0_sel:DWORD
	v_or_b32_e32 v14, v12, v11
	v_mul_f32_e32 v11, v7, v7
	v_mul_f32_e32 v12, v9, v9
	v_fmac_f32_e32 v11, v6, v6
	v_fmac_f32_e32 v12, v8, v8
	v_add_f32_e32 v11, v11, v12
	v_mov_b32_e32 v12, 0
	v_or_b32_e32 v15, v18, v15
	v_add_f32_dpp v11, v11, v11 quad_perm:[1,0,3,2] row_mask:0xf bank_mask:0xf bound_ctrl:1
	global_store_dwordx2 v[16:17], v[14:15], off
	s_nop 0
	v_add_f32_dpp v11, v11, v11 quad_perm:[2,3,0,1] row_mask:0xf bank_mask:0xf bound_ctrl:1
	s_nop 1
	v_add_f32_dpp v11, v11, v11 row_half_mirror row_mask:0xf bank_mask:0xf bound_ctrl:1
	s_nop 1
	v_add_f32_dpp v11, v11, v11 row_mirror row_mask:0xf bank_mask:0xf bound_ctrl:1
	s_nop 1
	v_mov_b32_dpp v12, v11 row_bcast:15 row_mask:0xa bank_mask:0xf
	v_add_f32_e32 v11, v11, v12
	s_nop 1
	v_mov_b32_dpp v13, v11 row_bcast:31 row_mask:0xc bank_mask:0xf
	v_add_f32_e32 v11, v11, v13
	s_nop 0
	v_readlane_b32 s6, v11, 63
	s_and_saveexec_b64 s[4:5], vcc
	s_lshl_b32 s7, s96, 2
	s_add_i32 s7, s7, 0
	v_mov_b32_e32 v11, s7
	v_mov_b32_e32 v12, s6
	ds_write_b32 v11, v12 offset:32
	s_or_b64 exec, exec, s[4:5]
	v_mov_b32_e32 v11, 0
	s_waitcnt lgkmcnt(0)
	s_barrier
	ds_read_b128 v[12:15], v11 offset:32
	ds_read_b128 v[16:19], v11 offset:48
	s_lshl_b64 s[0:1], s[0:1], 1
	v_readlane_b32 s4, v254, 60
	v_pk_mul_f32 v[2:3], v[2:3], v[6:7]
	s_waitcnt lgkmcnt(1)
	v_add_f32_e32 v11, 0, v12
	v_add_f32_e32 v11, v11, v13
	v_add_f32_e32 v11, v11, v14
	v_add_f32_e32 v11, v11, v15
	s_waitcnt lgkmcnt(0)
	v_add_f32_e32 v11, v11, v16
	v_add_f32_e32 v11, v11, v17
	v_add_f32_e32 v11, v11, v18
	v_add_f32_e32 v11, v11, v19
	v_fmac_f32_e32 v1, 0x3a000000, v11
	v_rsq_f32_e32 v12, v1
	v_readlane_b32 s5, v254, 61
	s_add_u32 s0, s4, s0
	v_pk_mul_f32 v[4:5], v[4:5], v[8:9]
	v_pk_mul_f32 v[2:3], v[2:3], v[12:13] op_sel_hi:[1,0]
	s_addc_u32 s1, s5, s1
	v_pk_mul_f32 v[4:5], v[4:5], v[12:13] op_sel_hi:[1,0]
	v_cvt_pk_bf16_f32 v2, v2, v3
	s_nop 0
	v_cvt_pk_bf16_f32 v3, v4, v5
	global_store_dwordx2 v10, v[2:3], s[0:1]
	s_barrier

.LBB0_3285:
	s_cmp_lt_i32 s42, 38
	s_cselect_b64 s[0:1], -1, 0
	s_cmp_gt_i32 s43, 37
	s_cselect_b64 s[4:5], -1, 0
	s_and_b64 s[0:1], s[0:1], s[4:5]
	s_andn2_b64 vcc, exec, s[0:1]
	s_cbranch_vccnz .LBB0_3365
	v_readlane_b32 s4, v254, 2
	v_readlane_b32 s14, v254, 12
	v_readlane_b32 s15, v254, 13
	v_readlane_b32 s18, v254, 16
	v_readlane_b32 s19, v254, 17
	v_readlane_b32 s6, v254, 4
	s_mov_b64 s[14:15], s[18:19]
	v_readlane_b32 s7, v254, 5
	s_add_u32 s6, s14, 0x2a000
	v_readlane_b32 s8, v254, 6
	s_addc_u32 s7, s15, 0
	v_readlane_b32 s9, v254, 7
	s_add_u32 s8, s14, 0x2c000
	v_readlane_b32 s10, v254, 8
	s_addc_u32 s9, s15, 0
	s_ashr_i32 s1, s90, 5
	s_abs_i32 s0, s1
	v_cvt_f32_u32_e32 v169, s0
	s_sub_i32 s10, 0, s0
	s_abs_i32 s4, s62
	s_xor_b32 s5, s62, s1
	v_rcp_iflag_f32_e32 v169, v169
	s_ashr_i32 s5, s5, 31
	v_mul_f32_e32 v169, 0x4f7ffffe, v169
	v_cvt_u32_f32_e32 v169, v169
	s_nop 0
	v_readfirstlane_b32 s11, v169
	s_mul_i32 s10, s10, s11
	s_mul_hi_u32 s10, s11, s10
	s_add_i32 s11, s11, s10
	s_mul_hi_u32 s10, s4, s11
	s_mul_i32 s11, s10, s0
	s_sub_i32 s4, s4, s11
	s_add_i32 s12, s10, 1
	s_sub_i32 s11, s4, s0
	s_cmp_ge_u32 s4, s0
	s_cselect_b32 s10, s12, s10
	s_cselect_b32 s4, s11, s4
	s_add_i32 s11, s10, 1
	s_cmp_ge_u32 s4, s0
	s_cselect_b32 s0, s11, s10
	s_xor_b32 s0, s0, s5
	s_sub_i32 s0, s0, s5
	s_mul_i32 s1, s0, s1
	s_sub_i32 s1, s62, s1
	s_cmp_lg_u32 s1, 0
	s_ashr_i32 s1, s0, 31
	s_lshl_b64 s[4:5], s[0:1], 13
	v_readlane_b32 s10, v254, 58
	v_readlane_b32 s11, v254, 59
	s_add_u32 s4, s10, s4
	s_addc_u32 s5, s11, s5
	v_mov_b32_e32 v179, 0
	v_lshlrev_b32_e32 v178, 4, v0
	v_lshl_add_u64 v[170:171], s[4:5], 0, v[178:179]
	v_add_co_u32_e32 v172, vcc, 0x40000, v170
	global_load_dwordx4 v[184:187], v178, s[4:5]
	s_nop 0
	v_addc_co_u32_e32 v173, vcc, 0, v171, vcc
	v_add_co_u32_e32 v174, vcc, 0x80000, v170
	s_add_i32 s4, s0, 0x2000
	s_nop 0
	v_addc_co_u32_e32 v175, vcc, 0, v171, vcc
	v_add_co_u32_e32 v170, vcc, 0xc0000, v170
	global_load_dwordx4 v[188:191], v[172:173], off
	global_load_dwordx4 v[192:195], v[174:175], off
	v_addc_co_u32_e32 v171, vcc, 0, v171, vcc
	global_load_dwordx4 v[196:199], v[170:171], off
	s_ashr_i32 s5, s4, 31
	s_lshl_b64 s[0:1], s[4:5], 12
	v_readlane_b32 s10, v254, 54
	v_readlane_b32 s11, v254, 55
	s_add_u32 s0, s10, s0
	s_addc_u32 s1, s11, s1
	v_lshlrev_b32_e32 v182, 3, v0
	global_load_dwordx4 v[174:177], v178, s[6:7]
	global_load_dwordx4 v[170:173], v178, s[8:9]
	global_load_dwordx2 v[180:181], v182, s[0:1]
	s_lshl_b32 s0, s62, 3
	s_add_i32 s10, s0, s96
	s_and_b32 s0, s0, 0xf8
	s_lshl_b32 s1, s62, 5
	v_readlane_b32 s11, v254, 9
	s_add_i32 s0, s0, s96
	s_and_b32 s1, s1, 0xfffffc00
	v_readlane_b32 s13, v254, 11
	s_add_i32 s11, s0, s1
	s_add_i32 s13, s11, 0x400
	s_cmpk_eq_i32 s90, 0x100
	v_readlane_b32 s5, v254, 3
	s_cselect_b64 s[0:1], -1, 0
	v_readlane_b32 s12, v254, 10
	s_and_b64 s[4:5], s[0:1], exec
	s_cselect_b32 s12, s11, s10
	s_cselect_b32 s11, s13, 0x2000
	s_cmp_ge_i32 s12, s11
	v_readlane_b32 s16, v254, 14
	v_readlane_b32 s17, v254, 15
	s_cbranch_scc1 .LBB0_3293
	s_lshl_b32 s4, s90, 3
	v_lshlrev_b32_e32 v1, 5, v166
	s_and_b64 s[0:1], s[0:1], exec
	v_or_b32_e32 v58, 0x800, v1
	v_or_b32_e32 v59, 0x1000, v1
	v_or_b32_e32 v66, 0x1800, v1
	s_cselect_b32 s14, 0x100, s4
	s_ashr_i32 s13, s12, 31
	global_load_dwordx4 v[2:5], v1, s[6:7] offset:16
	global_load_dwordx4 v[6:9], v1, s[6:7]
	global_load_dwordx4 v[10:13], v58, s[6:7] offset:16
	global_load_dwordx4 v[14:17], v58, s[6:7]
	global_load_dwordx4 v[18:21], v59, s[6:7] offset:16
	global_load_dwordx4 v[22:25], v59, s[6:7]
	global_load_dwordx4 v[26:29], v66, s[6:7] offset:16
	global_load_dwordx4 v[30:33], v66, s[6:7]
	global_load_dwordx4 v[34:37], v1, s[8:9] offset:16
	global_load_dwordx4 v[38:41], v1, s[8:9]
	global_load_dwordx4 v[42:45], v58, s[8:9] offset:16
	global_load_dwordx4 v[46:49], v58, s[8:9]
	global_load_dwordx4 v[50:53], v59, s[8:9] offset:16
	global_load_dwordx4 v[54:57], v59, s[8:9]
	s_lshl_b64 s[4:5], s[12:13], 11
	s_lshl_b64 s[16:17], s[12:13], 12
	v_readlane_b32 s0, v254, 54
	v_readlane_b32 s1, v254, 55
	s_add_u32 s0, s0, s16
	s_addc_u32 s1, s1, s17
	s_add_u32 s18, s80, s16
	v_lshlrev_b32_e32 v67, 4, v166
	s_addc_u32 s19, s81, s17
	global_load_dwordx4 v[110:113], v67, s[0:1]
	global_load_dwordx4 v[106:109], v67, s[0:1] offset:1024
	global_load_dwordx4 v[102:105], v67, s[0:1] offset:2048
	global_load_dwordx4 v[126:129], v67, s[18:19]
	global_load_dwordx4 v[122:125], v67, s[18:19] offset:1024
	global_load_dwordx4 v[98:101], v67, s[0:1] offset:3072
	global_load_dwordx4 v[118:121], v67, s[18:19] offset:2048
	global_load_dwordx4 v[114:117], v67, s[18:19] offset:3072
	global_load_dwordx4 v[58:61], v66, s[8:9] offset:16
	global_load_dwordx4 v[62:65], v66, s[8:9]
	v_lshl_or_b32 v130, v166, 3, s4
	v_mov_b32_e32 v131, s5
	s_lshl_b64 s[4:5], s[12:13], 2
	s_add_u32 s13, s4, 0x2ee80000
	s_addc_u32 s35, s5, 0
	s_add_i32 s4, s12, s14
	s_ashr_i32 s5, s4, 31
	s_lshl_b64 s[4:5], s[4:5], 12
	v_or_b32_e32 v132, s16, v67
	s_ashr_i32 s15, s14, 31
	v_or_b32_e32 v134, s4, v67
	v_cmp_eq_u32_e64 s[0:1], 0, v166
	s_mov_b32 s26, 0x2f1e0000
	s_mov_b32 s27, 0x2f1e1000
	v_mov_b32_e32 v1, 0
	v_mov_b32_e32 v136, 0x358637bd
	s_mov_b32 s28, 0x42fe0000
	s_mov_b32 s29, 0xc0c0400
	s_mov_b32 s30, 0xc040100
	s_mov_b32 s31, 0x4020100
	s_mov_b32 s34, 0x2de00000
	v_mov_b32_e32 v137, 0x3a000000
	v_mov_b32_e32 v138, 0x3c010204
	v_mov_b32_e32 v139, 0x42fe0000
	v_mov_b32_e32 v133, s17
	s_lshl_b64 s[16:17], s[14:15], 2
	s_lshl_b64 s[18:19], s[14:15], 11
	s_lshl_b64 s[20:21], s[14:15], 12
	v_mov_b32_e32 v135, s5
	s_waitcnt vmcnt(9)
	v_mov_b64_e32 v[66:67], v[110:111]
	s_waitcnt vmcnt(8)
	v_mov_b64_e32 v[70:71], v[106:107]
	s_waitcnt vmcnt(7)
	v_mov_b64_e32 v[78:79], v[102:103]
	s_waitcnt vmcnt(6)
	v_mov_b64_e32 v[74:75], v[126:127]
	s_waitcnt vmcnt(5)
	v_mov_b64_e32 v[82:83], v[122:123]
	s_waitcnt vmcnt(4)
	v_mov_b64_e32 v[94:95], v[98:99]
	s_waitcnt vmcnt(3)
	v_mov_b64_e32 v[86:87], v[118:119]
	s_waitcnt vmcnt(2)
	v_mov_b64_e32 v[90:91], v[114:115]
	v_mov_b64_e32 v[68:69], v[112:113]
	v_mov_b64_e32 v[72:73], v[108:109]
	v_mov_b64_e32 v[80:81], v[104:105]
	v_mov_b64_e32 v[76:77], v[128:129]
	v_mov_b64_e32 v[84:85], v[124:125]
	v_mov_b64_e32 v[88:89], v[120:121]
	v_mov_b64_e32 v[92:93], v[116:117]
	v_mov_b64_e32 v[96:97], v[100:101]
	s_branch .LBB0_3289

.LBB0_3301:
	s_cbranch_execz .LBB0_3312
	s_ashr_i32 s1, s90, 5
	s_abs_i32 s0, s1
	v_cvt_f32_u32_e32 v1, s0
	s_sub_i32 s10, 0, s0
	s_abs_i32 s4, s62
	s_xor_b32 s5, s62, s1
	v_rcp_iflag_f32_e32 v1, v1
	s_ashr_i32 s5, s5, 31
	v_mul_f32_e32 v1, 0x4f7ffffe, v1
	v_cvt_u32_f32_e32 v1, v1
	s_nop 0
	v_readfirstlane_b32 s11, v1
	s_mul_i32 s10, s10, s11
	s_mul_hi_u32 s10, s11, s10
	s_add_i32 s11, s11, s10
	s_mul_hi_u32 s10, s4, s11
	s_mul_i32 s11, s10, s0
	s_sub_i32 s4, s4, s11
	s_add_i32 s12, s10, 1
	s_sub_i32 s11, s4, s0
	s_cmp_ge_u32 s4, s0
	s_cselect_b32 s10, s12, s10
	s_cselect_b32 s4, s11, s4
	s_add_i32 s11, s10, 1
	s_cmp_ge_u32 s4, s0
	s_cselect_b32 s0, s11, s10
	s_xor_b32 s0, s0, s5
	s_sub_i32 s0, s0, s5
	s_mul_i32 s1, s0, s1
	s_sub_i32 s1, s62, s1
	s_cmp_lg_u32 s1, 0
	s_cbranch_scc1 .LBB0_3312
	s_ashr_i32 s1, s0, 31
	s_lshl_b64 s[4:5], s[0:1], 13
	v_readlane_b32 s10, v254, 58
	v_readlane_b32 s11, v254, 59
	s_add_u32 s4, s10, s4
	s_addc_u32 s5, s11, s5
	v_mov_b32_e32 v11, 0
	v_lshlrev_b32_e32 v10, 4, v0
	v_lshl_add_u64 v[2:3], s[4:5], 0, v[10:11]
	v_add_co_u32_e32 v4, vcc, 0x40000, v2
	s_waitcnt vmcnt(0)
	v_mov_b32_e32 v16, v184
	v_mov_b32_e32 v17, v185
	v_mov_b32_e32 v18, v186
	v_mov_b32_e32 v19, v187
	s_nop 0
	v_addc_co_u32_e32 v5, vcc, 0, v3, vcc
	v_add_co_u32_e32 v6, vcc, 0x80000, v2
	s_add_i32 s4, s0, 0x2000
	s_nop 0
	v_addc_co_u32_e32 v7, vcc, 0, v3, vcc
	v_add_co_u32_e32 v2, vcc, 0xc0000, v2
	v_mov_b32_e32 v20, v188
	v_mov_b32_e32 v21, v189
	v_mov_b32_e32 v22, v190
	v_mov_b32_e32 v23, v191
	v_mov_b32_e32 v24, v192
	v_mov_b32_e32 v25, v193
	v_mov_b32_e32 v26, v194
	v_mov_b32_e32 v27, v195
	v_addc_co_u32_e32 v3, vcc, 0, v3, vcc
	v_mov_b32_e32 v28, v196
	v_mov_b32_e32 v29, v197
	v_mov_b32_e32 v30, v198
	v_mov_b32_e32 v31, v199
	s_ashr_i32 s5, s4, 31
	s_lshl_b64 s[0:1], s[4:5], 12
	v_readlane_b32 s10, v254, 54
	v_readlane_b32 s11, v254, 55
	s_add_u32 s0, s10, s0
	s_addc_u32 s1, s11, s1
	v_lshlrev_b32_e32 v14, 3, v0
	v_mov_b32_e32 v6, v174
	v_mov_b32_e32 v7, v175
	v_mov_b32_e32 v8, v176
	v_mov_b32_e32 v9, v177
	v_mov_b32_e32 v2, v170
	v_mov_b32_e32 v3, v171
	v_mov_b32_e32 v4, v172
	v_mov_b32_e32 v5, v173
	v_mov_b32_e32 v12, v180
	v_mov_b32_e32 v13, v181
	v_mov_b32_e32 v1, v11
	v_mov_b32_e32 v10, v11
	v_mov_b32_e32 v15, v11
	v_lshl_add_u64 v[14:15], s[0:1], 0, v[14:15]
	v_cmp_eq_u32_e32 vcc, 0, v166
	s_waitcnt vmcnt(5)
	v_pk_add_f32 v[18:19], v[18:19], v[22:23]
	v_pk_add_f32 v[20:21], v[16:17], v[20:21]
	s_waitcnt vmcnt(3)
	v_pk_add_f32 v[16:17], v[26:27], v[30:31]
	v_pk_add_f32 v[22:23], v[24:25], v[28:29]
	v_pk_add_f32 v[16:17], v[18:19], v[16:17]
	v_pk_add_f32 v[18:19], v[20:21], v[22:23]
	v_mul_f32_e32 v21, v17, v17
	v_mul_f32_e32 v20, v19, v19
	v_fmac_f32_e32 v20, v18, v18
	v_fmac_f32_e32 v21, v16, v16
	v_add_f32_e32 v20, v20, v21
	s_nop 1
	v_add_f32_dpp v20, v20, v20 quad_perm:[1,0,3,2] row_mask:0xf bank_mask:0xf bound_ctrl:1
	s_nop 1
	v_add_f32_dpp v20, v20, v20 quad_perm:[2,3,0,1] row_mask:0xf bank_mask:0xf bound_ctrl:1
	s_nop 1
	v_add_f32_dpp v20, v20, v20 row_half_mirror row_mask:0xf bank_mask:0xf bound_ctrl:1
	s_nop 1
	v_add_f32_dpp v20, v20, v20 row_mirror row_mask:0xf bank_mask:0xf bound_ctrl:1
	s_nop 1
	v_mov_b32_dpp v1, v20 row_bcast:15 row_mask:0xa bank_mask:0xf
	v_add_f32_e32 v1, v20, v1
	s_nop 1
	v_mov_b32_dpp v10, v1 row_bcast:31 row_mask:0xc bank_mask:0xf
	v_add_f32_e32 v1, v1, v10
	s_nop 0
	v_readlane_b32 s6, v1, 63
	s_and_saveexec_b64 s[0:1], vcc
	s_lshl_b32 s7, s96, 2
	s_add_i32 s7, s7, 0
	v_mov_b32_e32 v1, s7
	v_mov_b32_e32 v10, s6
	ds_write_b32 v1, v10
	s_or_b64 exec, exec, s[0:1]
	s_waitcnt lgkmcnt(0)
	s_barrier
	ds_read_b128 v[20:23], v11
	ds_read_b128 v[24:27], v11 offset:16
	s_waitcnt vmcnt(2)
	v_pk_mul_f32 v[8:9], v[8:9], v[16:17]
	v_pk_mul_f32 v[6:7], v[6:7], v[18:19]
	s_waitcnt lgkmcnt(1)
	v_add_f32_e32 v1, 0, v20
	v_add_f32_e32 v1, v1, v21
	v_add_f32_e32 v1, v1, v22
	v_add_f32_e32 v1, v1, v23
	s_waitcnt lgkmcnt(0)
	v_add_f32_e32 v1, v1, v24
	v_add_f32_e32 v1, v1, v25
	v_add_f32_e32 v1, v1, v26
	v_add_f32_e32 v10, v1, v27
	v_mov_b32_e32 v1, 0x358637bd
	v_fmamk_f32 v10, v10, 0x3a000000, v1
	v_rsq_f32_e32 v10, v10
	s_waitcnt vmcnt(0)
	v_cvt_f32_f16_sdwa v21, v12 dst_sel:DWORD dst_unused:UNUSED_PAD src0_sel:WORD_1
	v_cvt_f32_f16_e32 v20, v12
	v_cvt_f32_f16_sdwa v23, v13 dst_sel:DWORD dst_unused:UNUSED_PAD src0_sel:WORD_1
	v_cvt_f32_f16_e32 v22, v13
	v_pk_fma_f32 v[6:7], v[6:7], v[10:11], v[20:21] op_sel_hi:[1,0,1]
	s_nop 0
	v_cvt_f16_f32_sdwa v12, v7 dst_sel:WORD_1 dst_unused:UNUSED_PAD src0_sel:DWORD
	v_pk_fma_f32 v[8:9], v[8:9], v[10:11], v[22:23] op_sel_hi:[1,0,1]
	v_cvt_f16_f32_e32 v10, v6
	v_cvt_f16_f32_e32 v13, v8
	v_cvt_f16_f32_sdwa v16, v9 dst_sel:WORD_1 dst_unused:UNUSED_PAD src0_sel:DWORD
	v_or_b32_e32 v12, v12, v10
	v_mul_f32_e32 v10, v7, v7
	v_or_b32_e32 v13, v16, v13
	global_store_dwordx2 v[14:15], v[12:13], off
	v_mul_f32_e32 v12, v9, v9
	v_fmac_f32_e32 v10, v6, v6
	v_fmac_f32_e32 v12, v8, v8
	v_add_f32_e32 v10, v10, v12
	v_mov_b32_e32 v12, 0
	s_nop 0
	v_add_f32_dpp v10, v10, v10 quad_perm:[1,0,3,2] row_mask:0xf bank_mask:0xf bound_ctrl:1
	s_nop 1
	v_add_f32_dpp v10, v10, v10 quad_perm:[2,3,0,1] row_mask:0xf bank_mask:0xf bound_ctrl:1
	s_nop 1
	v_add_f32_dpp v10, v10, v10 row_half_mirror row_mask:0xf bank_mask:0xf bound_ctrl:1
	s_nop 1
	v_add_f32_dpp v10, v10, v10 row_mirror row_mask:0xf bank_mask:0xf bound_ctrl:1
	s_nop 1
	v_mov_b32_dpp v12, v10 row_bcast:15 row_mask:0xa bank_mask:0xf
	v_add_f32_e32 v10, v10, v12
	s_nop 1
	v_mov_b32_dpp v11, v10 row_bcast:31 row_mask:0xc bank_mask:0xf
	v_add_f32_e32 v10, v10, v11
	s_nop 0
	v_readlane_b32 s6, v10, 63
	s_and_saveexec_b64 s[0:1], vcc
	s_lshl_b32 s7, s96, 2
	s_add_i32 s7, s7, 0
	v_mov_b32_e32 v10, s7
	v_mov_b32_e32 v11, s6
	ds_write_b32 v10, v11 offset:32
	s_or_b64 exec, exec, s[0:1]
	v_mov_b32_e32 v10, 0
	s_waitcnt lgkmcnt(0)
	s_barrier
	ds_read_b128 v[12:15], v10 offset:32
	ds_read_b128 v[16:19], v10 offset:48
	v_pk_mul_f32 v[4:5], v[4:5], v[8:9]
	v_pk_mul_f32 v[6:7], v[2:3], v[6:7]
	s_waitcnt lgkmcnt(1)
	v_add_f32_e32 v11, 0, v12
	v_add_f32_e32 v11, v11, v13
	v_add_f32_e32 v11, v11, v14
	v_add_f32_e32 v11, v11, v15
	s_waitcnt lgkmcnt(0)
	v_add_f32_e32 v11, v11, v16
	v_add_f32_e32 v11, v11, v17
	v_add_f32_e32 v11, v11, v18
	v_add_f32_e32 v11, v11, v19
	v_fmac_f32_e32 v1, 0x3a000000, v11
	v_rsq_f32_e32 v12, v1
	s_nop 0
	v_pk_mul_f32 v[2:3], v[4:5], v[12:13] op_sel_hi:[1,0]
	v_pk_mul_f32 v[4:5], v[6:7], v[12:13] op_sel_hi:[1,0]
	v_max_f32_e64 v1, |v2|, |v3|
	v_max3_f32 v1, |v4|, |v5|, v1
	v_mov_b32_e32 v6, 0
	s_nop 1
	v_mov_b32_dpp v6, v1 quad_perm:[1,0,3,2] row_mask:0xf bank_mask:0xf
	v_max_f32_e32 v6, v6, v6
	v_max_f32_e32 v1, v1, v6
	v_mov_b32_e32 v6, 0
	s_nop 1
	v_mov_b32_dpp v6, v1 quad_perm:[2,3,0,1] row_mask:0xf bank_mask:0xf
	v_max_f32_e32 v6, v6, v6
	v_max_f32_e32 v1, v1, v6
	v_mov_b32_e32 v6, 0
	s_nop 1
	v_mov_b32_dpp v6, v1 row_half_mirror row_mask:0xf bank_mask:0xf
	v_max_f32_e32 v6, v6, v6
	v_max_f32_e32 v1, v1, v6
	v_mov_b32_e32 v6, 0
	s_nop 1
	v_mov_b32_dpp v6, v1 row_mirror row_mask:0xf bank_mask:0xf
	v_max_f32_e32 v6, v6, v6
	v_max_f32_e32 v1, v1, v6
	v_mov_b32_e32 v6, 0
	s_nop 1
	v_mov_b32_dpp v6, v1 row_bcast:15 row_mask:0xa bank_mask:0xf
	v_max_f32_e32 v6, v6, v6
	v_max_f32_e32 v1, v1, v6
	v_mov_b32_e32 v6, 0
	s_nop 1
	v_mov_b32_dpp v6, v1 row_bcast:31 row_mask:0xc bank_mask:0xf
	v_max_f32_e32 v6, v6, v6
	v_max_f32_e32 v1, v1, v6
	s_nop 0
	v_readlane_b32 s6, v1, 63
	s_and_saveexec_b64 s[0:1], vcc
	s_lshl_b32 s7, s96, 2
	s_add_i32 s7, s7, 0
	v_mov_b32_e32 v1, s7
	v_mov_b32_e32 v6, s6
	ds_write_b32 v1, v6 offset:64
	s_or_b64 exec, exec, s[0:1]
	s_waitcnt lgkmcnt(0)
	s_barrier
	ds_read_b128 v[6:9], v10 offset:64
	ds_read_b128 v[10:13], v10 offset:80
	s_lshl_b64 s[6:7], s[4:5], 11
	s_waitcnt lgkmcnt(1)
	v_max3_f32 v1, v6, 0, v7
	v_max3_f32 v1, v1, v8, v9
	s_waitcnt lgkmcnt(0)
	v_max3_f32 v1, v1, v10, v11
	v_max3_f32 v1, v1, v12, v13
	v_cmp_lt_f32_e64 s[0:1], 0, v1
	s_mov_b64 s[8:9], exec
	v_readlane_b32 s10, v254, 36
	v_readlane_b32 s11, v254, 37
	s_and_b64 s[10:11], s[8:9], s[10:11]
	s_mov_b64 exec, s[10:11]
	s_cbranch_execz .LBB0_3311
	s_lshl_b64 s[4:5], s[4:5], 2
	v_mul_f32_e32 v6, 0x3c010204, v1
	s_add_u32 s4, s86, s4
	v_cndmask_b32_e64 v6, 1.0, v6, s[0:1]
	s_addc_u32 s5, s87, s5
	v_mov_b32_e32 v7, 0
	global_store_dword v7, v6, s[4:5]
